# v22 plus deep overlap in 10 FFN weight-conversion loops: tile A loads consumed after tile B loads are issued (two tiles in flight), separate temp registers per tile set
# baseline (speedup 1.0000x reference)
; DEVI unsigned pk_bf16(float lo, float hi) { unsigned r; asm("v_cvt_pk_bf16_f32 %0, %1, %2" : "=v"(r) : "v"(lo), "v"(hi)); return r; }
; DEVI void cvt_job(LAS float* tile, const float* src, int srcK, int srcN, bf16_t* dst, int dstLd, int dstRows, int dstCol0, int mode, const float* gk = nullptr) {
;     ...
;     auto gl = [&](int t, float (&regs)[16]) {
;         int rho0, kap0, n0; coords(t, rho0, kap0, n0);
;         const int n = n0 + tx, nc = n < srcN ? n : srcN - 1;
;         const bool nok = n < srcN;
;         float raw[16], gs[16];
; #pragma unroll
;         for (int i = 0; i < 16; ++i) { const int k = kap0 + ty + 8 * i - dstCol0; const int kc = k < 0 ? 0 : (k < srcK ? k : srcK - 1);
;             raw[i] = __builtin_nontemporal_load(src + (size_t)kc * srcN + nc); }
;         if (gk) {
; #pragma unroll
;             for (int i = 0; i < 16; ++i) { const int k = kap0 + ty + 8 * i - dstCol0; const int kc = k < 0 ? 0 : (k < srcK ? k : srcK - 1); gs[i] = gk[kc]; }
;         } else {
; #pragma unroll
;             for (int i = 0; i < 16; ++i) gs[i] = 1.0f;
;         }
; #pragma unroll
;         for (int i = 0; i < 16; ++i) { const int k = kap0 + ty + 8 * i - dstCol0; regs[i] = (nok && k >= 0 && k < srcK) ? raw[i] * gs[i] : 0.f; }
;     };
;     auto emit = [&](int t, float (&regs)[16]) {
; #pragma unroll
;         for (int i = 0; i < 16; ++i) tile[(ty + 8 * i) * 65 + tx] = regs[i];
;         __syncthreads();
;         int rho0, kap0, n0; coords(t, rho0, kap0, n0);
;         const int tn = t + 2 * gridDim.x;
;         if (tn < ntot) gl(tn, regs);
; #pragma unroll
;         for (int i = 0; i < 8; ++i) { const int row = ty + 8 * i;
;             const float lo = tile[(2 * tx) * 65 + row], hi = tile[(2 * tx + 1) * 65 + row];
;             *(unsigned*)(dst + (size_t)(rho0 + row) * dstLd + kap0 + 2 * tx) = pk_bf16(lo, hi); }
;         __syncthreads();
;     };
.LBB0_224:
	s_mov_b64 s[98:99], vcc
	v_cmp_gt_i32_e32 vcc, s25, v154
	v_cmp_gt_u32_e64 s[0:1], s26, v155
	s_and_b64 s[0:1], s[0:1], vcc
	v_cmp_gt_u32_e64 s[4:5], s26, v162
	v_cmp_gt_u32_e64 s[6:7], s26, v153
	v_cmp_gt_u32_e64 s[20:21], s26, v116
	v_cmp_gt_u32_e64 s[8:9], s26, v170
	v_cmp_gt_u32_e64 s[10:11], s26, v171
	v_cmp_gt_u32_e64 s[12:13], s26, v172
	v_cmp_gt_u32_e64 s[14:15], s26, v173
	v_cmp_gt_u32_e64 s[16:17], s26, v174
	v_cmp_gt_u32_e64 s[18:19], s26, v175
	v_cndmask_b32_e64 v0, 0, v163, s[0:1]
	v_cmp_gt_u32_e64 s[0:1], s26, v156
	s_and_b64 s[0:1], s[0:1], vcc
	v_cndmask_b32_e64 v1, 0, v164, s[0:1]
	v_cmp_gt_u32_e64 s[0:1], s26, v157
	s_and_b64 s[0:1], s[0:1], vcc
	v_cndmask_b32_e64 v2, 0, v165, s[0:1]
	v_cmp_gt_u32_e64 s[0:1], s26, v158
	s_and_b64 s[0:1], s[0:1], vcc
	v_cndmask_b32_e64 v3, 0, v166, s[0:1]
	v_cmp_gt_u32_e64 s[0:1], s26, v159
	s_and_b64 s[0:1], s[0:1], vcc
	v_cndmask_b32_e64 v4, 0, v167, s[0:1]
	v_cmp_gt_u32_e64 s[0:1], s26, v160
	s_and_b64 s[0:1], s[0:1], vcc
	v_cndmask_b32_e64 v5, 0, v168, s[0:1]
	v_cmp_gt_u32_e64 s[0:1], s26, v161
	s_and_b64 s[0:1], s[0:1], vcc
	v_cndmask_b32_e64 v6, 0, v169, s[0:1]
	s_and_b64 s[0:1], s[4:5], vcc
	v_cndmask_b32_e64 v7, 0, v152, s[0:1]
	s_and_b64 s[0:1], s[6:7], vcc
	v_cndmask_b32_e64 v8, 0, v176, s[0:1]
	s_and_b64 s[0:1], s[8:9], vcc
	v_cndmask_b32_e64 v9, 0, v177, s[0:1]
	s_and_b64 s[0:1], s[10:11], vcc
	v_cndmask_b32_e64 v10, 0, v124, s[0:1]
	s_and_b64 s[0:1], s[12:13], vcc
	v_cndmask_b32_e64 v11, 0, v125, s[0:1]
	s_and_b64 s[0:1], s[14:15], vcc
	v_cndmask_b32_e64 v12, 0, v178, s[0:1]
	s_and_b64 s[0:1], s[16:17], vcc
	v_cndmask_b32_e64 v13, 0, v123, s[0:1]
	s_and_b64 s[0:1], s[18:19], vcc
	s_and_b64 vcc, s[20:21], vcc
	v_cndmask_b32_e64 v14, 0, v179, s[0:1]
	v_cndmask_b32_e32 v15, 0, v180, vcc
	s_mov_b64 vcc, s[98:99]
	ds_read2_b32 v[142:143], v35 offset0:65 offset1:73
	ds_read2_b32 v[144:145], v35 offset1:8
	s_ashr_i32 s0, s29, 31
	s_lshr_b32 s0, s0, 27
	s_add_i32 s29, s29, s0
	s_ashr_i32 s4, s29, 5
	s_lshl_b32 s0, s4, 7
	s_waitcnt lgkmcnt(0)
	v_cvt_pk_bf16_f32 v142, v144, v142
	v_add_u32_e32 v144, s23, v37
	s_lshl_b32 s4, s4, 11
	v_subrev_u32_e32 v150, s4, v144
	v_readlane_b32 s4, v238, 59
	v_readlane_b32 s5, v238, 60
	s_ashr_i32 s1, s0, 31
	s_lshl_b64 s[0:1], s[0:1], 1
	v_mov_b64_e32 v[146:147], s[4:5]
	v_mad_i64_i32 v[148:149], s[4:5], v150, s27, v[146:147]
	v_lshl_add_u64 v[148:149], v[148:149], 0, s[0:1]
	v_lshl_add_u64 v[148:149], v[148:149], 0, v[32:33]
	global_store_dword v[148:149], v142, off
	v_cvt_pk_bf16_f32 v151, v145, v143
	ds_read2_b32 v[142:143], v35 offset0:16 offset1:24
	ds_read2_b32 v[144:145], v35 offset0:81 offset1:89
	v_add_u32_e32 v148, 8, v150
	v_mad_i64_i32 v[148:149], s[4:5], v148, s27, v[146:147]
	v_lshl_add_u64 v[148:149], v[148:149], 0, s[0:1]
	v_lshl_add_u64 v[148:149], v[148:149], 0, v[32:33]
	s_waitcnt lgkmcnt(0)
	v_cvt_pk_bf16_f32 v142, v142, v144
	v_add_u32_e32 v144, 16, v150
	global_store_dword v[148:149], v151, off
	v_mad_i64_i32 v[148:149], s[4:5], v144, s27, v[146:147]
	v_lshl_add_u64 v[148:149], v[148:149], 0, s[0:1]
	v_lshl_add_u64 v[148:149], v[148:149], 0, v[32:33]
	global_store_dword v[148:149], v142, off
	v_cvt_pk_bf16_f32 v151, v143, v145
	ds_read2_b32 v[142:143], v35 offset0:32 offset1:40
	ds_read2_b32 v[144:145], v35 offset0:97 offset1:105
	v_add_u32_e32 v148, 24, v150
	v_mad_i64_i32 v[148:149], s[4:5], v148, s27, v[146:147]
	v_lshl_add_u64 v[148:149], v[148:149], 0, s[0:1]
	v_lshl_add_u64 v[148:149], v[148:149], 0, v[32:33]
	s_waitcnt lgkmcnt(0)
	v_cvt_pk_bf16_f32 v142, v142, v144
	v_add_u32_e32 v144, 32, v150
	global_store_dword v[148:149], v151, off
	v_mad_i64_i32 v[148:149], s[4:5], v144, s27, v[146:147]
	v_lshl_add_u64 v[148:149], v[148:149], 0, s[0:1]
	v_lshl_add_u64 v[148:149], v[148:149], 0, v[32:33]
	global_store_dword v[148:149], v142, off
	v_cvt_pk_bf16_f32 v151, v143, v145
	ds_read2_b32 v[142:143], v35 offset0:48 offset1:56
	ds_read2_b32 v[144:145], v35 offset0:113 offset1:121
	v_add_u32_e32 v148, 40, v150
	v_mad_i64_i32 v[148:149], s[4:5], v148, s27, v[146:147]
	v_lshl_add_u64 v[148:149], v[148:149], 0, s[0:1]
	v_lshl_add_u64 v[148:149], v[148:149], 0, v[32:33]
	s_waitcnt lgkmcnt(0)
	v_cvt_pk_bf16_f32 v142, v142, v144
	v_add_u32_e32 v144, 48, v150
	global_store_dword v[148:149], v151, off
	v_mad_i64_i32 v[148:149], s[4:5], v144, s27, v[146:147]
	v_lshl_add_u64 v[148:149], v[148:149], 0, s[0:1]
	v_lshl_add_u64 v[148:149], v[148:149], 0, v[32:33]
	global_store_dword v[148:149], v142, off
	v_add_u32_e32 v142, 56, v150
	v_cvt_pk_bf16_f32 v144, v143, v145
	v_mad_i64_i32 v[142:143], s[4:5], v142, s27, v[146:147]
	v_lshl_add_u64 v[142:143], v[142:143], 0, s[0:1]
	v_lshl_add_u64 v[142:143], v[142:143], 0, v[32:33]
	global_store_dword v[142:143], v144, off
	v_cmp_gt_u32_e64 s[0:1], s26, v45
	s_and_b64 s[0:1], s[0:1], vcc
	v_cmp_gt_u32_e64 s[4:5], s26, v52
	v_cmp_gt_u32_e64 s[6:7], s26, v43
	v_cmp_gt_u32_e64 s[20:21], s26, v22
	v_cmp_gt_u32_e64 s[8:9], s26, v60
	v_cmp_gt_u32_e64 s[10:11], s26, v61
	v_cmp_gt_u32_e64 s[12:13], s26, v62
	v_cmp_gt_u32_e64 s[14:15], s26, v63
	v_cmp_gt_u32_e64 s[16:17], s26, v64
	v_cmp_gt_u32_e64 s[18:19], s26, v65
	s_waitcnt vmcnt(23)
	v_cndmask_b32_e64 v16, 0, v53, s[0:1]
	v_cmp_gt_u32_e64 s[0:1], s26, v46
	s_and_b64 s[0:1], s[0:1], vcc
	s_waitcnt vmcnt(22)
	v_cndmask_b32_e64 v17, 0, v54, s[0:1]
	v_cmp_gt_u32_e64 s[0:1], s26, v47
	s_and_b64 s[0:1], s[0:1], vcc
	s_waitcnt vmcnt(21)
	v_cndmask_b32_e64 v18, 0, v55, s[0:1]
	v_cmp_gt_u32_e64 s[0:1], s26, v48
	s_and_b64 s[0:1], s[0:1], vcc
	s_waitcnt vmcnt(20)
	v_cndmask_b32_e64 v19, 0, v56, s[0:1]
	v_cmp_gt_u32_e64 s[0:1], s26, v49
	s_and_b64 s[0:1], s[0:1], vcc
	s_waitcnt vmcnt(19)
	v_cndmask_b32_e64 v20, 0, v57, s[0:1]
	v_cmp_gt_u32_e64 s[0:1], s26, v50
	s_and_b64 s[0:1], s[0:1], vcc
	s_waitcnt vmcnt(18)
	v_cndmask_b32_e64 v21, 0, v58, s[0:1]
	v_cmp_gt_u32_e64 s[0:1], s26, v51
	s_and_b64 s[0:1], s[0:1], vcc
	s_waitcnt vmcnt(17)
	v_cndmask_b32_e64 v22, 0, v59, s[0:1]
	s_and_b64 s[0:1], s[4:5], vcc
	s_waitcnt vmcnt(16)
	v_cndmask_b32_e64 v23, 0, v42, s[0:1]
	s_and_b64 s[0:1], s[6:7], vcc
	s_waitcnt vmcnt(15)
	v_cndmask_b32_e64 v24, 0, v66, s[0:1]
	s_and_b64 s[0:1], s[8:9], vcc
	s_waitcnt vmcnt(14)
	v_cndmask_b32_e64 v25, 0, v67, s[0:1]
	s_and_b64 s[0:1], s[10:11], vcc
	s_waitcnt vmcnt(12)
	v_cndmask_b32_e64 v26, 0, v30, s[0:1]
	s_and_b64 s[0:1], s[12:13], vcc
	s_waitcnt vmcnt(11)
	v_cndmask_b32_e64 v27, 0, v31, s[0:1]
	s_and_b64 s[0:1], s[14:15], vcc
	v_cndmask_b32_e64 v28, 0, v68, s[0:1]
	s_and_b64 s[0:1], s[16:17], vcc
	s_waitcnt vmcnt(10)
	v_cndmask_b32_e64 v29, 0, v29, s[0:1]
	s_and_b64 s[0:1], s[18:19], vcc
	s_and_b64 vcc, s[20:21], vcc
	s_waitcnt vmcnt(9)
	v_cndmask_b32_e64 v30, 0, v69, s[0:1]
	s_waitcnt vmcnt(8)
	v_cndmask_b32_e32 v31, 0, v70, vcc
	s_waitcnt vmcnt(63) expcnt(7) lgkmcnt(15)
	s_barrier

; DEVI void cvt_job(LAS float* tile, const float* src, int srcK, int srcN, bf16_t* dst, int dstLd, int dstRows, int dstCol0, int mode, const float* gk = nullptr) {
;     ...
;         for (int i = 0; i < 16; ++i) { const int k = kap0 + ty + 8 * i - dstCol0; const int kc = k < 0 ? 0 : (k < srcK ? k : srcK - 1);
;             raw[i] = __builtin_nontemporal_load(src + (size_t)kc * srcN + nc); }
;         if (gk) {
; #pragma unroll
;             for (int i = 0; i < 16; ++i) { const int k = kap0 + ty + 8 * i - dstCol0; const int kc = k < 0 ? 0 : (k < srcK ? k : srcK - 1); gs[i] = gk[kc]; }
;         } else {
; #pragma unroll
;             for (int i = 0; i < 16; ++i) gs[i] = 1.0f;
;         }
; #pragma unroll
;         for (int i = 0; i < 16; ++i) { const int k = kap0 + ty + 8 * i - dstCol0; regs[i] = (nok && k >= 0 && k < srcK) ? raw[i] * gs[i] : 0.f; }
;     };
;     auto emit = [&](int t, float (&regs)[16]) {
; #pragma unroll
;         for (int i = 0; i < 16; ++i) tile[(ty + 8 * i) * 65 + tx] = regs[i];
;         __syncthreads();
;         int rho0, kap0, n0; coords(t, rho0, kap0, n0);
;         const int tn = t + 2 * gridDim.x;
;         if (tn < ntot) gl(tn, regs);
.LBB0_226:
	s_add_i32 s28, s22, s30
	s_cmpk_gt_i32 s28, 0x57f
	s_cselect_b64 s[2:3], -1, 0
	s_and_b64 vcc, exec, s[2:3]
	ds_write_b32 v40, v0
	ds_write_b32 v40, v1 offset:2080
	ds_write_b32 v40, v2 offset:4160
	ds_write_b32 v40, v3 offset:6240
	ds_write_b32 v40, v4 offset:8320
	ds_write_b32 v40, v5 offset:10400
	ds_write_b32 v40, v6 offset:12480
	ds_write_b32 v40, v7 offset:14560
	ds_write_b32 v40, v8 offset:16640
	ds_write_b32 v40, v9 offset:18720
	ds_write_b32 v40, v10 offset:20800
	ds_write_b32 v40, v11 offset:22880
	ds_write_b32 v40, v12 offset:24960
	ds_write_b32 v40, v13 offset:27040
	ds_write_b32 v40, v14 offset:29120
	ds_write_b32 v40, v15 offset:31200
	s_waitcnt lgkmcnt(0)
	s_barrier
	s_cbranch_vccnz .LBB0_228
	s_ashr_i32 s0, s28, 31
	s_lshr_b32 s0, s0, 27
	s_add_i32 s0, s28, s0
	s_ashr_i32 s0, s0, 5
	v_add_u32_e32 v110, s23, v39
	s_lshl_b32 s1, s0, 11
	v_subrev_u32_e32 v154, s1, v110
	v_lshl_add_u32 v155, s0, 7, v34
	v_min_i32_e32 v110, 0x7ff, v154
	v_add_u32_e32 v162, 56, v155
	v_ashrrev_i32_e32 v111, 31, v110
	v_med3_i32 v112, v155, 0, v41
	v_add_u32_e32 v156, 8, v155
	v_add_u32_e32 v157, 16, v155
	v_add_u32_e32 v158, 24, v155
	v_add_u32_e32 v159, 32, v155
	v_add_u32_e32 v160, 40, v155
	v_add_u32_e32 v161, 48, v155
	v_med3_i32 v152, v162, 0, v41
	v_lshl_add_u64 v[110:111], v[110:111], 2, s[58:59]
	v_lshlrev_b32_e32 v112, 13, v112
	v_mov_b32_e32 v113, v33
	v_med3_i32 v114, v156, 0, v41
	v_med3_i32 v116, v157, 0, v41
	v_med3_i32 v118, v158, 0, v41
	v_med3_i32 v120, v159, 0, v41
	v_med3_i32 v122, v160, 0, v41
	v_med3_i32 v124, v161, 0, v41
	v_lshlrev_b32_e32 v152, 13, v152
	v_mov_b32_e32 v153, v33
	v_lshl_add_u64 v[112:113], v[110:111], 0, v[112:113]
	v_lshlrev_b32_e32 v114, 13, v114
	v_mov_b32_e32 v115, v33
	v_lshlrev_b32_e32 v116, 13, v116
	v_mov_b32_e32 v117, v33
	v_lshlrev_b32_e32 v118, 13, v118
	v_mov_b32_e32 v119, v33
	v_lshlrev_b32_e32 v120, 13, v120
	v_mov_b32_e32 v121, v33
	v_lshlrev_b32_e32 v122, 13, v122
	v_mov_b32_e32 v123, v33
	v_lshlrev_b32_e32 v124, 13, v124
	v_mov_b32_e32 v125, v33
	v_lshl_add_u64 v[152:153], v[110:111], 0, v[152:153]
	v_lshl_add_u64 v[114:115], v[110:111], 0, v[114:115]
	v_lshl_add_u64 v[116:117], v[110:111], 0, v[116:117]
	v_lshl_add_u64 v[118:119], v[110:111], 0, v[118:119]
	v_lshl_add_u64 v[120:121], v[110:111], 0, v[120:121]
	v_lshl_add_u64 v[122:123], v[110:111], 0, v[122:123]
	v_lshl_add_u64 v[124:125], v[110:111], 0, v[124:125]
	global_load_dword v163, v[112:113], off nt
	global_load_dword v164, v[114:115], off nt
	global_load_dword v165, v[116:117], off nt
	global_load_dword v166, v[118:119], off nt
	global_load_dword v167, v[120:121], off nt
	global_load_dword v168, v[122:123], off nt
	global_load_dword v169, v[124:125], off nt
	s_nop 0
	global_load_dword v152, v[152:153], off nt
	v_add_u32_e32 v153, 64, v155
	v_med3_i32 v112, v153, 0, v41
	v_add_u32_e32 v170, 0x48, v155
	v_add_u32_e32 v173, 0x60, v155
	v_lshlrev_b32_e32 v112, 13, v112
	v_mov_b32_e32 v113, v33
	v_med3_i32 v114, v170, 0, v41
	v_add_u32_e32 v171, 0x50, v155
	v_add_u32_e32 v172, 0x58, v155
	v_med3_i32 v120, v173, 0, v41
	v_add_u32_e32 v174, 0x68, v155
	v_add_u32_e32 v175, 0x70, v155
	v_lshl_add_u64 v[112:113], v[110:111], 0, v[112:113]
	v_lshlrev_b32_e32 v114, 13, v114
	v_mov_b32_e32 v115, v33
	v_med3_i32 v116, v171, 0, v41
	v_med3_i32 v118, v172, 0, v41
	v_lshlrev_b32_e32 v120, 13, v120
	v_mov_b32_e32 v121, v33
	v_med3_i32 v122, v174, 0, v41
	v_med3_i32 v124, v175, 0, v41
	v_lshl_add_u64 v[114:115], v[110:111], 0, v[114:115]
	v_lshlrev_b32_e32 v116, 13, v116
	v_mov_b32_e32 v117, v33
	v_lshlrev_b32_e32 v118, 13, v118
	v_mov_b32_e32 v119, v33
	v_lshl_add_u64 v[120:121], v[110:111], 0, v[120:121]
	v_lshlrev_b32_e32 v122, 13, v122
	v_mov_b32_e32 v123, v33
	v_lshlrev_b32_e32 v124, 13, v124
	global_load_dword v176, v[112:113], off nt
	global_load_dword v177, v[114:115], off nt
	global_load_dword v178, v[120:121], off nt
	v_mov_b32_e32 v125, v33
	v_lshl_add_u64 v[116:117], v[110:111], 0, v[116:117]
	v_lshl_add_u64 v[118:119], v[110:111], 0, v[118:119]
	v_lshl_add_u64 v[122:123], v[110:111], 0, v[122:123]
	v_lshl_add_u64 v[112:113], v[110:111], 0, v[124:125]
	global_load_dword v124, v[116:117], off nt
	global_load_dword v125, v[118:119], off nt
	v_mov_b32_e32 v115, v33
	global_load_dword v123, v[122:123], off nt
	global_load_dword v179, v[112:113], off nt
	v_add_u32_e32 v116, 0x78, v155
	v_med3_i32 v114, v116, 0, v41
	v_lshlrev_b32_e32 v114, 13, v114
	v_lshl_add_u64 v[110:111], v[110:111], 0, v[114:115]
	global_load_dword v180, v[110:111], off nt
; DEVI unsigned pk_bf16(float lo, float hi) { unsigned r; asm("v_cvt_pk_bf16_f32 %0, %1, %2" : "=v"(r) : "v"(lo), "v"(hi)); return r; }
; DEVI void cvt_job(LAS float* tile, const float* src, int srcK, int srcN, bf16_t* dst, int dstLd, int dstRows, int dstCol0, int mode, const float* gk = nullptr) {
;     ...
;     auto emit = [&](int t, float (&regs)[16]) {
; #pragma unroll
;         for (int i = 0; i < 16; ++i) tile[(ty + 8 * i) * 65 + tx] = regs[i];
;         __syncthreads();
;         int rho0, kap0, n0; coords(t, rho0, kap0, n0);
;         const int tn = t + 2 * gridDim.x;
;         if (tn < ntot) gl(tn, regs);
; #pragma unroll
;         for (int i = 0; i < 8; ++i) { const int row = ty + 8 * i;
;             const float lo = tile[(2 * tx) * 65 + row], hi = tile[(2 * tx + 1) * 65 + row];
;             *(unsigned*)(dst + (size_t)(rho0 + row) * dstLd + kap0 + 2 * tx) = pk_bf16(lo, hi); }
;         __syncthreads();
;     };
.LBB0_228:
	ds_read2_b32 v[42:43], v35 offset0:65 offset1:73
	ds_read2_b32 v[44:45], v35 offset1:8
	s_ashr_i32 s0, s22, 31
	s_lshr_b32 s0, s0, 27
	s_add_i32 s0, s22, s0
	s_ashr_i32 s4, s0, 5
	s_lshl_b32 s0, s4, 7
	s_waitcnt lgkmcnt(0)
	v_cvt_pk_bf16_f32 v42, v44, v42
	v_add_u32_e32 v44, s23, v38
	s_lshl_b32 s4, s4, 11
	v_subrev_u32_e32 v50, s4, v44
	v_readlane_b32 s4, v238, 59
	v_readlane_b32 s5, v238, 60
	s_ashr_i32 s1, s0, 31
	s_lshl_b64 s[0:1], s[0:1], 1
	v_mov_b64_e32 v[46:47], s[4:5]
	v_mad_i64_i32 v[48:49], s[4:5], v50, s27, v[46:47]
	v_lshl_add_u64 v[48:49], v[48:49], 0, s[0:1]
	v_lshl_add_u64 v[48:49], v[48:49], 0, v[32:33]
	global_store_dword v[48:49], v42, off
	v_cvt_pk_bf16_f32 v51, v45, v43
	ds_read2_b32 v[42:43], v35 offset0:16 offset1:24
	ds_read2_b32 v[44:45], v35 offset0:81 offset1:89
	v_add_u32_e32 v48, 8, v50
	v_mad_i64_i32 v[48:49], s[4:5], v48, s27, v[46:47]
	v_lshl_add_u64 v[48:49], v[48:49], 0, s[0:1]
	v_lshl_add_u64 v[48:49], v[48:49], 0, v[32:33]
	s_waitcnt lgkmcnt(0)
	v_cvt_pk_bf16_f32 v42, v42, v44
	v_add_u32_e32 v44, 16, v50
	global_store_dword v[48:49], v51, off
	v_mad_i64_i32 v[48:49], s[4:5], v44, s27, v[46:47]
	v_lshl_add_u64 v[48:49], v[48:49], 0, s[0:1]
	v_lshl_add_u64 v[48:49], v[48:49], 0, v[32:33]
	global_store_dword v[48:49], v42, off
	v_cvt_pk_bf16_f32 v51, v43, v45
	ds_read2_b32 v[42:43], v35 offset0:32 offset1:40
	ds_read2_b32 v[44:45], v35 offset0:97 offset1:105
	v_add_u32_e32 v48, 24, v50
	v_mad_i64_i32 v[48:49], s[4:5], v48, s27, v[46:47]
	v_lshl_add_u64 v[48:49], v[48:49], 0, s[0:1]
	v_lshl_add_u64 v[48:49], v[48:49], 0, v[32:33]
	s_waitcnt lgkmcnt(0)
	v_cvt_pk_bf16_f32 v42, v42, v44
	v_add_u32_e32 v44, 32, v50
	global_store_dword v[48:49], v51, off
	v_mad_i64_i32 v[48:49], s[4:5], v44, s27, v[46:47]
	v_lshl_add_u64 v[48:49], v[48:49], 0, s[0:1]
	v_lshl_add_u64 v[48:49], v[48:49], 0, v[32:33]
	global_store_dword v[48:49], v42, off
	v_cvt_pk_bf16_f32 v51, v43, v45
	ds_read2_b32 v[42:43], v35 offset0:48 offset1:56
	ds_read2_b32 v[44:45], v35 offset0:113 offset1:121
	v_add_u32_e32 v48, 40, v50
	v_mad_i64_i32 v[48:49], s[4:5], v48, s27, v[46:47]
	v_lshl_add_u64 v[48:49], v[48:49], 0, s[0:1]
	v_lshl_add_u64 v[48:49], v[48:49], 0, v[32:33]
	s_waitcnt lgkmcnt(0)
	v_cvt_pk_bf16_f32 v42, v42, v44
	v_add_u32_e32 v44, 48, v50
	global_store_dword v[48:49], v51, off
	v_mad_i64_i32 v[48:49], s[4:5], v44, s27, v[46:47]
	v_lshl_add_u64 v[48:49], v[48:49], 0, s[0:1]
	v_lshl_add_u64 v[48:49], v[48:49], 0, v[32:33]
	global_store_dword v[48:49], v42, off
	v_add_u32_e32 v42, 56, v50
	v_cvt_pk_bf16_f32 v44, v43, v45
	v_mad_i64_i32 v[42:43], s[4:5], v42, s27, v[46:47]
	v_lshl_add_u64 v[42:43], v[42:43], 0, s[0:1]
	s_add_i32 s29, s33, s22
	v_lshl_add_u64 v[42:43], v[42:43], 0, v[32:33]
	s_cmpk_gt_i32 s29, 0x57f
	global_store_dword v[42:43], v44, off
	s_waitcnt vmcnt(63) expcnt(7) lgkmcnt(15)
	s_barrier
	s_cbranch_scc1 .LBB0_225
	s_add_i32 s0, s31, s22
	s_cmpk_gt_i32 s0, 0x57f
	ds_write_b32 v40, v16
	ds_write_b32 v40, v17 offset:2080
	ds_write_b32 v40, v18 offset:4160
	ds_write_b32 v40, v19 offset:6240
	ds_write_b32 v40, v20 offset:8320
	ds_write_b32 v40, v21 offset:10400
	ds_write_b32 v40, v22 offset:12480
	ds_write_b32 v40, v23 offset:14560
	ds_write_b32 v40, v24 offset:16640
	ds_write_b32 v40, v25 offset:18720
	ds_write_b32 v40, v26 offset:20800
	ds_write_b32 v40, v27 offset:22880
	ds_write_b32 v40, v28 offset:24960
	ds_write_b32 v40, v29 offset:27040
	ds_write_b32 v40, v30 offset:29120
	ds_write_b32 v40, v31 offset:31200
	s_waitcnt lgkmcnt(0)
	s_barrier
	s_cbranch_scc1 .Lcvt_stub_1
; DEVI int obid() { int b = __builtin_amdgcn_workgroup_id_x(); asm volatile("" : "+s"(b)); return b; }
; DEVI unsigned pk_bf16(float lo, float hi) { unsigned r; asm("v_cvt_pk_bf16_f32 %0, %1, %2" : "=v"(r) : "v"(lo), "v"(hi)); return r; }
; DEVI void cvt_job(LAS float* tile, const float* src, int srcK, int srcN, bf16_t* dst, int dstLd, int dstRows, int dstCol0, int mode, const float* gk = nullptr) {
;     ...
;     auto gl = [&](int t, float (&regs)[16]) {
;         int rho0, kap0, n0; coords(t, rho0, kap0, n0);
;         const int n = n0 + tx, nc = n < srcN ? n : srcN - 1;
;         const bool nok = n < srcN;
;         float raw[16], gs[16];
; #pragma unroll
;         for (int i = 0; i < 16; ++i) { const int k = kap0 + ty + 8 * i - dstCol0; const int kc = k < 0 ? 0 : (k < srcK ? k : srcK - 1);
;             raw[i] = __builtin_nontemporal_load(src + (size_t)kc * srcN + nc); }
;         if (gk) {
; #pragma unroll
;             for (int i = 0; i < 16; ++i) { const int k = kap0 + ty + 8 * i - dstCol0; const int kc = k < 0 ? 0 : (k < srcK ? k : srcK - 1); gs[i] = gk[kc]; }
;         } else {
; #pragma unroll
;             for (int i = 0; i < 16; ++i) gs[i] = 1.0f;
;         }
; #pragma unroll
;         for (int i = 0; i < 16; ++i) { const int k = kap0 + ty + 8 * i - dstCol0; regs[i] = (nok && k >= 0 && k < srcK) ? raw[i] * gs[i] : 0.f; }
;     };
;     auto emit = [&](int t, float (&regs)[16]) {
; #pragma unroll
;         for (int i = 0; i < 16; ++i) tile[(ty + 8 * i) * 65 + tx] = regs[i];
;         __syncthreads();
;         int rho0, kap0, n0; coords(t, rho0, kap0, n0);
;         const int tn = t + 2 * gridDim.x;
;         if (tn < ntot) gl(tn, regs);
; #pragma unroll
;         for (int i = 0; i < 8; ++i) { const int row = ty + 8 * i;
;             const float lo = tile[(2 * tx) * 65 + row], hi = tile[(2 * tx + 1) * 65 + row];
;             *(unsigned*)(dst + (size_t)(rho0 + row) * dstLd + kap0 + 2 * tx) = pk_bf16(lo, hi); }
;         __syncthreads();
;     };
;     const int G = gridDim.x;
;     int t = obid();
;     if (t < ntot) gl(t, regsA);
;     if (t + G < ntot) gl(t + G, regsB);
;     while (t < ntot) {
;         emit(t, regsA);
;         if (t + G < ntot) emit(t + G, regsB);
;         t += 2 * G;
	s_ashr_i32 s1, s0, 31
	s_lshr_b32 s1, s1, 27
	s_add_i32 s0, s0, s1
	s_ashr_i32 s0, s0, 5
	v_add_u32_e32 v16, s23, v36
	s_lshl_b32 s1, s0, 11
	v_subrev_u32_e32 v44, s1, v16
	v_lshl_add_u32 v45, s0, 7, v34
	v_min_i32_e32 v16, 0x7ff, v44
	v_add_u32_e32 v52, 56, v45
	v_ashrrev_i32_e32 v17, 31, v16
	v_med3_i32 v18, v45, 0, v41
	v_add_u32_e32 v46, 8, v45
	v_add_u32_e32 v47, 16, v45
	v_add_u32_e32 v48, 24, v45
	v_add_u32_e32 v49, 32, v45
	v_add_u32_e32 v50, 40, v45
	v_add_u32_e32 v51, 48, v45
	v_med3_i32 v42, v52, 0, v41
	v_lshl_add_u64 v[16:17], v[16:17], 2, s[58:59]
	v_lshlrev_b32_e32 v18, 13, v18
	v_mov_b32_e32 v19, v33
	v_med3_i32 v20, v46, 0, v41
	v_med3_i32 v22, v47, 0, v41
	v_med3_i32 v24, v48, 0, v41
	v_med3_i32 v26, v49, 0, v41
	v_med3_i32 v28, v50, 0, v41
	v_med3_i32 v30, v51, 0, v41
	v_lshlrev_b32_e32 v42, 13, v42
	v_mov_b32_e32 v43, v33
	v_lshl_add_u64 v[18:19], v[16:17], 0, v[18:19]
	v_lshlrev_b32_e32 v20, 13, v20
	v_mov_b32_e32 v21, v33
	v_lshlrev_b32_e32 v22, 13, v22
	v_mov_b32_e32 v23, v33
	v_lshlrev_b32_e32 v24, 13, v24
	v_mov_b32_e32 v25, v33
	v_lshlrev_b32_e32 v26, 13, v26
	v_mov_b32_e32 v27, v33
	v_lshlrev_b32_e32 v28, 13, v28
	v_mov_b32_e32 v29, v33
	v_lshlrev_b32_e32 v30, 13, v30
	v_mov_b32_e32 v31, v33
	v_lshl_add_u64 v[42:43], v[16:17], 0, v[42:43]
	v_lshl_add_u64 v[20:21], v[16:17], 0, v[20:21]
	v_lshl_add_u64 v[22:23], v[16:17], 0, v[22:23]
	v_lshl_add_u64 v[24:25], v[16:17], 0, v[24:25]
	v_lshl_add_u64 v[26:27], v[16:17], 0, v[26:27]
	v_lshl_add_u64 v[28:29], v[16:17], 0, v[28:29]
	v_lshl_add_u64 v[30:31], v[16:17], 0, v[30:31]
	global_load_dword v53, v[18:19], off nt
	global_load_dword v54, v[20:21], off nt
	global_load_dword v55, v[22:23], off nt
	global_load_dword v56, v[24:25], off nt
	global_load_dword v57, v[26:27], off nt
	global_load_dword v58, v[28:29], off nt
	global_load_dword v59, v[30:31], off nt
	s_nop 0
	global_load_dword v42, v[42:43], off nt
	v_add_u32_e32 v43, 64, v45
	v_med3_i32 v18, v43, 0, v41
	v_add_u32_e32 v60, 0x48, v45
	v_add_u32_e32 v63, 0x60, v45
	v_lshlrev_b32_e32 v18, 13, v18
	v_mov_b32_e32 v19, v33
	v_med3_i32 v20, v60, 0, v41
	v_add_u32_e32 v61, 0x50, v45
	v_add_u32_e32 v62, 0x58, v45
	v_med3_i32 v26, v63, 0, v41
	v_add_u32_e32 v64, 0x68, v45
	v_add_u32_e32 v65, 0x70, v45
	v_lshl_add_u64 v[18:19], v[16:17], 0, v[18:19]
	v_lshlrev_b32_e32 v20, 13, v20
	v_mov_b32_e32 v21, v33
	v_med3_i32 v22, v61, 0, v41
	v_med3_i32 v24, v62, 0, v41
	v_lshlrev_b32_e32 v26, 13, v26
	v_mov_b32_e32 v27, v33
	v_med3_i32 v28, v64, 0, v41
	v_med3_i32 v30, v65, 0, v41
	v_lshl_add_u64 v[20:21], v[16:17], 0, v[20:21]
	v_lshlrev_b32_e32 v22, 13, v22
	v_mov_b32_e32 v23, v33
	v_lshlrev_b32_e32 v24, 13, v24
	v_mov_b32_e32 v25, v33
	v_lshl_add_u64 v[26:27], v[16:17], 0, v[26:27]
	v_lshlrev_b32_e32 v28, 13, v28
	v_mov_b32_e32 v29, v33
	v_lshlrev_b32_e32 v30, 13, v30
	global_load_dword v66, v[18:19], off nt
	global_load_dword v67, v[20:21], off nt
	global_load_dword v68, v[26:27], off nt
	v_mov_b32_e32 v31, v33
	v_lshl_add_u64 v[22:23], v[16:17], 0, v[22:23]
	v_lshl_add_u64 v[24:25], v[16:17], 0, v[24:25]
	v_lshl_add_u64 v[28:29], v[16:17], 0, v[28:29]
	v_lshl_add_u64 v[18:19], v[16:17], 0, v[30:31]
	global_load_dword v30, v[22:23], off nt
	global_load_dword v31, v[24:25], off nt
	v_mov_b32_e32 v21, v33
	global_load_dword v29, v[28:29], off nt
	v_cmp_gt_i32_e32 vcc, s25, v44
	global_load_dword v69, v[18:19], off nt
	v_add_u32_e32 v22, 0x78, v45
	v_med3_i32 v20, v22, 0, v41
	v_lshlrev_b32_e32 v20, 13, v20
	v_lshl_add_u64 v[16:17], v[16:17], 0, v[20:21]
	global_load_dword v70, v[16:17], off nt
	s_waitcnt vmcnt(24)
	s_branch .LBB0_224
.Lcvt_stub_1:
	s_waitcnt vmcnt(8)
	s_branch .LBB0_224

; DEVI unsigned pk_bf16(float lo, float hi) { unsigned r; asm("v_cvt_pk_bf16_f32 %0, %1, %2" : "=v"(r) : "v"(lo), "v"(hi)); return r; }
; DEVI void cvt_job(LAS float* tile, const float* src, int srcK, int srcN, bf16_t* dst, int dstLd, int dstRows, int dstCol0, int mode, const float* gk = nullptr) {
;     ...
;         for (int i = 0; i < 16; ++i) { const int k = kap0 + ty + 8 * i - dstCol0; const int kc = k < 0 ? 0 : (k < srcK ? k : srcK - 1);
;             raw[i] = __builtin_nontemporal_load(src + (size_t)kc * srcN + nc); }
;         if (gk) {
; #pragma unroll
;             for (int i = 0; i < 16; ++i) { const int k = kap0 + ty + 8 * i - dstCol0; const int kc = k < 0 ? 0 : (k < srcK ? k : srcK - 1); gs[i] = gk[kc]; }
;         } else {
; #pragma unroll
;             for (int i = 0; i < 16; ++i) gs[i] = 1.0f;
;         }
; #pragma unroll
;         for (int i = 0; i < 16; ++i) { const int k = kap0 + ty + 8 * i - dstCol0; regs[i] = (nok && k >= 0 && k < srcK) ? raw[i] * gs[i] : 0.f; }
;     };
;     auto emit = [&](int t, float (&regs)[16]) {
; #pragma unroll
;         for (int i = 0; i < 16; ++i) tile[(ty + 8 * i) * 65 + tx] = regs[i];
;         __syncthreads();
;         int rho0, kap0, n0; coords(t, rho0, kap0, n0);
;         const int tn = t + 2 * gridDim.x;
;         if (tn < ntot) gl(tn, regs);
; #pragma unroll
;         for (int i = 0; i < 8; ++i) { const int row = ty + 8 * i;
;             const float lo = tile[(2 * tx) * 65 + row], hi = tile[(2 * tx + 1) * 65 + row];
;             *(unsigned*)(dst + (size_t)(rho0 + row) * dstLd + kap0 + 2 * tx) = pk_bf16(lo, hi); }
.LBB0_335:
	v_mov_b32_e32 v17, v33
	v_mov_b32_e32 v19, v33
	v_mov_b32_e32 v21, v33
	v_mov_b32_e32 v23, v33
	v_mov_b32_e32 v25, v33
	v_mov_b32_e32 v27, v33
	v_mov_b32_e32 v29, v33
	v_mov_b32_e32 v31, v33
	v_mov_b32_e32 v35, v33
	v_mov_b32_e32 v37, v33
	v_mov_b32_e32 v39, v33
	v_mov_b32_e32 v41, v33
	v_lshl_add_u64 v[16:17], v[16:17], 2, s[38:39]
	v_lshl_add_u64 v[18:19], v[18:19], 2, s[38:39]
	v_lshl_add_u64 v[20:21], v[20:21], 2, s[38:39]
	v_lshl_add_u64 v[22:23], v[22:23], 2, s[38:39]
	v_lshl_add_u64 v[24:25], v[24:25], 2, s[38:39]
	v_lshl_add_u64 v[26:27], v[26:27], 2, s[38:39]
	v_lshl_add_u64 v[28:29], v[28:29], 2, s[38:39]
	v_lshl_add_u64 v[30:31], v[30:31], 2, s[38:39]
	v_mov_b32_e32 v43, v33
	v_mov_b32_e32 v45, v33
	v_mov_b32_e32 v47, v33
	v_mov_b32_e32 v49, v33
	global_load_dword v16, v[16:17], off
	s_nop 0
	global_load_dword v17, v[18:19], off
	s_nop 0
	global_load_dword v18, v[20:21], off
	global_load_dword v19, v[22:23], off
	s_nop 0
	global_load_dword v20, v[24:25], off
	global_load_dword v21, v[26:27], off
	global_load_dword v22, v[28:29], off
	global_load_dword v23, v[30:31], off
	v_lshl_add_u64 v[24:25], v[34:35], 2, s[38:39]
	v_lshl_add_u64 v[26:27], v[36:37], 2, s[38:39]
	v_lshl_add_u64 v[28:29], v[38:39], 2, s[38:39]
	v_lshl_add_u64 v[30:31], v[40:41], 2, s[38:39]
	v_lshl_add_u64 v[34:35], v[42:43], 2, s[38:39]
	v_lshl_add_u64 v[36:37], v[44:45], 2, s[38:39]
	v_lshl_add_u64 v[38:39], v[46:47], 2, s[38:39]
	v_lshl_add_u64 v[40:41], v[48:49], 2, s[38:39]
	global_load_dword v24, v[24:25], off
	s_nop 0
	global_load_dword v25, v[26:27], off
	s_nop 0
	global_load_dword v26, v[28:29], off
	global_load_dword v27, v[30:31], off
	s_nop 0
	global_load_dword v28, v[34:35], off
	global_load_dword v29, v[36:37], off
	global_load_dword v30, v[38:39], off
	global_load_dword v31, v[40:41], off
	s_waitcnt vmcnt(40)
.LBB0_336:
.LBB0_337:
	v_cmp_gt_i32_e32 vcc, s12, v203
	v_cmp_gt_u32_e64 s[36:37], s13, v202
	v_mul_f32_e32 v140, v205, v140
	s_and_b64 s[36:37], s[36:37], vcc
	v_cndmask_b32_e64 v0, 0, v140, s[36:37]
	v_cmp_gt_u32_e64 s[36:37], s13, v204
	v_mul_f32_e32 v141, v207, v141
	s_and_b64 s[36:37], s[36:37], vcc
	v_cndmask_b32_e64 v1, 0, v141, s[36:37]
	v_cmp_gt_u32_e64 s[36:37], s13, v206
	v_mul_f32_e32 v142, v209, v142
	s_and_b64 s[36:37], s[36:37], vcc
	v_cndmask_b32_e64 v2, 0, v142, s[36:37]
	v_cmp_gt_u32_e64 s[36:37], s13, v208
	v_mul_f32_e32 v143, v211, v143
	s_and_b64 s[36:37], s[36:37], vcc
	v_cndmask_b32_e64 v3, 0, v143, s[36:37]
	v_cmp_gt_u32_e64 s[36:37], s13, v210
	v_mul_f32_e32 v144, v213, v144
	s_and_b64 s[36:37], s[36:37], vcc
	v_cndmask_b32_e64 v4, 0, v144, s[36:37]
	v_cmp_gt_u32_e64 s[36:37], s13, v212
	v_mul_f32_e32 v145, v215, v145
	s_and_b64 s[36:37], s[36:37], vcc
	v_cndmask_b32_e64 v5, 0, v145, s[36:37]
	v_cmp_gt_u32_e64 s[36:37], s13, v214
	v_mul_f32_e32 v146, v217, v146
	s_and_b64 s[36:37], s[36:37], vcc
	v_cndmask_b32_e64 v6, 0, v146, s[36:37]
	v_cmp_gt_u32_e64 s[36:37], s13, v216
	v_mul_f32_e32 v147, v220, v147
	s_and_b64 s[36:37], s[36:37], vcc
	v_cndmask_b32_e64 v7, 0, v147, s[36:37]
	v_cmp_gt_u32_e64 s[36:37], s13, v218
	v_mul_f32_e32 v148, v221, v148
	s_and_b64 s[36:37], s[36:37], vcc
	v_cndmask_b32_e64 v8, 0, v148, s[36:37]
	v_cmp_gt_u32_e64 s[36:37], s13, v219
	v_mul_f32_e32 v149, v223, v149
	s_and_b64 s[36:37], s[36:37], vcc
	v_cndmask_b32_e64 v9, 0, v149, s[36:37]
	v_cmp_gt_u32_e64 s[36:37], s13, v222
	v_mul_f32_e32 v150, v225, v150
	s_and_b64 s[36:37], s[36:37], vcc
	v_cndmask_b32_e64 v10, 0, v150, s[36:37]
	v_cmp_gt_u32_e64 s[36:37], s13, v224
	v_mul_f32_e32 v151, v227, v151
	s_and_b64 s[36:37], s[36:37], vcc
	v_cndmask_b32_e64 v11, 0, v151, s[36:37]
	v_cmp_gt_u32_e64 s[36:37], s13, v226
	v_mul_f32_e32 v152, v229, v152
	s_and_b64 s[36:37], s[36:37], vcc
	v_cndmask_b32_e64 v12, 0, v152, s[36:37]
	v_cmp_gt_u32_e64 s[36:37], s13, v228
	v_mul_f32_e32 v153, v231, v153
	s_and_b64 s[36:37], s[36:37], vcc
	v_cndmask_b32_e64 v13, 0, v153, s[36:37]
	v_cmp_gt_u32_e64 s[36:37], s13, v230
	v_mul_f32_e32 v154, v233, v154
	s_and_b64 s[36:37], s[36:37], vcc
	v_cndmask_b32_e64 v14, 0, v154, s[36:37]
	v_cmp_gt_u32_e64 s[36:37], s13, v232
	v_mul_f32_e32 v155, v234, v155
	s_and_b64 vcc, s[36:37], vcc
	v_cndmask_b32_e32 v15, 0, v155, vcc
	s_mul_hi_i32 s4, s8, 0x2e8ba2e9
	s_lshr_b32 s8, s4, 31
	s_ashr_i32 s4, s4, 4
	s_add_i32 s8, s4, s8
	s_mul_i32 s4, s8, 0x3ffff50
	s_add_i32 s9, s30, s7
	s_add_i32 s9, s9, s4
	s_and_b32 s4, s9, 0x3fffffc
	s_or_b32 s4, s4, s5
	s_lshl_b32 s4, s4, 6
	ds_read2_b32 v[134:135], v52 offset0:65 offset1:73
	ds_read2_b32 v[136:137], v52 offset1:8
	v_add_u32_e32 v138, s4, v51
	s_lshl_b32 s8, s8, 7
	v_ashrrev_i32_e32 v139, 31, v138
	s_ashr_i32 s9, s8, 31
	v_lshlrev_b64 v[138:139], 12, v[138:139]
	v_lshl_add_u64 v[138:139], s[62:63], 0, v[138:139]
	s_lshl_b64 s[8:9], s[8:9], 1
	v_lshl_add_u64 v[138:139], v[138:139], 0, s[8:9]
	s_waitcnt lgkmcnt(0)
; DEVI unsigned pk_bf16(float lo, float hi) { unsigned r; asm("v_cvt_pk_bf16_f32 %0, %1, %2" : "=v"(r) : "v"(lo), "v"(hi)); return r; }
; DEVI void cvt_job(LAS float* tile, const float* src, int srcK, int srcN, bf16_t* dst, int dstLd, int dstRows, int dstCol0, int mode, const float* gk = nullptr) {
;     ...
;         for (int i = 0; i < 16; ++i) { const int k = kap0 + ty + 8 * i - dstCol0; regs[i] = (nok && k >= 0 && k < srcK) ? raw[i] * gs[i] : 0.f; }
;     };
;     auto emit = [&](int t, float (&regs)[16]) {
; #pragma unroll
;         for (int i = 0; i < 16; ++i) tile[(ty + 8 * i) * 65 + tx] = regs[i];
;         __syncthreads();
;         int rho0, kap0, n0; coords(t, rho0, kap0, n0);
;         const int tn = t + 2 * gridDim.x;
;         if (tn < ntot) gl(tn, regs);
; #pragma unroll
;         for (int i = 0; i < 8; ++i) { const int row = ty + 8 * i;
;             const float lo = tile[(2 * tx) * 65 + row], hi = tile[(2 * tx + 1) * 65 + row];
;             *(unsigned*)(dst + (size_t)(rho0 + row) * dstLd + kap0 + 2 * tx) = pk_bf16(lo, hi); }
;         __syncthreads();
	v_cvt_pk_bf16_f32 v134, v136, v134
	v_lshl_add_u64 v[138:139], v[138:139], 0, v[32:33]
	global_store_dword v[138:139], v134, off
	v_add_u32_e32 v134, s4, v53
	v_cvt_pk_bf16_f32 v136, v137, v135
	v_ashrrev_i32_e32 v135, 31, v134
	v_lshlrev_b64 v[134:135], 12, v[134:135]
	v_lshl_add_u64 v[134:135], s[62:63], 0, v[134:135]
	v_lshl_add_u64 v[134:135], v[134:135], 0, s[8:9]
	v_lshl_add_u64 v[134:135], v[134:135], 0, v[32:33]
	global_store_dword v[134:135], v136, off
	ds_read2_b32 v[134:135], v52 offset0:16 offset1:24
	ds_read2_b32 v[136:137], v52 offset0:81 offset1:89
	v_add_u32_e32 v138, s4, v54
	v_ashrrev_i32_e32 v139, 31, v138
	v_lshlrev_b64 v[138:139], 12, v[138:139]
	v_lshl_add_u64 v[138:139], s[62:63], 0, v[138:139]
	v_lshl_add_u64 v[138:139], v[138:139], 0, s[8:9]
	s_waitcnt lgkmcnt(0)
	v_cvt_pk_bf16_f32 v134, v134, v136
	v_lshl_add_u64 v[138:139], v[138:139], 0, v[32:33]
	global_store_dword v[138:139], v134, off
	v_add_u32_e32 v134, s4, v55
	v_cvt_pk_bf16_f32 v136, v135, v137
	v_ashrrev_i32_e32 v135, 31, v134
	v_lshlrev_b64 v[134:135], 12, v[134:135]
	v_lshl_add_u64 v[134:135], s[62:63], 0, v[134:135]
	v_lshl_add_u64 v[134:135], v[134:135], 0, s[8:9]
	v_lshl_add_u64 v[134:135], v[134:135], 0, v[32:33]
	global_store_dword v[134:135], v136, off
	ds_read2_b32 v[134:135], v52 offset0:32 offset1:40
	ds_read2_b32 v[136:137], v52 offset0:97 offset1:105
	v_add_u32_e32 v138, s4, v56
	v_ashrrev_i32_e32 v139, 31, v138
	v_lshlrev_b64 v[138:139], 12, v[138:139]
	v_lshl_add_u64 v[138:139], s[62:63], 0, v[138:139]
	v_lshl_add_u64 v[138:139], v[138:139], 0, s[8:9]
	s_waitcnt lgkmcnt(0)
	v_cvt_pk_bf16_f32 v134, v134, v136
	v_lshl_add_u64 v[138:139], v[138:139], 0, v[32:33]
	global_store_dword v[138:139], v134, off
	v_add_u32_e32 v134, s4, v57
	v_cvt_pk_bf16_f32 v136, v135, v137
	v_ashrrev_i32_e32 v135, 31, v134
	v_lshlrev_b64 v[134:135], 12, v[134:135]
	v_lshl_add_u64 v[134:135], s[62:63], 0, v[134:135]
	v_lshl_add_u64 v[134:135], v[134:135], 0, s[8:9]
	v_lshl_add_u64 v[134:135], v[134:135], 0, v[32:33]
	global_store_dword v[134:135], v136, off
	ds_read2_b32 v[134:135], v52 offset0:48 offset1:56
	ds_read2_b32 v[136:137], v52 offset0:113 offset1:121
	v_add_u32_e32 v138, s4, v58
	v_ashrrev_i32_e32 v139, 31, v138
	v_lshlrev_b64 v[138:139], 12, v[138:139]
	v_lshl_add_u64 v[138:139], s[62:63], 0, v[138:139]
	v_lshl_add_u64 v[138:139], v[138:139], 0, s[8:9]
	s_waitcnt lgkmcnt(0)
	v_cvt_pk_bf16_f32 v134, v134, v136
	v_lshl_add_u64 v[138:139], v[138:139], 0, v[32:33]
	global_store_dword v[138:139], v134, off
	v_add_u32_e32 v134, s4, v59
	v_cvt_pk_bf16_f32 v136, v135, v137
	v_ashrrev_i32_e32 v135, 31, v134
	v_lshlrev_b64 v[134:135], 12, v[134:135]
	v_lshl_add_u64 v[134:135], s[62:63], 0, v[134:135]
	v_lshl_add_u64 v[134:135], v[134:135], 0, s[8:9]
	v_lshl_add_u64 v[134:135], v[134:135], 0, v[32:33]
	global_store_dword v[134:135], v136, off
	v_cmp_gt_i32_e32 vcc, s12, v63
	v_cmp_gt_u32_e64 s[36:37], s13, v62
	s_waitcnt vmcnt(23)
	v_mul_f32_e32 v16, v65, v16
	s_and_b64 s[36:37], s[36:37], vcc
	v_cndmask_b32_e64 v16, 0, v16, s[36:37]
	v_cmp_gt_u32_e64 s[36:37], s13, v64
	s_waitcnt vmcnt(22)
	v_mul_f32_e32 v17, v67, v17
	s_and_b64 s[36:37], s[36:37], vcc
	v_cndmask_b32_e64 v17, 0, v17, s[36:37]
	v_cmp_gt_u32_e64 s[36:37], s13, v66
	s_waitcnt vmcnt(21)
	v_mul_f32_e32 v18, v69, v18
	s_and_b64 s[36:37], s[36:37], vcc
	v_cndmask_b32_e64 v18, 0, v18, s[36:37]
	v_cmp_gt_u32_e64 s[36:37], s13, v68
	s_waitcnt vmcnt(20)
	v_mul_f32_e32 v19, v71, v19
	s_and_b64 s[36:37], s[36:37], vcc
	v_cndmask_b32_e64 v19, 0, v19, s[36:37]
	v_cmp_gt_u32_e64 s[36:37], s13, v70
	s_waitcnt vmcnt(19)
	v_mul_f32_e32 v20, v73, v20
	s_and_b64 s[36:37], s[36:37], vcc
	v_cndmask_b32_e64 v20, 0, v20, s[36:37]
	v_cmp_gt_u32_e64 s[36:37], s13, v72
	s_waitcnt vmcnt(18)
	v_mul_f32_e32 v21, v75, v21
	s_and_b64 s[36:37], s[36:37], vcc
	v_cndmask_b32_e64 v21, 0, v21, s[36:37]
	v_cmp_gt_u32_e64 s[36:37], s13, v74
	s_waitcnt vmcnt(17)
	v_mul_f32_e32 v22, v77, v22
	s_and_b64 s[36:37], s[36:37], vcc
	v_cndmask_b32_e64 v22, 0, v22, s[36:37]
	v_cmp_gt_u32_e64 s[36:37], s13, v76
	s_waitcnt vmcnt(16)
	v_mul_f32_e32 v23, v80, v23
	s_and_b64 s[36:37], s[36:37], vcc
	v_cndmask_b32_e64 v23, 0, v23, s[36:37]
	v_cmp_gt_u32_e64 s[36:37], s13, v78
	s_waitcnt vmcnt(15)
	v_mul_f32_e32 v24, v81, v24
	s_and_b64 s[36:37], s[36:37], vcc
	v_cndmask_b32_e64 v24, 0, v24, s[36:37]
	v_cmp_gt_u32_e64 s[36:37], s13, v79
	s_waitcnt vmcnt(14)
	v_mul_f32_e32 v25, v83, v25
	s_and_b64 s[36:37], s[36:37], vcc
	v_cndmask_b32_e64 v25, 0, v25, s[36:37]
	v_cmp_gt_u32_e64 s[36:37], s13, v82
	s_waitcnt vmcnt(13)
	v_mul_f32_e32 v26, v85, v26
	s_and_b64 s[36:37], s[36:37], vcc
	v_cndmask_b32_e64 v26, 0, v26, s[36:37]
	v_cmp_gt_u32_e64 s[36:37], s13, v84
	s_waitcnt vmcnt(12)
	v_mul_f32_e32 v27, v87, v27
	s_and_b64 s[36:37], s[36:37], vcc
	v_cndmask_b32_e64 v27, 0, v27, s[36:37]
	v_cmp_gt_u32_e64 s[36:37], s13, v86
	s_waitcnt vmcnt(11)
	v_mul_f32_e32 v28, v89, v28
	s_and_b64 s[36:37], s[36:37], vcc
	v_cndmask_b32_e64 v28, 0, v28, s[36:37]
	v_cmp_gt_u32_e64 s[36:37], s13, v88
	s_waitcnt vmcnt(10)
	v_mul_f32_e32 v29, v91, v29
	s_and_b64 s[36:37], s[36:37], vcc
	v_cndmask_b32_e64 v29, 0, v29, s[36:37]
	v_cmp_gt_u32_e64 s[36:37], s13, v90
	s_waitcnt vmcnt(9)
	v_mul_f32_e32 v30, v93, v30
	s_and_b64 s[36:37], s[36:37], vcc
	v_cndmask_b32_e64 v30, 0, v30, s[36:37]
	v_cmp_gt_u32_e64 s[36:37], s13, v92
	s_waitcnt vmcnt(8)
	v_mul_f32_e32 v31, v94, v31
	s_and_b64 vcc, s[36:37], vcc
	v_cndmask_b32_e32 v31, 0, v31, vcc
	s_barrier

; DEVI void cvt_job(LAS float* tile, const float* src, int srcK, int srcN, bf16_t* dst, int dstLd, int dstRows, int dstCol0, int mode, const float* gk = nullptr) {
;     ...
;     auto gl = [&](int t, float (&regs)[16]) {
;         int rho0, kap0, n0; coords(t, rho0, kap0, n0);
;         const int n = n0 + tx, nc = n < srcN ? n : srcN - 1;
;         const bool nok = n < srcN;
;         float raw[16], gs[16];
; #pragma unroll
;         for (int i = 0; i < 16; ++i) { const int k = kap0 + ty + 8 * i - dstCol0; const int kc = k < 0 ? 0 : (k < srcK ? k : srcK - 1);
;             raw[i] = __builtin_nontemporal_load(src + (size_t)kc * srcN + nc); }
;         if (gk) {
; #pragma unroll
;             for (int i = 0; i < 16; ++i) { const int k = kap0 + ty + 8 * i - dstCol0; const int kc = k < 0 ? 0 : (k < srcK ? k : srcK - 1); gs[i] = gk[kc]; }
;         } else {
; #pragma unroll
;             for (int i = 0; i < 16; ++i) gs[i] = 1.0f;
;         }
; #pragma unroll
;         for (int i = 0; i < 16; ++i) { const int k = kap0 + ty + 8 * i - dstCol0; regs[i] = (nok && k >= 0 && k < srcK) ? raw[i] * gs[i] : 0.f; }
;     };
;     auto emit = [&](int t, float (&regs)[16]) {
; #pragma unroll
;         for (int i = 0; i < 16; ++i) tile[(ty + 8 * i) * 65 + tx] = regs[i];
;         __syncthreads();
;         int rho0, kap0, n0; coords(t, rho0, kap0, n0);
;         const int tn = t + 2 * gridDim.x;
;         if (tn < ntot) gl(tn, regs);
.LBB0_339:
	s_add_i32 s14, s4, s30
	s_cmpk_gt_i32 s14, 0x57f
	s_cselect_b64 s[2:3], -1, 0
	s_and_b64 vcc, exec, s[2:3]
	ds_write_b32 v60, v0
	ds_write_b32 v60, v1 offset:2080
	ds_write_b32 v60, v2 offset:4160
	ds_write_b32 v60, v3 offset:6240
	ds_write_b32 v60, v4 offset:8320
	ds_write_b32 v60, v5 offset:10400
	ds_write_b32 v60, v6 offset:12480
	ds_write_b32 v60, v7 offset:14560
	ds_write_b32 v60, v8 offset:16640
	ds_write_b32 v60, v9 offset:18720
	ds_write_b32 v60, v10 offset:20800
	ds_write_b32 v60, v11 offset:22880
	ds_write_b32 v60, v12 offset:24960
	ds_write_b32 v60, v13 offset:27040
	ds_write_b32 v60, v14 offset:29120
	ds_write_b32 v60, v15 offset:31200
	s_waitcnt lgkmcnt(0)
	s_barrier
	s_cbranch_vccnz .LBB0_344
	s_mul_hi_i32 s8, s14, 0x2e8ba2e9
	s_lshr_b32 s9, s8, 31
	s_ashr_i32 s8, s8, 4
	s_add_i32 s8, s8, s9
	s_mul_i32 s9, s8, 0x3ffff50
	s_add_i32 s15, s10, s7
	s_add_i32 s15, s15, s9
	s_and_b32 s9, s15, 0x3fffffc
	s_or_b32 s9, s9, s6
	s_lshl_b32 s9, s9, 6
	s_ashr_i32 s15, s9, 1
	s_and_b32 s15, s15, 0xffffff80
	s_and_b32 s9, s9, 64
	s_or_b32 s9, s9, s15
	v_or_b32_e32 v203, s9, v50
	v_min_i32_e32 v140, 0x15ff, v203
	v_lshl_add_u32 v202, s8, 7, v51
	v_ashrrev_i32_e32 v141, 31, v140
	v_lshl_add_u64 v[234:235], v[140:141], 2, s[0:1]
	v_med3_i32 v140, v202, 0, v61
	v_mad_u64_u32 v[142:143], s[8:9], v140, s11, v[234:235]
	v_add_u32_e32 v204, 8, v202
	global_load_dword v205, v[142:143], off nt
	v_med3_i32 v142, v204, 0, v61
	v_mad_u64_u32 v[144:145], s[8:9], v142, s11, v[234:235]
	v_add_u32_e32 v206, 16, v202
	global_load_dword v207, v[144:145], off nt
	v_med3_i32 v144, v206, 0, v61
	v_mad_u64_u32 v[146:147], s[8:9], v144, s11, v[234:235]
	v_add_u32_e32 v208, 24, v202
	global_load_dword v209, v[146:147], off nt
	v_med3_i32 v146, v208, 0, v61
	v_mad_u64_u32 v[148:149], s[8:9], v146, s11, v[234:235]
	v_add_u32_e32 v210, 32, v202
	global_load_dword v211, v[148:149], off nt
	v_med3_i32 v148, v210, 0, v61
	v_mad_u64_u32 v[150:151], s[8:9], v148, s11, v[234:235]
	v_add_u32_e32 v212, 40, v202
	global_load_dword v213, v[150:151], off nt
	v_med3_i32 v150, v212, 0, v61
	v_mad_u64_u32 v[152:153], s[8:9], v150, s11, v[234:235]
	v_add_u32_e32 v214, 48, v202
	global_load_dword v215, v[152:153], off nt
	v_med3_i32 v152, v214, 0, v61
	v_mad_u64_u32 v[154:155], s[8:9], v152, s11, v[234:235]
	v_add_u32_e32 v216, 56, v202
	global_load_dword v217, v[154:155], off nt
	v_med3_i32 v154, v216, 0, v61
	v_mad_u64_u32 v[174:175], s[8:9], v154, s11, v[234:235]
	v_add_u32_e32 v218, 64, v202
	global_load_dword v220, v[174:175], off nt
	v_med3_i32 v174, v218, 0, v61
	v_mad_u64_u32 v[176:177], s[8:9], v174, s11, v[234:235]
	v_add_u32_e32 v219, 0x48, v202
	global_load_dword v221, v[176:177], off nt
	v_med3_i32 v176, v219, 0, v61
	v_mad_u64_u32 v[178:179], s[8:9], v176, s11, v[234:235]
	v_add_u32_e32 v222, 0x50, v202
	global_load_dword v223, v[178:179], off nt
	v_med3_i32 v178, v222, 0, v61
	v_mad_u64_u32 v[180:181], s[8:9], v178, s11, v[234:235]
	v_add_u32_e32 v224, 0x58, v202
	global_load_dword v225, v[180:181], off nt
	v_med3_i32 v180, v224, 0, v61
	v_mad_u64_u32 v[182:183], s[8:9], v180, s11, v[234:235]
	v_add_u32_e32 v226, 0x60, v202
	global_load_dword v227, v[182:183], off nt
	v_med3_i32 v182, v226, 0, v61
	v_mad_u64_u32 v[184:185], s[8:9], v182, s11, v[234:235]
	v_add_u32_e32 v228, 0x68, v202
	global_load_dword v229, v[184:185], off nt
	v_med3_i32 v184, v228, 0, v61
	v_mad_u64_u32 v[186:187], s[8:9], v184, s11, v[234:235]
	v_add_u32_e32 v230, 0x70, v202
	global_load_dword v231, v[186:187], off nt
	v_med3_i32 v186, v230, 0, v61
	v_mad_u64_u32 v[188:189], s[8:9], v186, s11, v[234:235]
	v_add_u32_e32 v232, 0x78, v202
	global_load_dword v233, v[188:189], off nt
	v_med3_i32 v188, v232, 0, v61
	v_mad_u64_u32 v[234:235], s[8:9], v188, s11, v[234:235]
	global_load_dword v234, v[234:235], off nt
	v_readlane_b32 s8, v240, 48
	v_readlane_b32 s9, v240, 49
	s_and_b64 vcc, exec, s[8:9]
	s_cbranch_vccnz .LBB0_342
	v_mov_b32_e32 v141, v33
	v_mov_b32_e32 v143, v33
	v_mov_b32_e32 v145, v33
	v_mov_b32_e32 v147, v33
	v_mov_b32_e32 v149, v33
	v_mov_b32_e32 v151, v33
	v_mov_b32_e32 v153, v33
	v_mov_b32_e32 v155, v33
	v_mov_b32_e32 v175, v33
	v_mov_b32_e32 v177, v33
	v_mov_b32_e32 v179, v33
	v_mov_b32_e32 v181, v33
	v_lshl_add_u64 v[140:141], v[140:141], 2, s[38:39]
	v_lshl_add_u64 v[142:143], v[142:143], 2, s[38:39]
	v_lshl_add_u64 v[144:145], v[144:145], 2, s[38:39]
	v_lshl_add_u64 v[146:147], v[146:147], 2, s[38:39]
	v_lshl_add_u64 v[148:149], v[148:149], 2, s[38:39]
	v_lshl_add_u64 v[150:151], v[150:151], 2, s[38:39]
	v_lshl_add_u64 v[152:153], v[152:153], 2, s[38:39]
	v_lshl_add_u64 v[154:155], v[154:155], 2, s[38:39]
	v_mov_b32_e32 v183, v33
	v_mov_b32_e32 v185, v33
	v_mov_b32_e32 v187, v33
	v_mov_b32_e32 v189, v33
	global_load_dword v140, v[140:141], off
	s_nop 0
	global_load_dword v141, v[142:143], off
	s_nop 0
	global_load_dword v142, v[144:145], off
	global_load_dword v143, v[146:147], off
	s_nop 0
	global_load_dword v144, v[148:149], off
	global_load_dword v145, v[150:151], off
	global_load_dword v146, v[152:153], off
	global_load_dword v147, v[154:155], off
	v_lshl_add_u64 v[148:149], v[174:175], 2, s[38:39]
	v_lshl_add_u64 v[150:151], v[176:177], 2, s[38:39]
	v_lshl_add_u64 v[152:153], v[178:179], 2, s[38:39]
	v_lshl_add_u64 v[154:155], v[180:181], 2, s[38:39]
	v_lshl_add_u64 v[174:175], v[182:183], 2, s[38:39]
	v_lshl_add_u64 v[176:177], v[184:185], 2, s[38:39]
	v_lshl_add_u64 v[178:179], v[186:187], 2, s[38:39]
	v_lshl_add_u64 v[180:181], v[188:189], 2, s[38:39]
	global_load_dword v148, v[148:149], off
	s_nop 0
	global_load_dword v149, v[150:151], off
	s_nop 0
	global_load_dword v150, v[152:153], off
	global_load_dword v151, v[154:155], off
	s_nop 0
	global_load_dword v152, v[174:175], off
	global_load_dword v153, v[176:177], off
	global_load_dword v154, v[178:179], off
	global_load_dword v155, v[180:181], off
	s_branch .LBB0_343
; DEVI unsigned pk_bf16(float lo, float hi) { unsigned r; asm("v_cvt_pk_bf16_f32 %0, %1, %2" : "=v"(r) : "v"(lo), "v"(hi)); return r; }
; DEVI void cvt_job(LAS float* tile, const float* src, int srcK, int srcN, bf16_t* dst, int dstLd, int dstRows, int dstCol0, int mode, const float* gk = nullptr) {
;     ...
;         } else {
; #pragma unroll
;             for (int i = 0; i < 16; ++i) gs[i] = 1.0f;
;         }
; #pragma unroll
;         for (int i = 0; i < 16; ++i) { const int k = kap0 + ty + 8 * i - dstCol0; regs[i] = (nok && k >= 0 && k < srcK) ? raw[i] * gs[i] : 0.f; }
;     };
;     auto emit = [&](int t, float (&regs)[16]) {
; #pragma unroll
;         for (int i = 0; i < 16; ++i) tile[(ty + 8 * i) * 65 + tx] = regs[i];
;         __syncthreads();
;         int rho0, kap0, n0; coords(t, rho0, kap0, n0);
;         const int tn = t + 2 * gridDim.x;
;         if (tn < ntot) gl(tn, regs);
; #pragma unroll
;         for (int i = 0; i < 8; ++i) { const int row = ty + 8 * i;
;             const float lo = tile[(2 * tx) * 65 + row], hi = tile[(2 * tx + 1) * 65 + row];
;             *(unsigned*)(dst + (size_t)(rho0 + row) * dstLd + kap0 + 2 * tx) = pk_bf16(lo, hi); }
;         __syncthreads();
.LBB0_342:
	v_mov_b32_e32 v155, 1.0
	v_mov_b32_e32 v154, 1.0
	v_mov_b32_e32 v153, 1.0
	v_mov_b32_e32 v152, 1.0
	v_mov_b32_e32 v151, 1.0
	v_mov_b32_e32 v150, 1.0
	v_mov_b32_e32 v149, 1.0
	v_mov_b32_e32 v148, 1.0
	v_mov_b32_e32 v147, 1.0
	v_mov_b32_e32 v146, 1.0
	v_mov_b32_e32 v145, 1.0
	v_mov_b32_e32 v144, 1.0
	v_mov_b32_e32 v143, 1.0
	v_mov_b32_e32 v142, 1.0
	v_mov_b32_e32 v141, 1.0
	v_mov_b32_e32 v140, 1.0
.LBB0_343:
.LBB0_344:
	s_mul_hi_i32 s8, s4, 0x2e8ba2e9
	s_lshr_b32 s9, s8, 31
	s_ashr_i32 s8, s8, 4
	s_add_i32 s8, s8, s9
	s_mul_i32 s9, s8, 0x3ffff50
	s_add_i32 s9, s7, s9
	s_and_b32 s9, s9, 0x3fffffc
	s_or_b32 s9, s9, s6
	s_lshl_b32 s15, s9, 6
	ds_read2_b32 v[34:35], v52 offset0:65 offset1:73
	ds_read2_b32 v[36:37], v52 offset1:8
	v_add_u32_e32 v38, s15, v51
	s_lshl_b32 s8, s8, 7
	v_ashrrev_i32_e32 v39, 31, v38
	s_ashr_i32 s9, s8, 31
	v_lshlrev_b64 v[38:39], 12, v[38:39]
	v_lshl_add_u64 v[38:39], s[62:63], 0, v[38:39]
	s_lshl_b64 s[8:9], s[8:9], 1
	v_lshl_add_u64 v[38:39], v[38:39], 0, s[8:9]
	s_waitcnt lgkmcnt(0)
	v_cvt_pk_bf16_f32 v34, v36, v34
	v_lshl_add_u64 v[38:39], v[38:39], 0, v[32:33]
	global_store_dword v[38:39], v34, off
	v_add_u32_e32 v34, s15, v53
	v_cvt_pk_bf16_f32 v36, v37, v35
	v_ashrrev_i32_e32 v35, 31, v34
	v_lshlrev_b64 v[34:35], 12, v[34:35]
	v_lshl_add_u64 v[34:35], s[62:63], 0, v[34:35]
	v_lshl_add_u64 v[34:35], v[34:35], 0, s[8:9]
	v_lshl_add_u64 v[34:35], v[34:35], 0, v[32:33]
	global_store_dword v[34:35], v36, off
	ds_read2_b32 v[34:35], v52 offset0:16 offset1:24
	ds_read2_b32 v[36:37], v52 offset0:81 offset1:89
	v_add_u32_e32 v38, s15, v54
	v_ashrrev_i32_e32 v39, 31, v38
	v_lshlrev_b64 v[38:39], 12, v[38:39]
	v_lshl_add_u64 v[38:39], s[62:63], 0, v[38:39]
	v_lshl_add_u64 v[38:39], v[38:39], 0, s[8:9]
	s_waitcnt lgkmcnt(0)
	v_cvt_pk_bf16_f32 v34, v34, v36
	v_lshl_add_u64 v[38:39], v[38:39], 0, v[32:33]
	global_store_dword v[38:39], v34, off
	v_add_u32_e32 v34, s15, v55
	v_cvt_pk_bf16_f32 v36, v35, v37
	v_ashrrev_i32_e32 v35, 31, v34
	v_lshlrev_b64 v[34:35], 12, v[34:35]
	v_lshl_add_u64 v[34:35], s[62:63], 0, v[34:35]
	v_lshl_add_u64 v[34:35], v[34:35], 0, s[8:9]
	v_lshl_add_u64 v[34:35], v[34:35], 0, v[32:33]
	global_store_dword v[34:35], v36, off
	ds_read2_b32 v[34:35], v52 offset0:32 offset1:40
	ds_read2_b32 v[36:37], v52 offset0:97 offset1:105
	v_add_u32_e32 v38, s15, v56
	v_ashrrev_i32_e32 v39, 31, v38
	v_lshlrev_b64 v[38:39], 12, v[38:39]
	v_lshl_add_u64 v[38:39], s[62:63], 0, v[38:39]
	v_lshl_add_u64 v[38:39], v[38:39], 0, s[8:9]
	s_waitcnt lgkmcnt(0)
	v_cvt_pk_bf16_f32 v34, v34, v36
	v_lshl_add_u64 v[38:39], v[38:39], 0, v[32:33]
	global_store_dword v[38:39], v34, off
	v_add_u32_e32 v34, s15, v57
	v_cvt_pk_bf16_f32 v36, v35, v37
	v_ashrrev_i32_e32 v35, 31, v34
	v_lshlrev_b64 v[34:35], 12, v[34:35]
	v_lshl_add_u64 v[34:35], s[62:63], 0, v[34:35]
	v_lshl_add_u64 v[34:35], v[34:35], 0, s[8:9]
	v_lshl_add_u64 v[34:35], v[34:35], 0, v[32:33]
	global_store_dword v[34:35], v36, off
	ds_read2_b32 v[34:35], v52 offset0:48 offset1:56
	ds_read2_b32 v[36:37], v52 offset0:113 offset1:121
	v_add_u32_e32 v38, s15, v58
	v_ashrrev_i32_e32 v39, 31, v38
	v_lshlrev_b64 v[38:39], 12, v[38:39]
	v_lshl_add_u64 v[38:39], s[62:63], 0, v[38:39]
	v_lshl_add_u64 v[38:39], v[38:39], 0, s[8:9]
	s_waitcnt lgkmcnt(0)
	v_cvt_pk_bf16_f32 v34, v34, v36
	v_lshl_add_u64 v[38:39], v[38:39], 0, v[32:33]
	global_store_dword v[38:39], v34, off
	v_add_u32_e32 v34, s15, v59
	v_cvt_pk_bf16_f32 v36, v35, v37
	v_ashrrev_i32_e32 v35, 31, v34
	v_lshlrev_b64 v[34:35], 12, v[34:35]
	v_lshl_add_u64 v[34:35], s[62:63], 0, v[34:35]
	v_lshl_add_u64 v[34:35], v[34:35], 0, s[8:9]
	s_add_i32 s8, s33, s4
	v_lshl_add_u64 v[34:35], v[34:35], 0, v[32:33]
	s_cmpk_gt_i32 s8, 0x57f
	global_store_dword v[34:35], v36, off
	s_barrier
	s_cbranch_scc1 .LBB0_338
; DEVI void cvt_job(LAS float* tile, const float* src, int srcK, int srcN, bf16_t* dst, int dstLd, int dstRows, int dstCol0, int mode, const float* gk = nullptr) {
;     ...
;         for (int i = 0; i < 16; ++i) { const int k = kap0 + ty + 8 * i - dstCol0; const int kc = k < 0 ? 0 : (k < srcK ? k : srcK - 1);
;             raw[i] = __builtin_nontemporal_load(src + (size_t)kc * srcN + nc); }
;         if (gk) {
; #pragma unroll
;             for (int i = 0; i < 16; ++i) { const int k = kap0 + ty + 8 * i - dstCol0; const int kc = k < 0 ? 0 : (k < srcK ? k : srcK - 1); gs[i] = gk[kc]; }
;         } else {
; #pragma unroll
;             for (int i = 0; i < 16; ++i) gs[i] = 1.0f;
;         }
; #pragma unroll
;         for (int i = 0; i < 16; ++i) { const int k = kap0 + ty + 8 * i - dstCol0; regs[i] = (nok && k >= 0 && k < srcK) ? raw[i] * gs[i] : 0.f; }
;     };
;     auto emit = [&](int t, float (&regs)[16]) {
; #pragma unroll
;         for (int i = 0; i < 16; ++i) tile[(ty + 8 * i) * 65 + tx] = regs[i];
;         __syncthreads();
;         int rho0, kap0, n0; coords(t, rho0, kap0, n0);
;         const int tn = t + 2 * gridDim.x;
;         if (tn < ntot) gl(tn, regs);
;     ...
;     while (t < ntot) {
;         emit(t, regsA);
;         if (t + G < ntot) emit(t + G, regsB);
;         t += 2 * G;
	s_add_i32 s4, s31, s4
	s_cmpk_gt_i32 s4, 0x57f
	ds_write_b32 v60, v16
	ds_write_b32 v60, v17 offset:2080
	ds_write_b32 v60, v18 offset:4160
	ds_write_b32 v60, v19 offset:6240
	ds_write_b32 v60, v20 offset:8320
	ds_write_b32 v60, v21 offset:10400
	ds_write_b32 v60, v22 offset:12480
	ds_write_b32 v60, v23 offset:14560
	ds_write_b32 v60, v24 offset:16640
	ds_write_b32 v60, v25 offset:18720
	ds_write_b32 v60, v26 offset:20800
	ds_write_b32 v60, v27 offset:22880
	ds_write_b32 v60, v28 offset:24960
	ds_write_b32 v60, v29 offset:27040
	ds_write_b32 v60, v30 offset:29120
	ds_write_b32 v60, v31 offset:31200
	s_waitcnt lgkmcnt(0)
	s_barrier
	s_cbranch_scc1 .Lcvt_stub_2
	s_mul_hi_i32 s4, s4, 0x2e8ba2e9
	s_lshr_b32 s9, s4, 31
	s_ashr_i32 s4, s4, 4
	s_add_i32 s4, s4, s9
	s_mul_i32 s9, s4, 0x3ffff50
	s_add_i32 s15, s96, s7
	s_add_i32 s15, s15, s9
	s_and_b32 s9, s15, 0x3fffffc
	s_or_b32 s9, s9, s5
	s_lshl_b32 s9, s9, 6
	s_ashr_i32 s15, s9, 1
	s_and_b32 s15, s15, 0xffffff80
	s_and_b32 s9, s9, 64
	s_or_b32 s9, s9, s15
	v_or_b32_e32 v63, s9, v50
	v_min_i32_e32 v16, 0x15ff, v63
	v_lshl_add_u32 v62, s4, 7, v51
	v_ashrrev_i32_e32 v17, 31, v16
	v_lshl_add_u64 v[94:95], v[16:17], 2, s[0:1]
	v_med3_i32 v16, v62, 0, v61
	v_mad_u64_u32 v[18:19], s[16:17], v16, s11, v[94:95]
	v_add_u32_e32 v64, 8, v62
	global_load_dword v65, v[18:19], off nt
	v_med3_i32 v18, v64, 0, v61
	v_mad_u64_u32 v[20:21], s[16:17], v18, s11, v[94:95]
	v_add_u32_e32 v66, 16, v62
	global_load_dword v67, v[20:21], off nt
	v_med3_i32 v20, v66, 0, v61
	v_mad_u64_u32 v[22:23], s[16:17], v20, s11, v[94:95]
	v_add_u32_e32 v68, 24, v62
	global_load_dword v69, v[22:23], off nt
	v_med3_i32 v22, v68, 0, v61
	v_mad_u64_u32 v[24:25], s[16:17], v22, s11, v[94:95]
	v_add_u32_e32 v70, 32, v62
	global_load_dword v71, v[24:25], off nt
	v_med3_i32 v24, v70, 0, v61
	v_mad_u64_u32 v[26:27], s[16:17], v24, s11, v[94:95]
	v_add_u32_e32 v72, 40, v62
	global_load_dword v73, v[26:27], off nt
	v_med3_i32 v26, v72, 0, v61
	v_mad_u64_u32 v[28:29], s[16:17], v26, s11, v[94:95]
	v_add_u32_e32 v74, 48, v62
	global_load_dword v75, v[28:29], off nt
	v_med3_i32 v28, v74, 0, v61
	v_mad_u64_u32 v[30:31], s[16:17], v28, s11, v[94:95]
	v_add_u32_e32 v76, 56, v62
	global_load_dword v77, v[30:31], off nt
	v_med3_i32 v30, v76, 0, v61
	v_mad_u64_u32 v[34:35], s[16:17], v30, s11, v[94:95]
	v_add_u32_e32 v78, 64, v62
	global_load_dword v80, v[34:35], off nt
	v_med3_i32 v34, v78, 0, v61
	v_mad_u64_u32 v[36:37], s[16:17], v34, s11, v[94:95]
	v_add_u32_e32 v79, 0x48, v62
	global_load_dword v81, v[36:37], off nt
	v_med3_i32 v36, v79, 0, v61
	v_mad_u64_u32 v[38:39], s[16:17], v36, s11, v[94:95]
	v_add_u32_e32 v82, 0x50, v62
	global_load_dword v83, v[38:39], off nt
	v_med3_i32 v38, v82, 0, v61
	v_mad_u64_u32 v[40:41], s[16:17], v38, s11, v[94:95]
	v_add_u32_e32 v84, 0x58, v62
	global_load_dword v85, v[40:41], off nt
	v_med3_i32 v40, v84, 0, v61
	v_mad_u64_u32 v[42:43], s[16:17], v40, s11, v[94:95]
	v_add_u32_e32 v86, 0x60, v62
	global_load_dword v87, v[42:43], off nt
	v_med3_i32 v42, v86, 0, v61
	v_mad_u64_u32 v[44:45], s[16:17], v42, s11, v[94:95]
	v_add_u32_e32 v88, 0x68, v62
	global_load_dword v89, v[44:45], off nt
	v_med3_i32 v44, v88, 0, v61
	v_mad_u64_u32 v[46:47], s[16:17], v44, s11, v[94:95]
	v_add_u32_e32 v90, 0x70, v62
	global_load_dword v91, v[46:47], off nt
	v_med3_i32 v46, v90, 0, v61
	v_mad_u64_u32 v[48:49], s[16:17], v46, s11, v[94:95]
	v_add_u32_e32 v92, 0x78, v62
	global_load_dword v93, v[48:49], off nt
	v_med3_i32 v48, v92, 0, v61
	v_mad_u64_u32 v[94:95], s[16:17], v48, s11, v[94:95]
	global_load_dword v94, v[94:95], off nt
	v_readlane_b32 s16, v240, 48
	v_readlane_b32 s17, v240, 49
	s_and_b64 vcc, exec, s[16:17]
	s_cbranch_vccz .LBB0_335
	v_mov_b32_e32 v31, 1.0
	v_mov_b32_e32 v30, 1.0
	v_mov_b32_e32 v29, 1.0
	v_mov_b32_e32 v28, 1.0
	v_mov_b32_e32 v27, 1.0
	v_mov_b32_e32 v26, 1.0
	v_mov_b32_e32 v25, 1.0
	v_mov_b32_e32 v24, 1.0
	v_mov_b32_e32 v23, 1.0
	v_mov_b32_e32 v22, 1.0
	v_mov_b32_e32 v21, 1.0
	v_mov_b32_e32 v20, 1.0
	v_mov_b32_e32 v19, 1.0
	v_mov_b32_e32 v18, 1.0
	v_mov_b32_e32 v17, 1.0
	v_mov_b32_e32 v16, 1.0
	s_waitcnt vmcnt(24)
	s_branch .LBB0_336

; DEVI unsigned pk_bf16(float lo, float hi) { unsigned r; asm("v_cvt_pk_bf16_f32 %0, %1, %2" : "=v"(r) : "v"(lo), "v"(hi)); return r; }
; DEVI void cvt_job(LAS float* tile, const float* src, int srcK, int srcN, bf16_t* dst, int dstLd, int dstRows, int dstCol0, int mode, const float* gk = nullptr) {
;     ...
;         for (int i = 0; i < 16; ++i) { const int k = kap0 + ty + 8 * i - dstCol0; regs[i] = (nok && k >= 0 && k < srcK) ? raw[i] * gs[i] : 0.f; }
;     };
;     auto emit = [&](int t, float (&regs)[16]) {
; #pragma unroll
;         for (int i = 0; i < 16; ++i) tile[(ty + 8 * i) * 65 + tx] = regs[i];
;         __syncthreads();
;         int rho0, kap0, n0; coords(t, rho0, kap0, n0);
;         const int tn = t + 2 * gridDim.x;
;         if (tn < ntot) gl(tn, regs);
; #pragma unroll
;         for (int i = 0; i < 8; ++i) { const int row = ty + 8 * i;
;             const float lo = tile[(2 * tx) * 65 + row], hi = tile[(2 * tx + 1) * 65 + row];
;             *(unsigned*)(dst + (size_t)(rho0 + row) * dstLd + kap0 + 2 * tx) = pk_bf16(lo, hi); }
.LBB0_361:
.LBB0_362:
	v_cmp_gt_i32_e32 vcc, s12, v203
	v_cmp_gt_u32_e64 s[36:37], s13, v202
	v_mul_f32_e32 v140, v205, v140
	s_and_b64 s[36:37], s[36:37], vcc
	v_cndmask_b32_e64 v0, 0, v140, s[36:37]
	v_cmp_gt_u32_e64 s[36:37], s13, v204
	v_mul_f32_e32 v141, v207, v141
	s_and_b64 s[36:37], s[36:37], vcc
	v_cndmask_b32_e64 v1, 0, v141, s[36:37]
	v_cmp_gt_u32_e64 s[36:37], s13, v206
	v_mul_f32_e32 v142, v209, v142
	s_and_b64 s[36:37], s[36:37], vcc
	v_cndmask_b32_e64 v2, 0, v142, s[36:37]
	v_cmp_gt_u32_e64 s[36:37], s13, v208
	v_mul_f32_e32 v143, v211, v143
	s_and_b64 s[36:37], s[36:37], vcc
	v_cndmask_b32_e64 v3, 0, v143, s[36:37]
	v_cmp_gt_u32_e64 s[36:37], s13, v210
	v_mul_f32_e32 v144, v213, v144
	s_and_b64 s[36:37], s[36:37], vcc
	v_cndmask_b32_e64 v4, 0, v144, s[36:37]
	v_cmp_gt_u32_e64 s[36:37], s13, v212
	v_mul_f32_e32 v145, v215, v145
	s_and_b64 s[36:37], s[36:37], vcc
	v_cndmask_b32_e64 v5, 0, v145, s[36:37]
	v_cmp_gt_u32_e64 s[36:37], s13, v214
	v_mul_f32_e32 v146, v217, v146
	s_and_b64 s[36:37], s[36:37], vcc
	v_cndmask_b32_e64 v6, 0, v146, s[36:37]
	v_cmp_gt_u32_e64 s[36:37], s13, v216
	v_mul_f32_e32 v147, v220, v147
	s_and_b64 s[36:37], s[36:37], vcc
	v_cndmask_b32_e64 v7, 0, v147, s[36:37]
	v_cmp_gt_u32_e64 s[36:37], s13, v218
	v_mul_f32_e32 v148, v221, v148
	s_and_b64 s[36:37], s[36:37], vcc
	v_cndmask_b32_e64 v8, 0, v148, s[36:37]
	v_cmp_gt_u32_e64 s[36:37], s13, v219
	v_mul_f32_e32 v149, v223, v149
	s_and_b64 s[36:37], s[36:37], vcc
	v_cndmask_b32_e64 v9, 0, v149, s[36:37]
	v_cmp_gt_u32_e64 s[36:37], s13, v222
	v_mul_f32_e32 v150, v225, v150
	s_and_b64 s[36:37], s[36:37], vcc
	v_cndmask_b32_e64 v10, 0, v150, s[36:37]
	v_cmp_gt_u32_e64 s[36:37], s13, v224
	v_mul_f32_e32 v151, v227, v151
	s_and_b64 s[36:37], s[36:37], vcc
	v_cndmask_b32_e64 v11, 0, v151, s[36:37]
	v_cmp_gt_u32_e64 s[36:37], s13, v226
	v_mul_f32_e32 v152, v229, v152
	s_and_b64 s[36:37], s[36:37], vcc
	v_cndmask_b32_e64 v12, 0, v152, s[36:37]
	v_cmp_gt_u32_e64 s[36:37], s13, v228
	v_mul_f32_e32 v153, v231, v153
	s_and_b64 s[36:37], s[36:37], vcc
	v_cndmask_b32_e64 v13, 0, v153, s[36:37]
	v_cmp_gt_u32_e64 s[36:37], s13, v230
	v_mul_f32_e32 v154, v233, v154
	s_and_b64 s[36:37], s[36:37], vcc
	v_cndmask_b32_e64 v14, 0, v154, s[36:37]
	v_cmp_gt_u32_e64 s[36:37], s13, v232
	v_mul_f32_e32 v155, v234, v155
	s_and_b64 vcc, s[36:37], vcc
	v_cndmask_b32_e32 v15, 0, v155, vcc
	s_mul_hi_i32 s4, s8, 0x2e8ba2e9
	s_lshr_b32 s8, s4, 31
	s_ashr_i32 s4, s4, 4
	s_add_i32 s8, s4, s8
	s_mul_i32 s4, s8, 0x3ffff50
	s_add_i32 s9, s30, s7
	s_add_i32 s9, s9, s4
	s_and_b32 s4, s9, 0x3fffffc
	s_or_b32 s4, s4, s5
	s_lshl_b32 s4, s4, 6
	s_bitset1_b32 s4, 7
	ds_read2_b32 v[134:135], v52 offset0:65 offset1:73
	ds_read2_b32 v[136:137], v52 offset1:8
	v_add_u32_e32 v138, s4, v51
	s_lshl_b32 s8, s8, 7
	v_ashrrev_i32_e32 v139, 31, v138
	s_ashr_i32 s9, s8, 31
	v_lshlrev_b64 v[138:139], 12, v[138:139]
	v_lshl_add_u64 v[138:139], s[62:63], 0, v[138:139]
	s_lshl_b64 s[8:9], s[8:9], 1
	v_lshl_add_u64 v[138:139], v[138:139], 0, s[8:9]
	s_waitcnt lgkmcnt(0)
	v_cvt_pk_bf16_f32 v134, v136, v134
	v_lshl_add_u64 v[138:139], v[138:139], 0, v[32:33]
	global_store_dword v[138:139], v134, off
	v_add_u32_e32 v134, s4, v53
	v_cvt_pk_bf16_f32 v136, v137, v135
	v_ashrrev_i32_e32 v135, 31, v134
	v_lshlrev_b64 v[134:135], 12, v[134:135]
	v_lshl_add_u64 v[134:135], s[62:63], 0, v[134:135]
	v_lshl_add_u64 v[134:135], v[134:135], 0, s[8:9]
	v_lshl_add_u64 v[134:135], v[134:135], 0, v[32:33]
	global_store_dword v[134:135], v136, off
	ds_read2_b32 v[134:135], v52 offset0:16 offset1:24
	ds_read2_b32 v[136:137], v52 offset0:81 offset1:89
	v_add_u32_e32 v138, s4, v54
	v_ashrrev_i32_e32 v139, 31, v138
	v_lshlrev_b64 v[138:139], 12, v[138:139]
	v_lshl_add_u64 v[138:139], s[62:63], 0, v[138:139]
	v_lshl_add_u64 v[138:139], v[138:139], 0, s[8:9]
	s_waitcnt lgkmcnt(0)
	v_cvt_pk_bf16_f32 v134, v134, v136
	v_lshl_add_u64 v[138:139], v[138:139], 0, v[32:33]
	global_store_dword v[138:139], v134, off
	v_add_u32_e32 v134, s4, v55
	v_cvt_pk_bf16_f32 v136, v135, v137
	v_ashrrev_i32_e32 v135, 31, v134
	v_lshlrev_b64 v[134:135], 12, v[134:135]
	v_lshl_add_u64 v[134:135], s[62:63], 0, v[134:135]
	v_lshl_add_u64 v[134:135], v[134:135], 0, s[8:9]
	v_lshl_add_u64 v[134:135], v[134:135], 0, v[32:33]
	global_store_dword v[134:135], v136, off
	ds_read2_b32 v[134:135], v52 offset0:32 offset1:40
	ds_read2_b32 v[136:137], v52 offset0:97 offset1:105
	v_add_u32_e32 v138, s4, v56
	v_ashrrev_i32_e32 v139, 31, v138
	v_lshlrev_b64 v[138:139], 12, v[138:139]
	v_lshl_add_u64 v[138:139], s[62:63], 0, v[138:139]
	v_lshl_add_u64 v[138:139], v[138:139], 0, s[8:9]
	s_waitcnt lgkmcnt(0)
; DEVI unsigned pk_bf16(float lo, float hi) { unsigned r; asm("v_cvt_pk_bf16_f32 %0, %1, %2" : "=v"(r) : "v"(lo), "v"(hi)); return r; }
; DEVI void cvt_job(LAS float* tile, const float* src, int srcK, int srcN, bf16_t* dst, int dstLd, int dstRows, int dstCol0, int mode, const float* gk = nullptr) {
;     ...
;         for (int i = 0; i < 16; ++i) { const int k = kap0 + ty + 8 * i - dstCol0; regs[i] = (nok && k >= 0 && k < srcK) ? raw[i] * gs[i] : 0.f; }
;     };
;     auto emit = [&](int t, float (&regs)[16]) {
; #pragma unroll
;         for (int i = 0; i < 16; ++i) tile[(ty + 8 * i) * 65 + tx] = regs[i];
;         __syncthreads();
;         int rho0, kap0, n0; coords(t, rho0, kap0, n0);
;         const int tn = t + 2 * gridDim.x;
;         if (tn < ntot) gl(tn, regs);
; #pragma unroll
;         for (int i = 0; i < 8; ++i) { const int row = ty + 8 * i;
;             const float lo = tile[(2 * tx) * 65 + row], hi = tile[(2 * tx + 1) * 65 + row];
;             *(unsigned*)(dst + (size_t)(rho0 + row) * dstLd + kap0 + 2 * tx) = pk_bf16(lo, hi); }
;         __syncthreads();
	v_cvt_pk_bf16_f32 v134, v134, v136
	v_lshl_add_u64 v[138:139], v[138:139], 0, v[32:33]
	global_store_dword v[138:139], v134, off
	v_add_u32_e32 v134, s4, v57
	v_cvt_pk_bf16_f32 v136, v135, v137
	v_ashrrev_i32_e32 v135, 31, v134
	v_lshlrev_b64 v[134:135], 12, v[134:135]
	v_lshl_add_u64 v[134:135], s[62:63], 0, v[134:135]
	v_lshl_add_u64 v[134:135], v[134:135], 0, s[8:9]
	v_lshl_add_u64 v[134:135], v[134:135], 0, v[32:33]
	global_store_dword v[134:135], v136, off
	ds_read2_b32 v[134:135], v52 offset0:48 offset1:56
	ds_read2_b32 v[136:137], v52 offset0:113 offset1:121
	v_add_u32_e32 v138, s4, v58
	v_ashrrev_i32_e32 v139, 31, v138
	v_lshlrev_b64 v[138:139], 12, v[138:139]
	v_lshl_add_u64 v[138:139], s[62:63], 0, v[138:139]
	v_lshl_add_u64 v[138:139], v[138:139], 0, s[8:9]
	s_waitcnt lgkmcnt(0)
	v_cvt_pk_bf16_f32 v134, v134, v136
	v_lshl_add_u64 v[138:139], v[138:139], 0, v[32:33]
	global_store_dword v[138:139], v134, off
	v_add_u32_e32 v134, s4, v59
	v_cvt_pk_bf16_f32 v136, v135, v137
	v_ashrrev_i32_e32 v135, 31, v134
	v_lshlrev_b64 v[134:135], 12, v[134:135]
	v_lshl_add_u64 v[134:135], s[62:63], 0, v[134:135]
	v_lshl_add_u64 v[134:135], v[134:135], 0, s[8:9]
	v_lshl_add_u64 v[134:135], v[134:135], 0, v[32:33]
	global_store_dword v[134:135], v136, off
	v_cmp_gt_i32_e32 vcc, s12, v63
	v_cmp_gt_u32_e64 s[36:37], s13, v62
	s_waitcnt vmcnt(23)
	v_mul_f32_e32 v16, v65, v16
	s_and_b64 s[36:37], s[36:37], vcc
	v_cndmask_b32_e64 v16, 0, v16, s[36:37]
	v_cmp_gt_u32_e64 s[36:37], s13, v64
	s_waitcnt vmcnt(22)
	v_mul_f32_e32 v17, v67, v17
	s_and_b64 s[36:37], s[36:37], vcc
	v_cndmask_b32_e64 v17, 0, v17, s[36:37]
	v_cmp_gt_u32_e64 s[36:37], s13, v66
	s_waitcnt vmcnt(21)
	v_mul_f32_e32 v18, v69, v18
	s_and_b64 s[36:37], s[36:37], vcc
	v_cndmask_b32_e64 v18, 0, v18, s[36:37]
	v_cmp_gt_u32_e64 s[36:37], s13, v68
	s_waitcnt vmcnt(20)
	v_mul_f32_e32 v19, v71, v19
	s_and_b64 s[36:37], s[36:37], vcc
	v_cndmask_b32_e64 v19, 0, v19, s[36:37]
	v_cmp_gt_u32_e64 s[36:37], s13, v70
	s_waitcnt vmcnt(19)
	v_mul_f32_e32 v20, v73, v20
	s_and_b64 s[36:37], s[36:37], vcc
	v_cndmask_b32_e64 v20, 0, v20, s[36:37]
	v_cmp_gt_u32_e64 s[36:37], s13, v72
	s_waitcnt vmcnt(18)
	v_mul_f32_e32 v21, v75, v21
	s_and_b64 s[36:37], s[36:37], vcc
	v_cndmask_b32_e64 v21, 0, v21, s[36:37]
	v_cmp_gt_u32_e64 s[36:37], s13, v74
	s_waitcnt vmcnt(17)
	v_mul_f32_e32 v22, v77, v22
	s_and_b64 s[36:37], s[36:37], vcc
	v_cndmask_b32_e64 v22, 0, v22, s[36:37]
	v_cmp_gt_u32_e64 s[36:37], s13, v76
	s_waitcnt vmcnt(16)
	v_mul_f32_e32 v23, v80, v23
	s_and_b64 s[36:37], s[36:37], vcc
	v_cndmask_b32_e64 v23, 0, v23, s[36:37]
	v_cmp_gt_u32_e64 s[36:37], s13, v78
	s_waitcnt vmcnt(15)
	v_mul_f32_e32 v24, v81, v24
	s_and_b64 s[36:37], s[36:37], vcc
	v_cndmask_b32_e64 v24, 0, v24, s[36:37]
	v_cmp_gt_u32_e64 s[36:37], s13, v79
	s_waitcnt vmcnt(14)
	v_mul_f32_e32 v25, v83, v25
	s_and_b64 s[36:37], s[36:37], vcc
	v_cndmask_b32_e64 v25, 0, v25, s[36:37]
	v_cmp_gt_u32_e64 s[36:37], s13, v82
	s_waitcnt vmcnt(13)
	v_mul_f32_e32 v26, v85, v26
	s_and_b64 s[36:37], s[36:37], vcc
	v_cndmask_b32_e64 v26, 0, v26, s[36:37]
	v_cmp_gt_u32_e64 s[36:37], s13, v84
	s_waitcnt vmcnt(12)
	v_mul_f32_e32 v27, v87, v27
	s_and_b64 s[36:37], s[36:37], vcc
	v_cndmask_b32_e64 v27, 0, v27, s[36:37]
	v_cmp_gt_u32_e64 s[36:37], s13, v86
	s_waitcnt vmcnt(11)
	v_mul_f32_e32 v28, v89, v28
	s_and_b64 s[36:37], s[36:37], vcc
	v_cndmask_b32_e64 v28, 0, v28, s[36:37]
	v_cmp_gt_u32_e64 s[36:37], s13, v88
	s_waitcnt vmcnt(10)
	v_mul_f32_e32 v29, v91, v29
	s_and_b64 s[36:37], s[36:37], vcc
	v_cndmask_b32_e64 v29, 0, v29, s[36:37]
	v_cmp_gt_u32_e64 s[36:37], s13, v90
	s_waitcnt vmcnt(9)
	v_mul_f32_e32 v30, v93, v30
	s_and_b64 s[36:37], s[36:37], vcc
	v_cndmask_b32_e64 v30, 0, v30, s[36:37]
	v_cmp_gt_u32_e64 s[36:37], s13, v92
	s_waitcnt vmcnt(8)
	v_mul_f32_e32 v31, v94, v31
	s_and_b64 vcc, s[36:37], vcc
	v_cndmask_b32_e32 v31, 0, v31, vcc
	s_barrier

; DEVI unsigned pk_bf16(float lo, float hi) { unsigned r; asm("v_cvt_pk_bf16_f32 %0, %1, %2" : "=v"(r) : "v"(lo), "v"(hi)); return r; }
; DEVI void cvt_job(LAS float* tile, const float* src, int srcK, int srcN, bf16_t* dst, int dstLd, int dstRows, int dstCol0, int mode, const float* gk = nullptr) {
;     ...
;     auto emit = [&](int t, float (&regs)[16]) {
; #pragma unroll
;         for (int i = 0; i < 16; ++i) tile[(ty + 8 * i) * 65 + tx] = regs[i];
;         __syncthreads();
;         int rho0, kap0, n0; coords(t, rho0, kap0, n0);
;         const int tn = t + 2 * gridDim.x;
;         if (tn < ntot) gl(tn, regs);
; #pragma unroll
;         for (int i = 0; i < 8; ++i) { const int row = ty + 8 * i;
;             const float lo = tile[(2 * tx) * 65 + row], hi = tile[(2 * tx + 1) * 65 + row];
;             *(unsigned*)(dst + (size_t)(rho0 + row) * dstLd + kap0 + 2 * tx) = pk_bf16(lo, hi); }
;         __syncthreads();
;     };
.LBB0_368:
.LBB0_369:
	s_mul_hi_i32 s8, s4, 0x2e8ba2e9
	s_lshr_b32 s9, s8, 31
	s_ashr_i32 s8, s8, 4
	s_add_i32 s8, s8, s9
	s_mul_i32 s9, s8, 0x3ffff50
	s_add_i32 s9, s7, s9
	s_and_b32 s9, s9, 0x3fffffc
	s_or_b32 s9, s9, s6
	s_lshl_b32 s15, s9, 6
	s_bitset1_b32 s15, 7
	ds_read2_b32 v[34:35], v52 offset0:65 offset1:73
	ds_read2_b32 v[36:37], v52 offset1:8
	v_add_u32_e32 v38, s15, v51
	s_lshl_b32 s8, s8, 7
	v_ashrrev_i32_e32 v39, 31, v38
	s_ashr_i32 s9, s8, 31
	v_lshlrev_b64 v[38:39], 12, v[38:39]
	v_lshl_add_u64 v[38:39], s[62:63], 0, v[38:39]
	s_lshl_b64 s[8:9], s[8:9], 1
	v_lshl_add_u64 v[38:39], v[38:39], 0, s[8:9]
	s_waitcnt lgkmcnt(0)
	v_cvt_pk_bf16_f32 v34, v36, v34
	v_lshl_add_u64 v[38:39], v[38:39], 0, v[32:33]
	global_store_dword v[38:39], v34, off
	v_add_u32_e32 v34, s15, v53
	v_cvt_pk_bf16_f32 v36, v37, v35
	v_ashrrev_i32_e32 v35, 31, v34
	v_lshlrev_b64 v[34:35], 12, v[34:35]
	v_lshl_add_u64 v[34:35], s[62:63], 0, v[34:35]
	v_lshl_add_u64 v[34:35], v[34:35], 0, s[8:9]
	v_lshl_add_u64 v[34:35], v[34:35], 0, v[32:33]
	global_store_dword v[34:35], v36, off
	ds_read2_b32 v[34:35], v52 offset0:16 offset1:24
	ds_read2_b32 v[36:37], v52 offset0:81 offset1:89
	v_add_u32_e32 v38, s15, v54
	v_ashrrev_i32_e32 v39, 31, v38
	v_lshlrev_b64 v[38:39], 12, v[38:39]
	v_lshl_add_u64 v[38:39], s[62:63], 0, v[38:39]
	v_lshl_add_u64 v[38:39], v[38:39], 0, s[8:9]
	s_waitcnt lgkmcnt(0)
	v_cvt_pk_bf16_f32 v34, v34, v36
	v_lshl_add_u64 v[38:39], v[38:39], 0, v[32:33]
	global_store_dword v[38:39], v34, off
	v_add_u32_e32 v34, s15, v55
	v_cvt_pk_bf16_f32 v36, v35, v37
	v_ashrrev_i32_e32 v35, 31, v34
	v_lshlrev_b64 v[34:35], 12, v[34:35]
	v_lshl_add_u64 v[34:35], s[62:63], 0, v[34:35]
	v_lshl_add_u64 v[34:35], v[34:35], 0, s[8:9]
	v_lshl_add_u64 v[34:35], v[34:35], 0, v[32:33]
	global_store_dword v[34:35], v36, off
	ds_read2_b32 v[34:35], v52 offset0:32 offset1:40
	ds_read2_b32 v[36:37], v52 offset0:97 offset1:105
	v_add_u32_e32 v38, s15, v56
	v_ashrrev_i32_e32 v39, 31, v38
	v_lshlrev_b64 v[38:39], 12, v[38:39]
	v_lshl_add_u64 v[38:39], s[62:63], 0, v[38:39]
	v_lshl_add_u64 v[38:39], v[38:39], 0, s[8:9]
	s_waitcnt lgkmcnt(0)
	v_cvt_pk_bf16_f32 v34, v34, v36
	v_lshl_add_u64 v[38:39], v[38:39], 0, v[32:33]
	global_store_dword v[38:39], v34, off
	v_add_u32_e32 v34, s15, v57
	v_cvt_pk_bf16_f32 v36, v35, v37
	v_ashrrev_i32_e32 v35, 31, v34
	v_lshlrev_b64 v[34:35], 12, v[34:35]
	v_lshl_add_u64 v[34:35], s[62:63], 0, v[34:35]
	v_lshl_add_u64 v[34:35], v[34:35], 0, s[8:9]
	v_lshl_add_u64 v[34:35], v[34:35], 0, v[32:33]
	global_store_dword v[34:35], v36, off
	ds_read2_b32 v[34:35], v52 offset0:48 offset1:56
	ds_read2_b32 v[36:37], v52 offset0:113 offset1:121
	v_add_u32_e32 v38, s15, v58
	v_ashrrev_i32_e32 v39, 31, v38
	v_lshlrev_b64 v[38:39], 12, v[38:39]
	v_lshl_add_u64 v[38:39], s[62:63], 0, v[38:39]
	v_lshl_add_u64 v[38:39], v[38:39], 0, s[8:9]
	s_waitcnt lgkmcnt(0)
	v_cvt_pk_bf16_f32 v34, v34, v36
	v_lshl_add_u64 v[38:39], v[38:39], 0, v[32:33]
	global_store_dword v[38:39], v34, off
	v_add_u32_e32 v34, s15, v59
	v_cvt_pk_bf16_f32 v36, v35, v37
	v_ashrrev_i32_e32 v35, 31, v34
	v_lshlrev_b64 v[34:35], 12, v[34:35]
	v_lshl_add_u64 v[34:35], s[62:63], 0, v[34:35]
	v_lshl_add_u64 v[34:35], v[34:35], 0, s[8:9]
	s_add_i32 s8, s33, s4
	v_lshl_add_u64 v[34:35], v[34:35], 0, v[32:33]
	s_cmpk_gt_i32 s8, 0x57f
	global_store_dword v[34:35], v36, off
	s_barrier
	s_cbranch_scc1 .LBB0_363
	s_add_i32 s4, s31, s4
	s_cmpk_gt_i32 s4, 0x57f
	ds_write_b32 v60, v16
	ds_write_b32 v60, v17 offset:2080
	ds_write_b32 v60, v18 offset:4160
	ds_write_b32 v60, v19 offset:6240
	ds_write_b32 v60, v20 offset:8320
	ds_write_b32 v60, v21 offset:10400
	ds_write_b32 v60, v22 offset:12480
	ds_write_b32 v60, v23 offset:14560
	ds_write_b32 v60, v24 offset:16640
	ds_write_b32 v60, v25 offset:18720
	ds_write_b32 v60, v26 offset:20800
	ds_write_b32 v60, v27 offset:22880
	ds_write_b32 v60, v28 offset:24960
	ds_write_b32 v60, v29 offset:27040
	ds_write_b32 v60, v30 offset:29120
	ds_write_b32 v60, v31 offset:31200
	s_waitcnt lgkmcnt(0)
	s_barrier
; DEVI void cvt_job(LAS float* tile, const float* src, int srcK, int srcN, bf16_t* dst, int dstLd, int dstRows, int dstCol0, int mode, const float* gk = nullptr) {
;     ...
;     auto gl = [&](int t, float (&regs)[16]) {
;         int rho0, kap0, n0; coords(t, rho0, kap0, n0);
;         const int n = n0 + tx, nc = n < srcN ? n : srcN - 1;
;         const bool nok = n < srcN;
;         float raw[16], gs[16];
; #pragma unroll
;         for (int i = 0; i < 16; ++i) { const int k = kap0 + ty + 8 * i - dstCol0; const int kc = k < 0 ? 0 : (k < srcK ? k : srcK - 1);
;             raw[i] = __builtin_nontemporal_load(src + (size_t)kc * srcN + nc); }
;         if (gk) {
; #pragma unroll
;             for (int i = 0; i < 16; ++i) { const int k = kap0 + ty + 8 * i - dstCol0; const int kc = k < 0 ? 0 : (k < srcK ? k : srcK - 1); gs[i] = gk[kc]; }
;         } else {
; #pragma unroll
;             for (int i = 0; i < 16; ++i) gs[i] = 1.0f;
;         }
; #pragma unroll
;         for (int i = 0; i < 16; ++i) { const int k = kap0 + ty + 8 * i - dstCol0; regs[i] = (nok && k >= 0 && k < srcK) ? raw[i] * gs[i] : 0.f; }
;     };
;     auto emit = [&](int t, float (&regs)[16]) {
; #pragma unroll
;         for (int i = 0; i < 16; ++i) tile[(ty + 8 * i) * 65 + tx] = regs[i];
;         __syncthreads();
;         int rho0, kap0, n0; coords(t, rho0, kap0, n0);
;         const int tn = t + 2 * gridDim.x;
;         if (tn < ntot) gl(tn, regs);
;     ...
;     while (t < ntot) {
;         emit(t, regsA);
;         if (t + G < ntot) emit(t + G, regsB);
;         t += 2 * G;
	s_cbranch_scc1 .Lcvt_stub_3
	s_mul_hi_i32 s4, s4, 0x2e8ba2e9
	s_lshr_b32 s9, s4, 31
	s_ashr_i32 s4, s4, 4
	s_add_i32 s4, s4, s9
	s_mul_i32 s9, s4, 0x3ffff50
	s_add_i32 s15, s96, s7
	s_add_i32 s15, s15, s9
	s_and_b32 s9, s15, 0x3fffffc
	s_or_b32 s9, s9, s5
	s_lshl_b32 s9, s9, 6
	s_ashr_i32 s15, s9, 1
	s_and_b32 s15, s15, 0xffffff80
	s_and_b32 s9, s9, 64
	s_or_b32 s9, s9, s15
	v_or_b32_e32 v63, s9, v50
	v_min_i32_e32 v16, 0x15ff, v63
	v_lshl_add_u32 v62, s4, 7, v51
	v_ashrrev_i32_e32 v17, 31, v16
	v_lshl_add_u64 v[94:95], v[16:17], 2, s[0:1]
	v_med3_i32 v16, v62, 0, v61
	v_mad_u64_u32 v[18:19], s[16:17], v16, s11, v[94:95]
	v_add_u32_e32 v64, 8, v62
	global_load_dword v65, v[18:19], off nt
	v_med3_i32 v18, v64, 0, v61
	v_mad_u64_u32 v[20:21], s[16:17], v18, s11, v[94:95]
	v_add_u32_e32 v66, 16, v62
	global_load_dword v67, v[20:21], off nt
	v_med3_i32 v20, v66, 0, v61
	v_mad_u64_u32 v[22:23], s[16:17], v20, s11, v[94:95]
	v_add_u32_e32 v68, 24, v62
	global_load_dword v69, v[22:23], off nt
	v_med3_i32 v22, v68, 0, v61
	v_mad_u64_u32 v[24:25], s[16:17], v22, s11, v[94:95]
	v_add_u32_e32 v70, 32, v62
	global_load_dword v71, v[24:25], off nt
	v_med3_i32 v24, v70, 0, v61
	v_mad_u64_u32 v[26:27], s[16:17], v24, s11, v[94:95]
	v_add_u32_e32 v72, 40, v62
	global_load_dword v73, v[26:27], off nt
	v_med3_i32 v26, v72, 0, v61
	v_mad_u64_u32 v[28:29], s[16:17], v26, s11, v[94:95]
	v_add_u32_e32 v74, 48, v62
	global_load_dword v75, v[28:29], off nt
	v_med3_i32 v28, v74, 0, v61
	v_mad_u64_u32 v[30:31], s[16:17], v28, s11, v[94:95]
	v_add_u32_e32 v76, 56, v62
	global_load_dword v77, v[30:31], off nt
	v_med3_i32 v30, v76, 0, v61
	v_mad_u64_u32 v[34:35], s[16:17], v30, s11, v[94:95]
	v_add_u32_e32 v78, 64, v62
	global_load_dword v80, v[34:35], off nt
	v_med3_i32 v34, v78, 0, v61
	v_mad_u64_u32 v[36:37], s[16:17], v34, s11, v[94:95]
	v_add_u32_e32 v79, 0x48, v62
	global_load_dword v81, v[36:37], off nt
	v_med3_i32 v36, v79, 0, v61
	v_mad_u64_u32 v[38:39], s[16:17], v36, s11, v[94:95]
	v_add_u32_e32 v82, 0x50, v62
	global_load_dword v83, v[38:39], off nt
	v_med3_i32 v38, v82, 0, v61
	v_mad_u64_u32 v[40:41], s[16:17], v38, s11, v[94:95]
	v_add_u32_e32 v84, 0x58, v62
	global_load_dword v85, v[40:41], off nt
	v_med3_i32 v40, v84, 0, v61
	v_mad_u64_u32 v[42:43], s[16:17], v40, s11, v[94:95]
	v_add_u32_e32 v86, 0x60, v62
	global_load_dword v87, v[42:43], off nt
	v_med3_i32 v42, v86, 0, v61
	v_mad_u64_u32 v[44:45], s[16:17], v42, s11, v[94:95]
	v_add_u32_e32 v88, 0x68, v62
	global_load_dword v89, v[44:45], off nt
	v_med3_i32 v44, v88, 0, v61
	v_mad_u64_u32 v[46:47], s[16:17], v44, s11, v[94:95]
	v_add_u32_e32 v90, 0x70, v62
	global_load_dword v91, v[46:47], off nt
	v_med3_i32 v46, v90, 0, v61
	v_mad_u64_u32 v[48:49], s[16:17], v46, s11, v[94:95]
	v_add_u32_e32 v92, 0x78, v62
	global_load_dword v93, v[48:49], off nt
	v_med3_i32 v48, v92, 0, v61
	v_mad_u64_u32 v[94:95], s[16:17], v48, s11, v[94:95]
	global_load_dword v94, v[94:95], off nt
	v_readlane_b32 s16, v240, 48
	v_readlane_b32 s17, v240, 49
	s_and_b64 vcc, exec, s[16:17]
	s_cbranch_vccz .LBB0_360
	v_mov_b32_e32 v31, 1.0
	v_mov_b32_e32 v30, 1.0
	v_mov_b32_e32 v29, 1.0
	v_mov_b32_e32 v28, 1.0
	v_mov_b32_e32 v27, 1.0
	v_mov_b32_e32 v26, 1.0
	v_mov_b32_e32 v25, 1.0
	v_mov_b32_e32 v24, 1.0
	v_mov_b32_e32 v23, 1.0
	v_mov_b32_e32 v22, 1.0
	v_mov_b32_e32 v21, 1.0
	v_mov_b32_e32 v20, 1.0
	v_mov_b32_e32 v19, 1.0
	v_mov_b32_e32 v18, 1.0
	v_mov_b32_e32 v17, 1.0
	v_mov_b32_e32 v16, 1.0
	s_waitcnt vmcnt(24)
	s_branch .LBB0_361

; DEVI unsigned pk_bf16(float lo, float hi) { unsigned r; asm("v_cvt_pk_bf16_f32 %0, %1, %2" : "=v"(r) : "v"(lo), "v"(hi)); return r; }
; DEVI void cvt_job(LAS float* tile, const float* src, int srcK, int srcN, bf16_t* dst, int dstLd, int dstRows, int dstCol0, int mode, const float* gk = nullptr) {
;     ...
;         for (int i = 0; i < 16; ++i) { const int k = kap0 + ty + 8 * i - dstCol0; regs[i] = (nok && k >= 0 && k < srcK) ? raw[i] * gs[i] : 0.f; }
;     };
;     auto emit = [&](int t, float (&regs)[16]) {
; #pragma unroll
;         for (int i = 0; i < 16; ++i) tile[(ty + 8 * i) * 65 + tx] = regs[i];
;         __syncthreads();
;         int rho0, kap0, n0; coords(t, rho0, kap0, n0);
;         const int tn = t + 2 * gridDim.x;
;         if (tn < ntot) gl(tn, regs);
; #pragma unroll
;         for (int i = 0; i < 8; ++i) { const int row = ty + 8 * i;
;             const float lo = tile[(2 * tx) * 65 + row], hi = tile[(2 * tx + 1) * 65 + row];
;             *(unsigned*)(dst + (size_t)(rho0 + row) * dstLd + kap0 + 2 * tx) = pk_bf16(lo, hi); }
.LBB0_1411:
	v_cmp_gt_i32_e32 vcc, s7, v154
	v_cmp_gt_u32_e64 s[36:37], s10, v155
	s_and_b64 s[36:37], s[36:37], vcc
	v_cndmask_b32_e64 v0, 0, v163, s[36:37]
	v_cmp_gt_u32_e64 s[36:37], s10, v156
	s_and_b64 s[36:37], s[36:37], vcc
	v_cndmask_b32_e64 v1, 0, v164, s[36:37]
	v_cmp_gt_u32_e64 s[36:37], s10, v157
	s_and_b64 s[36:37], s[36:37], vcc
	v_cndmask_b32_e64 v2, 0, v165, s[36:37]
	v_cmp_gt_u32_e64 s[36:37], s10, v158
	s_and_b64 s[36:37], s[36:37], vcc
	v_cndmask_b32_e64 v3, 0, v166, s[36:37]
	v_cmp_gt_u32_e64 s[36:37], s10, v159
	s_and_b64 s[36:37], s[36:37], vcc
	v_cndmask_b32_e64 v4, 0, v167, s[36:37]
	v_cmp_gt_u32_e64 s[36:37], s10, v160
	s_and_b64 s[36:37], s[36:37], vcc
	v_cndmask_b32_e64 v5, 0, v122, s[36:37]
	v_cmp_gt_u32_e64 s[36:37], s10, v161
	s_and_b64 s[36:37], s[36:37], vcc
	v_cndmask_b32_e64 v6, 0, v123, s[36:37]
	v_cmp_gt_u32_e64 s[36:37], s10, v162
	s_and_b64 s[36:37], s[36:37], vcc
	v_cndmask_b32_e64 v7, 0, v124, s[36:37]
	v_cmp_gt_u32_e64 s[36:37], s10, v125
	s_and_b64 s[36:37], s[36:37], vcc
	v_cndmask_b32_e64 v8, 0, v170, s[36:37]
	v_cmp_gt_u32_e64 s[36:37], s10, v152
	s_and_b64 s[36:37], s[36:37], vcc
	v_cndmask_b32_e64 v9, 0, v171, s[36:37]
	v_cmp_gt_u32_e64 s[36:37], s10, v153
	s_and_b64 s[36:37], s[36:37], vcc
	v_cndmask_b32_e64 v10, 0, v172, s[36:37]
	v_cmp_gt_u32_e64 s[36:37], s10, v168
	s_and_b64 s[36:37], s[36:37], vcc
	v_cndmask_b32_e64 v11, 0, v173, s[36:37]
	v_cmp_gt_u32_e64 s[36:37], s10, v169
	s_and_b64 s[36:37], s[36:37], vcc
	v_cndmask_b32_e64 v12, 0, v174, s[36:37]
	v_cmp_gt_u32_e64 s[36:37], s10, v175
	s_and_b64 s[36:37], s[36:37], vcc
	v_cndmask_b32_e64 v13, 0, v177, s[36:37]
	v_cmp_gt_u32_e64 s[36:37], s10, v176
	s_and_b64 s[36:37], s[36:37], vcc
	v_cndmask_b32_e64 v14, 0, v178, s[36:37]
	v_cmp_gt_u32_e64 s[36:37], s10, v179
	s_and_b64 vcc, s[36:37], vcc
	v_cndmask_b32_e32 v15, 0, v180, vcc
	ds_read2_b32 v[142:143], v35 offset0:65 offset1:73
	ds_read2_b32 v[144:145], v35 offset1:8
	s_ashr_i32 s4, s8, 31
	s_lshr_b32 s4, s4, 27
	s_add_i32 s8, s8, s4
	s_ashr_i32 s4, s8, 5
	v_readlane_b32 s14, v238, 59
	s_lshl_b32 s8, s4, 7
	s_waitcnt lgkmcnt(0)
	v_cvt_pk_bf16_f32 v142, v144, v142
	v_add_u32_e32 v144, s5, v37
	s_lshl_b32 s4, s4, 11
	v_readlane_b32 s15, v238, 60
	s_ashr_i32 s9, s8, 31
	v_subrev_u32_e32 v150, s4, v144
	v_mov_b64_e32 v[146:147], s[14:15]
	v_mad_i64_i32 v[148:149], s[14:15], v150, s11, v[146:147]
	s_lshl_b64 s[8:9], s[8:9], 1
	v_lshl_add_u64 v[148:149], v[148:149], 0, s[8:9]
	v_lshl_add_u64 v[148:149], v[148:149], 0, v[32:33]
	global_store_dword v[148:149], v142, off
	v_add_u32_e32 v142, 8, v150
	v_cvt_pk_bf16_f32 v144, v145, v143
	v_mad_i64_i32 v[142:143], s[14:15], v142, s11, v[146:147]
	v_lshl_add_u64 v[142:143], v[142:143], 0, s[8:9]
	v_lshl_add_u64 v[142:143], v[142:143], 0, v[32:33]
	global_store_dword v[142:143], v144, off
	ds_read2_b32 v[142:143], v35 offset0:16 offset1:24
	ds_read2_b32 v[144:145], v35 offset0:81 offset1:89
	s_waitcnt lgkmcnt(0)
	v_cvt_pk_bf16_f32 v142, v142, v144
	v_add_u32_e32 v144, 16, v150
	v_mad_i64_i32 v[148:149], s[14:15], v144, s11, v[146:147]
	v_lshl_add_u64 v[148:149], v[148:149], 0, s[8:9]
	v_lshl_add_u64 v[148:149], v[148:149], 0, v[32:33]
	global_store_dword v[148:149], v142, off
	v_add_u32_e32 v142, 24, v150
	v_cvt_pk_bf16_f32 v144, v143, v145
	v_mad_i64_i32 v[142:143], s[14:15], v142, s11, v[146:147]
	v_lshl_add_u64 v[142:143], v[142:143], 0, s[8:9]
	v_lshl_add_u64 v[142:143], v[142:143], 0, v[32:33]
	global_store_dword v[142:143], v144, off
	ds_read2_b32 v[142:143], v35 offset0:32 offset1:40
	ds_read2_b32 v[144:145], v35 offset0:97 offset1:105
	s_waitcnt lgkmcnt(0)
	v_cvt_pk_bf16_f32 v142, v142, v144
	v_add_u32_e32 v144, 32, v150
	v_mad_i64_i32 v[148:149], s[14:15], v144, s11, v[146:147]
	v_lshl_add_u64 v[148:149], v[148:149], 0, s[8:9]
	v_lshl_add_u64 v[148:149], v[148:149], 0, v[32:33]
	global_store_dword v[148:149], v142, off
	v_add_u32_e32 v142, 40, v150
	v_cvt_pk_bf16_f32 v144, v143, v145
	v_mad_i64_i32 v[142:143], s[14:15], v142, s11, v[146:147]
	v_lshl_add_u64 v[142:143], v[142:143], 0, s[8:9]
	v_lshl_add_u64 v[142:143], v[142:143], 0, v[32:33]
	global_store_dword v[142:143], v144, off
	ds_read2_b32 v[142:143], v35 offset0:48 offset1:56
	ds_read2_b32 v[144:145], v35 offset0:113 offset1:121
	s_waitcnt lgkmcnt(0)
	v_cvt_pk_bf16_f32 v142, v142, v144
	v_add_u32_e32 v144, 48, v150
	v_mad_i64_i32 v[148:149], s[14:15], v144, s11, v[146:147]
	v_lshl_add_u64 v[148:149], v[148:149], 0, s[8:9]
	v_lshl_add_u64 v[148:149], v[148:149], 0, v[32:33]
	global_store_dword v[148:149], v142, off
	v_add_u32_e32 v142, 56, v150
	v_cvt_pk_bf16_f32 v144, v143, v145
	v_mad_i64_i32 v[142:143], s[14:15], v142, s11, v[146:147]
	v_lshl_add_u64 v[142:143], v[142:143], 0, s[8:9]
	v_lshl_add_u64 v[142:143], v[142:143], 0, v[32:33]
	global_store_dword v[142:143], v144, off
	v_cmp_gt_i32_e32 vcc, s7, v44
	v_cmp_gt_u32_e64 s[36:37], s10, v45
	s_and_b64 s[36:37], s[36:37], vcc
	s_waitcnt vmcnt(23)
	v_cndmask_b32_e64 v16, 0, v53, s[36:37]
	v_cmp_gt_u32_e64 s[36:37], s10, v46
	s_and_b64 s[36:37], s[36:37], vcc
	s_waitcnt vmcnt(22)
	v_cndmask_b32_e64 v17, 0, v54, s[36:37]
	v_cmp_gt_u32_e64 s[36:37], s10, v47
	s_and_b64 s[36:37], s[36:37], vcc
	s_waitcnt vmcnt(21)
	v_cndmask_b32_e64 v18, 0, v55, s[36:37]
	v_cmp_gt_u32_e64 s[36:37], s10, v48
	s_and_b64 s[36:37], s[36:37], vcc
	s_waitcnt vmcnt(20)
	v_cndmask_b32_e64 v19, 0, v56, s[36:37]
	v_cmp_gt_u32_e64 s[36:37], s10, v49
	s_and_b64 s[36:37], s[36:37], vcc
	s_waitcnt vmcnt(19)
	v_cndmask_b32_e64 v20, 0, v57, s[36:37]
	v_cmp_gt_u32_e64 s[36:37], s10, v50
	s_and_b64 s[36:37], s[36:37], vcc
	s_waitcnt vmcnt(18)
	v_cndmask_b32_e64 v21, 0, v28, s[36:37]
	v_cmp_gt_u32_e64 s[36:37], s10, v51
	s_and_b64 s[36:37], s[36:37], vcc
	s_waitcnt vmcnt(17)
	v_cndmask_b32_e64 v22, 0, v29, s[36:37]
	v_cmp_gt_u32_e64 s[36:37], s10, v52
	s_and_b64 s[36:37], s[36:37], vcc
	s_waitcnt vmcnt(16)
	v_cndmask_b32_e64 v23, 0, v30, s[36:37]
	v_cmp_gt_u32_e64 s[36:37], s10, v31
	s_and_b64 s[36:37], s[36:37], vcc
	s_waitcnt vmcnt(15)
	v_cndmask_b32_e64 v24, 0, v60, s[36:37]
	v_cmp_gt_u32_e64 s[36:37], s10, v42
	s_and_b64 s[36:37], s[36:37], vcc
	s_waitcnt vmcnt(14)
	v_cndmask_b32_e64 v25, 0, v61, s[36:37]
	v_cmp_gt_u32_e64 s[36:37], s10, v43
	s_and_b64 s[36:37], s[36:37], vcc
	s_waitcnt vmcnt(13)
	v_cndmask_b32_e64 v26, 0, v62, s[36:37]
	v_cmp_gt_u32_e64 s[36:37], s10, v58
	s_and_b64 s[36:37], s[36:37], vcc
	s_waitcnt vmcnt(12)
	v_cndmask_b32_e64 v27, 0, v63, s[36:37]
	v_cmp_gt_u32_e64 s[36:37], s10, v59
	s_and_b64 s[36:37], s[36:37], vcc
	s_waitcnt vmcnt(11)
	v_cndmask_b32_e64 v28, 0, v64, s[36:37]
	v_cmp_gt_u32_e64 s[36:37], s10, v65
	s_and_b64 s[36:37], s[36:37], vcc
	s_waitcnt vmcnt(10)
	v_cndmask_b32_e64 v29, 0, v67, s[36:37]
	v_cmp_gt_u32_e64 s[36:37], s10, v66
	s_and_b64 s[36:37], s[36:37], vcc
	s_waitcnt vmcnt(9)
	v_cndmask_b32_e64 v30, 0, v68, s[36:37]
	v_cmp_gt_u32_e64 s[36:37], s10, v69
	s_and_b64 vcc, s[36:37], vcc
	s_waitcnt vmcnt(8)
	v_cndmask_b32_e32 v31, 0, v70, vcc
	s_barrier

; DEVI void cvt_job(LAS float* tile, const float* src, int srcK, int srcN, bf16_t* dst, int dstLd, int dstRows, int dstCol0, int mode, const float* gk = nullptr) {
;     ...
;         for (int i = 0; i < 16; ++i) { const int k = kap0 + ty + 8 * i - dstCol0; const int kc = k < 0 ? 0 : (k < srcK ? k : srcK - 1);
;             raw[i] = __builtin_nontemporal_load(src + (size_t)kc * srcN + nc); }
;         if (gk) {
; #pragma unroll
;             for (int i = 0; i < 16; ++i) { const int k = kap0 + ty + 8 * i - dstCol0; const int kc = k < 0 ? 0 : (k < srcK ? k : srcK - 1); gs[i] = gk[kc]; }
;         } else {
; #pragma unroll
;             for (int i = 0; i < 16; ++i) gs[i] = 1.0f;
;         }
; #pragma unroll
;         for (int i = 0; i < 16; ++i) { const int k = kap0 + ty + 8 * i - dstCol0; regs[i] = (nok && k >= 0 && k < srcK) ? raw[i] * gs[i] : 0.f; }
;     };
;     auto emit = [&](int t, float (&regs)[16]) {
; #pragma unroll
;         for (int i = 0; i < 16; ++i) tile[(ty + 8 * i) * 65 + tx] = regs[i];
;         __syncthreads();
;         int rho0, kap0, n0; coords(t, rho0, kap0, n0);
;         const int tn = t + 2 * gridDim.x;
;         if (tn < ntot) gl(tn, regs);
.LBB0_1413:
	s_add_i32 s12, s4, s30
	s_cmpk_gt_i32 s12, 0x57f
	s_cselect_b64 s[2:3], -1, 0
	s_and_b64 vcc, exec, s[2:3]
	ds_write_b32 v40, v0
	ds_write_b32 v40, v1 offset:2080
	ds_write_b32 v40, v2 offset:4160
	ds_write_b32 v40, v3 offset:6240
	ds_write_b32 v40, v4 offset:8320
	ds_write_b32 v40, v5 offset:10400
	ds_write_b32 v40, v6 offset:12480
	ds_write_b32 v40, v7 offset:14560
	ds_write_b32 v40, v8 offset:16640
	ds_write_b32 v40, v9 offset:18720
	ds_write_b32 v40, v10 offset:20800
	ds_write_b32 v40, v11 offset:22880
	ds_write_b32 v40, v12 offset:24960
	ds_write_b32 v40, v13 offset:27040
	ds_write_b32 v40, v14 offset:29120
	ds_write_b32 v40, v15 offset:31200
	s_waitcnt lgkmcnt(0)
	s_barrier
	s_cbranch_vccnz .LBB0_1415
	s_ashr_i32 s8, s12, 31
	s_lshr_b32 s8, s8, 27
	s_add_i32 s8, s12, s8
	s_ashr_i32 s8, s8, 5
	v_add_u32_e32 v110, s5, v39
	s_lshl_b32 s9, s8, 11
	v_subrev_u32_e32 v154, s9, v110
	v_lshl_add_u32 v155, s8, 7, v34
	v_min_i32_e32 v110, 0x7ff, v154
	v_add_u32_e32 v160, 40, v155
	v_add_u32_e32 v161, 48, v155
	v_ashrrev_i32_e32 v111, 31, v110
	v_med3_i32 v112, v155, 0, v41
	v_add_u32_e32 v156, 8, v155
	v_add_u32_e32 v157, 16, v155
	v_add_u32_e32 v158, 24, v155
	v_add_u32_e32 v159, 32, v155
	v_med3_i32 v122, v160, 0, v41
	v_med3_i32 v124, v161, 0, v41
	v_add_u32_e32 v162, 56, v155
	v_lshl_add_u64 v[110:111], v[110:111], 2, s[0:1]
	v_lshlrev_b32_e32 v112, 13, v112
	v_mov_b32_e32 v113, v33
	v_med3_i32 v114, v156, 0, v41
	v_med3_i32 v116, v157, 0, v41
	v_med3_i32 v118, v158, 0, v41
	v_med3_i32 v120, v159, 0, v41
	v_lshlrev_b32_e32 v122, 13, v122
	v_mov_b32_e32 v123, v33
	v_lshlrev_b32_e32 v124, 13, v124
	v_mov_b32_e32 v125, v33
	v_med3_i32 v152, v162, 0, v41
	v_lshl_add_u64 v[112:113], v[110:111], 0, v[112:113]
	v_lshlrev_b32_e32 v114, 13, v114
	v_mov_b32_e32 v115, v33
	v_lshlrev_b32_e32 v116, 13, v116
	v_mov_b32_e32 v117, v33
	v_lshlrev_b32_e32 v118, 13, v118
	v_mov_b32_e32 v119, v33
	v_lshlrev_b32_e32 v120, 13, v120
	v_mov_b32_e32 v121, v33
	v_lshl_add_u64 v[122:123], v[110:111], 0, v[122:123]
	v_lshl_add_u64 v[124:125], v[110:111], 0, v[124:125]
	v_lshlrev_b32_e32 v152, 13, v152
	v_mov_b32_e32 v153, v33
	v_lshl_add_u64 v[114:115], v[110:111], 0, v[114:115]
	v_lshl_add_u64 v[116:117], v[110:111], 0, v[116:117]
	v_lshl_add_u64 v[118:119], v[110:111], 0, v[118:119]
	v_lshl_add_u64 v[120:121], v[110:111], 0, v[120:121]
	v_lshl_add_u64 v[152:153], v[110:111], 0, v[152:153]
	global_load_dword v163, v[112:113], off nt
	global_load_dword v164, v[114:115], off nt
	global_load_dword v165, v[116:117], off nt
	global_load_dword v166, v[118:119], off nt
	global_load_dword v167, v[120:121], off nt
	s_nop 0
	global_load_dword v122, v[122:123], off nt
	s_nop 0
	global_load_dword v123, v[124:125], off nt
	s_nop 0
	global_load_dword v124, v[152:153], off nt
	v_add_u32_e32 v125, 64, v155
	v_med3_i32 v112, v125, 0, v41
	v_add_u32_e32 v152, 0x48, v155
	v_add_u32_e32 v153, 0x50, v155
	v_add_u32_e32 v168, 0x58, v155
	v_add_u32_e32 v169, 0x60, v155
	v_lshlrev_b32_e32 v112, 13, v112
	v_mov_b32_e32 v113, v33
	v_med3_i32 v114, v152, 0, v41
	v_med3_i32 v116, v153, 0, v41
	v_med3_i32 v118, v168, 0, v41
	v_med3_i32 v120, v169, 0, v41
	v_lshl_add_u64 v[112:113], v[110:111], 0, v[112:113]
	v_lshlrev_b32_e32 v114, 13, v114
	v_mov_b32_e32 v115, v33
	v_lshlrev_b32_e32 v116, 13, v116
	v_mov_b32_e32 v117, v33
	v_lshlrev_b32_e32 v118, 13, v118
	v_mov_b32_e32 v119, v33
	v_lshlrev_b32_e32 v120, 13, v120
	v_mov_b32_e32 v121, v33
	v_lshl_add_u64 v[114:115], v[110:111], 0, v[114:115]
	v_lshl_add_u64 v[116:117], v[110:111], 0, v[116:117]
	v_lshl_add_u64 v[118:119], v[110:111], 0, v[118:119]
	v_lshl_add_u64 v[120:121], v[110:111], 0, v[120:121]
	global_load_dword v170, v[112:113], off nt
	global_load_dword v171, v[114:115], off nt
	global_load_dword v172, v[116:117], off nt
	global_load_dword v173, v[118:119], off nt
	global_load_dword v174, v[120:121], off nt
	v_add_u32_e32 v175, 0x68, v155
	v_med3_i32 v112, v175, 0, v41
	v_add_u32_e32 v176, 0x70, v155
	v_lshlrev_b32_e32 v112, 13, v112
	v_mov_b32_e32 v113, v33
	v_med3_i32 v114, v176, 0, v41
	v_lshl_add_u64 v[112:113], v[110:111], 0, v[112:113]
	v_lshlrev_b32_e32 v114, 13, v114
	v_mov_b32_e32 v115, v33
	v_add_u32_e32 v179, 0x78, v155
	v_lshl_add_u64 v[114:115], v[110:111], 0, v[114:115]
	global_load_dword v177, v[112:113], off nt
	global_load_dword v178, v[114:115], off nt
	v_med3_i32 v112, v179, 0, v41
	v_lshlrev_b32_e32 v112, 13, v112
	v_mov_b32_e32 v113, v33
	v_lshl_add_u64 v[110:111], v[110:111], 0, v[112:113]
	global_load_dword v180, v[110:111], off nt
; DEVI unsigned pk_bf16(float lo, float hi) { unsigned r; asm("v_cvt_pk_bf16_f32 %0, %1, %2" : "=v"(r) : "v"(lo), "v"(hi)); return r; }
; DEVI void cvt_job(LAS float* tile, const float* src, int srcK, int srcN, bf16_t* dst, int dstLd, int dstRows, int dstCol0, int mode, const float* gk = nullptr) {
;     ...
;     auto emit = [&](int t, float (&regs)[16]) {
; #pragma unroll
;         for (int i = 0; i < 16; ++i) tile[(ty + 8 * i) * 65 + tx] = regs[i];
;         __syncthreads();
;         int rho0, kap0, n0; coords(t, rho0, kap0, n0);
;         const int tn = t + 2 * gridDim.x;
;         if (tn < ntot) gl(tn, regs);
; #pragma unroll
;         for (int i = 0; i < 8; ++i) { const int row = ty + 8 * i;
;             const float lo = tile[(2 * tx) * 65 + row], hi = tile[(2 * tx + 1) * 65 + row];
;             *(unsigned*)(dst + (size_t)(rho0 + row) * dstLd + kap0 + 2 * tx) = pk_bf16(lo, hi); }
;         __syncthreads();
;     };
.LBB0_1415:
	ds_read2_b32 v[42:43], v35 offset0:65 offset1:73
	ds_read2_b32 v[44:45], v35 offset1:8
	s_ashr_i32 s8, s4, 31
	s_lshr_b32 s8, s8, 27
	s_add_i32 s8, s4, s8
	s_ashr_i32 s13, s8, 5
	v_readlane_b32 s14, v238, 59
	s_lshl_b32 s8, s13, 7
	s_waitcnt lgkmcnt(0)
	v_cvt_pk_bf16_f32 v42, v44, v42
	v_add_u32_e32 v44, s5, v38
	s_lshl_b32 s13, s13, 11
	v_readlane_b32 s15, v238, 60
	s_ashr_i32 s9, s8, 31
	v_subrev_u32_e32 v50, s13, v44
	v_mov_b64_e32 v[46:47], s[14:15]
	v_mad_i64_i32 v[48:49], s[14:15], v50, s11, v[46:47]
	s_lshl_b64 s[8:9], s[8:9], 1
	v_lshl_add_u64 v[48:49], v[48:49], 0, s[8:9]
	v_lshl_add_u64 v[48:49], v[48:49], 0, v[32:33]
	global_store_dword v[48:49], v42, off
	v_add_u32_e32 v42, 8, v50
	v_cvt_pk_bf16_f32 v44, v45, v43
	v_mad_i64_i32 v[42:43], s[14:15], v42, s11, v[46:47]
	v_lshl_add_u64 v[42:43], v[42:43], 0, s[8:9]
	v_lshl_add_u64 v[42:43], v[42:43], 0, v[32:33]
	global_store_dword v[42:43], v44, off
	ds_read2_b32 v[42:43], v35 offset0:16 offset1:24
	ds_read2_b32 v[44:45], v35 offset0:81 offset1:89
	s_waitcnt lgkmcnt(0)
	v_cvt_pk_bf16_f32 v42, v42, v44
	v_add_u32_e32 v44, 16, v50
	v_mad_i64_i32 v[48:49], s[14:15], v44, s11, v[46:47]
	v_lshl_add_u64 v[48:49], v[48:49], 0, s[8:9]
	v_lshl_add_u64 v[48:49], v[48:49], 0, v[32:33]
	global_store_dword v[48:49], v42, off
	v_add_u32_e32 v42, 24, v50
	v_cvt_pk_bf16_f32 v44, v43, v45
	v_mad_i64_i32 v[42:43], s[14:15], v42, s11, v[46:47]
	v_lshl_add_u64 v[42:43], v[42:43], 0, s[8:9]
	v_lshl_add_u64 v[42:43], v[42:43], 0, v[32:33]
	global_store_dword v[42:43], v44, off
	ds_read2_b32 v[42:43], v35 offset0:32 offset1:40
	ds_read2_b32 v[44:45], v35 offset0:97 offset1:105
	s_waitcnt lgkmcnt(0)
	v_cvt_pk_bf16_f32 v42, v42, v44
	v_add_u32_e32 v44, 32, v50
	v_mad_i64_i32 v[48:49], s[14:15], v44, s11, v[46:47]
	v_lshl_add_u64 v[48:49], v[48:49], 0, s[8:9]
	v_lshl_add_u64 v[48:49], v[48:49], 0, v[32:33]
	global_store_dword v[48:49], v42, off
	v_add_u32_e32 v42, 40, v50
	v_cvt_pk_bf16_f32 v44, v43, v45
	v_mad_i64_i32 v[42:43], s[14:15], v42, s11, v[46:47]
	v_lshl_add_u64 v[42:43], v[42:43], 0, s[8:9]
	v_lshl_add_u64 v[42:43], v[42:43], 0, v[32:33]
	global_store_dword v[42:43], v44, off
	ds_read2_b32 v[42:43], v35 offset0:48 offset1:56
	ds_read2_b32 v[44:45], v35 offset0:113 offset1:121
	s_waitcnt lgkmcnt(0)
	v_cvt_pk_bf16_f32 v42, v42, v44
	v_add_u32_e32 v44, 48, v50
	v_mad_i64_i32 v[48:49], s[14:15], v44, s11, v[46:47]
	v_lshl_add_u64 v[48:49], v[48:49], 0, s[8:9]
	v_lshl_add_u64 v[48:49], v[48:49], 0, v[32:33]
	global_store_dword v[48:49], v42, off
	v_add_u32_e32 v42, 56, v50
	v_cvt_pk_bf16_f32 v44, v43, v45
	v_mad_i64_i32 v[42:43], s[14:15], v42, s11, v[46:47]
	v_lshl_add_u64 v[42:43], v[42:43], 0, s[8:9]
	s_add_i32 s8, s33, s4
	v_lshl_add_u64 v[42:43], v[42:43], 0, v[32:33]
	s_cmpk_gt_i32 s8, 0x57f
	global_store_dword v[42:43], v44, off
	s_barrier
	s_cbranch_scc1 .LBB0_1412
	s_add_i32 s4, s18, s4
	s_cmpk_gt_i32 s4, 0x57f
	ds_write_b32 v40, v16
	ds_write_b32 v40, v17 offset:2080
	ds_write_b32 v40, v18 offset:4160
	ds_write_b32 v40, v19 offset:6240
	ds_write_b32 v40, v20 offset:8320
	ds_write_b32 v40, v21 offset:10400
	ds_write_b32 v40, v22 offset:12480
	ds_write_b32 v40, v23 offset:14560
	ds_write_b32 v40, v24 offset:16640
	ds_write_b32 v40, v25 offset:18720
	ds_write_b32 v40, v26 offset:20800
	ds_write_b32 v40, v27 offset:22880
	ds_write_b32 v40, v28 offset:24960
	ds_write_b32 v40, v29 offset:27040
	ds_write_b32 v40, v30 offset:29120
	ds_write_b32 v40, v31 offset:31200
	s_waitcnt lgkmcnt(0)
	s_barrier
	s_cbranch_scc1 .Lcvt_stub_4
; DEVI int obid() { int b = __builtin_amdgcn_workgroup_id_x(); asm volatile("" : "+s"(b)); return b; }
; DEVI unsigned pk_bf16(float lo, float hi) { unsigned r; asm("v_cvt_pk_bf16_f32 %0, %1, %2" : "=v"(r) : "v"(lo), "v"(hi)); return r; }
; DEVI void cvt_job(LAS float* tile, const float* src, int srcK, int srcN, bf16_t* dst, int dstLd, int dstRows, int dstCol0, int mode, const float* gk = nullptr) {
;     ...
;     auto gl = [&](int t, float (&regs)[16]) {
;         int rho0, kap0, n0; coords(t, rho0, kap0, n0);
;         const int n = n0 + tx, nc = n < srcN ? n : srcN - 1;
;         const bool nok = n < srcN;
;         float raw[16], gs[16];
; #pragma unroll
;         for (int i = 0; i < 16; ++i) { const int k = kap0 + ty + 8 * i - dstCol0; const int kc = k < 0 ? 0 : (k < srcK ? k : srcK - 1);
;             raw[i] = __builtin_nontemporal_load(src + (size_t)kc * srcN + nc); }
;         if (gk) {
; #pragma unroll
;             for (int i = 0; i < 16; ++i) { const int k = kap0 + ty + 8 * i - dstCol0; const int kc = k < 0 ? 0 : (k < srcK ? k : srcK - 1); gs[i] = gk[kc]; }
;         } else {
; #pragma unroll
;             for (int i = 0; i < 16; ++i) gs[i] = 1.0f;
;         }
; #pragma unroll
;         for (int i = 0; i < 16; ++i) { const int k = kap0 + ty + 8 * i - dstCol0; regs[i] = (nok && k >= 0 && k < srcK) ? raw[i] * gs[i] : 0.f; }
;     };
;     auto emit = [&](int t, float (&regs)[16]) {
; #pragma unroll
;         for (int i = 0; i < 16; ++i) tile[(ty + 8 * i) * 65 + tx] = regs[i];
;         __syncthreads();
;         int rho0, kap0, n0; coords(t, rho0, kap0, n0);
;         const int tn = t + 2 * gridDim.x;
;         if (tn < ntot) gl(tn, regs);
; #pragma unroll
;         for (int i = 0; i < 8; ++i) { const int row = ty + 8 * i;
;             const float lo = tile[(2 * tx) * 65 + row], hi = tile[(2 * tx + 1) * 65 + row];
;             *(unsigned*)(dst + (size_t)(rho0 + row) * dstLd + kap0 + 2 * tx) = pk_bf16(lo, hi); }
;         __syncthreads();
;     };
;     const int G = gridDim.x;
;     int t = obid();
;     if (t < ntot) gl(t, regsA);
;     if (t + G < ntot) gl(t + G, regsB);
;     while (t < ntot) {
;         emit(t, regsA);
;         if (t + G < ntot) emit(t + G, regsB);
;         t += 2 * G;
	s_ashr_i32 s9, s4, 31
	s_lshr_b32 s9, s9, 27
	s_add_i32 s4, s4, s9
	s_ashr_i32 s4, s4, 5
	v_add_u32_e32 v16, s5, v36
	s_lshl_b32 s9, s4, 11
	v_subrev_u32_e32 v44, s9, v16
	v_lshl_add_u32 v45, s4, 7, v34
	v_min_i32_e32 v16, 0x7ff, v44
	v_add_u32_e32 v50, 40, v45
	v_add_u32_e32 v51, 48, v45
	v_ashrrev_i32_e32 v17, 31, v16
	v_med3_i32 v18, v45, 0, v41
	v_add_u32_e32 v46, 8, v45
	v_add_u32_e32 v47, 16, v45
	v_add_u32_e32 v48, 24, v45
	v_add_u32_e32 v49, 32, v45
	v_med3_i32 v28, v50, 0, v41
	v_med3_i32 v30, v51, 0, v41
	v_add_u32_e32 v52, 56, v45
	v_lshl_add_u64 v[16:17], v[16:17], 2, s[0:1]
	v_lshlrev_b32_e32 v18, 13, v18
	v_mov_b32_e32 v19, v33
	v_med3_i32 v20, v46, 0, v41
	v_med3_i32 v22, v47, 0, v41
	v_med3_i32 v24, v48, 0, v41
	v_med3_i32 v26, v49, 0, v41
	v_lshlrev_b32_e32 v28, 13, v28
	v_mov_b32_e32 v29, v33
	v_lshlrev_b32_e32 v30, 13, v30
	v_mov_b32_e32 v31, v33
	v_med3_i32 v42, v52, 0, v41
	v_lshl_add_u64 v[18:19], v[16:17], 0, v[18:19]
	v_lshlrev_b32_e32 v20, 13, v20
	v_mov_b32_e32 v21, v33
	v_lshlrev_b32_e32 v22, 13, v22
	v_mov_b32_e32 v23, v33
	v_lshlrev_b32_e32 v24, 13, v24
	v_mov_b32_e32 v25, v33
	v_lshlrev_b32_e32 v26, 13, v26
	v_mov_b32_e32 v27, v33
	v_lshl_add_u64 v[28:29], v[16:17], 0, v[28:29]
	v_lshl_add_u64 v[30:31], v[16:17], 0, v[30:31]
	v_lshlrev_b32_e32 v42, 13, v42
	v_mov_b32_e32 v43, v33
	v_lshl_add_u64 v[20:21], v[16:17], 0, v[20:21]
	v_lshl_add_u64 v[22:23], v[16:17], 0, v[22:23]
	v_lshl_add_u64 v[24:25], v[16:17], 0, v[24:25]
	v_lshl_add_u64 v[26:27], v[16:17], 0, v[26:27]
	v_lshl_add_u64 v[42:43], v[16:17], 0, v[42:43]
	global_load_dword v53, v[18:19], off nt
	global_load_dword v54, v[20:21], off nt
	global_load_dword v55, v[22:23], off nt
	global_load_dword v56, v[24:25], off nt
	global_load_dword v57, v[26:27], off nt
	s_nop 0
	global_load_dword v28, v[28:29], off nt
	s_nop 0
	global_load_dword v29, v[30:31], off nt
	s_nop 0
	global_load_dword v30, v[42:43], off nt
	v_add_u32_e32 v31, 64, v45
	v_med3_i32 v18, v31, 0, v41
	v_add_u32_e32 v42, 0x48, v45
	v_add_u32_e32 v43, 0x50, v45
	v_add_u32_e32 v58, 0x58, v45
	v_add_u32_e32 v59, 0x60, v45
	v_lshlrev_b32_e32 v18, 13, v18
	v_mov_b32_e32 v19, v33
	v_med3_i32 v20, v42, 0, v41
	v_med3_i32 v22, v43, 0, v41
	v_med3_i32 v24, v58, 0, v41
	v_med3_i32 v26, v59, 0, v41
	v_lshl_add_u64 v[18:19], v[16:17], 0, v[18:19]
	v_lshlrev_b32_e32 v20, 13, v20
	v_mov_b32_e32 v21, v33
	v_lshlrev_b32_e32 v22, 13, v22
	v_mov_b32_e32 v23, v33
	v_lshlrev_b32_e32 v24, 13, v24
	v_mov_b32_e32 v25, v33
	v_lshlrev_b32_e32 v26, 13, v26
	v_mov_b32_e32 v27, v33
	v_lshl_add_u64 v[20:21], v[16:17], 0, v[20:21]
	v_lshl_add_u64 v[22:23], v[16:17], 0, v[22:23]
	v_lshl_add_u64 v[24:25], v[16:17], 0, v[24:25]
	v_lshl_add_u64 v[26:27], v[16:17], 0, v[26:27]
	global_load_dword v60, v[18:19], off nt
	global_load_dword v61, v[20:21], off nt
	global_load_dword v62, v[22:23], off nt
	global_load_dword v63, v[24:25], off nt
	global_load_dword v64, v[26:27], off nt
	v_add_u32_e32 v65, 0x68, v45
	v_med3_i32 v18, v65, 0, v41
	v_add_u32_e32 v66, 0x70, v45
	v_lshlrev_b32_e32 v18, 13, v18
	v_mov_b32_e32 v19, v33
	v_med3_i32 v20, v66, 0, v41
	v_lshl_add_u64 v[18:19], v[16:17], 0, v[18:19]
	v_lshlrev_b32_e32 v20, 13, v20
	v_mov_b32_e32 v21, v33
	v_add_u32_e32 v69, 0x78, v45
	v_lshl_add_u64 v[20:21], v[16:17], 0, v[20:21]
	global_load_dword v67, v[18:19], off nt
	global_load_dword v68, v[20:21], off nt
	v_med3_i32 v18, v69, 0, v41
	v_lshlrev_b32_e32 v18, 13, v18
	v_mov_b32_e32 v19, v33
	v_lshl_add_u64 v[16:17], v[16:17], 0, v[18:19]
	global_load_dword v70, v[16:17], off nt
	s_waitcnt vmcnt(24)
	s_branch .LBB0_1411

; DEVI unsigned pk_bf16(float lo, float hi) { unsigned r; asm("v_cvt_pk_bf16_f32 %0, %1, %2" : "=v"(r) : "v"(lo), "v"(hi)); return r; }
; DEVI void cvt_job(LAS float* tile, const float* src, int srcK, int srcN, bf16_t* dst, int dstLd, int dstRows, int dstCol0, int mode, const float* gk = nullptr) {
;     ...
;         for (int i = 0; i < 16; ++i) { const int k = kap0 + ty + 8 * i - dstCol0; regs[i] = (nok && k >= 0 && k < srcK) ? raw[i] * gs[i] : 0.f; }
;     };
;     auto emit = [&](int t, float (&regs)[16]) {
; #pragma unroll
;         for (int i = 0; i < 16; ++i) tile[(ty + 8 * i) * 65 + tx] = regs[i];
;         __syncthreads();
;         int rho0, kap0, n0; coords(t, rho0, kap0, n0);
;         const int tn = t + 2 * gridDim.x;
;         if (tn < ntot) gl(tn, regs);
; #pragma unroll
;         for (int i = 0; i < 8; ++i) { const int row = ty + 8 * i;
;             const float lo = tile[(2 * tx) * 65 + row], hi = tile[(2 * tx + 1) * 65 + row];
;             *(unsigned*)(dst + (size_t)(rho0 + row) * dstLd + kap0 + 2 * tx) = pk_bf16(lo, hi); }
.LBB0_1522:
.LBB0_1523:
	v_cmp_gt_i32_e32 vcc, s11, v203
	v_cmp_gt_u32_e64 s[36:37], s12, v202
	v_mul_f32_e32 v140, v205, v140
	s_and_b64 s[36:37], s[36:37], vcc
	v_cndmask_b32_e64 v0, 0, v140, s[36:37]
	v_cmp_gt_u32_e64 s[36:37], s12, v204
	v_mul_f32_e32 v141, v207, v141
	s_and_b64 s[36:37], s[36:37], vcc
	v_cndmask_b32_e64 v1, 0, v141, s[36:37]
	v_cmp_gt_u32_e64 s[36:37], s12, v206
	v_mul_f32_e32 v142, v209, v142
	s_and_b64 s[36:37], s[36:37], vcc
	v_cndmask_b32_e64 v2, 0, v142, s[36:37]
	v_cmp_gt_u32_e64 s[36:37], s12, v208
	v_mul_f32_e32 v143, v211, v143
	s_and_b64 s[36:37], s[36:37], vcc
	v_cndmask_b32_e64 v3, 0, v143, s[36:37]
	v_cmp_gt_u32_e64 s[36:37], s12, v210
	v_mul_f32_e32 v144, v213, v144
	s_and_b64 s[36:37], s[36:37], vcc
	v_cndmask_b32_e64 v4, 0, v144, s[36:37]
	v_cmp_gt_u32_e64 s[36:37], s12, v212
	v_mul_f32_e32 v145, v215, v145
	s_and_b64 s[36:37], s[36:37], vcc
	v_cndmask_b32_e64 v5, 0, v145, s[36:37]
	v_cmp_gt_u32_e64 s[36:37], s12, v214
	v_mul_f32_e32 v146, v217, v146
	s_and_b64 s[36:37], s[36:37], vcc
	v_cndmask_b32_e64 v6, 0, v146, s[36:37]
	v_cmp_gt_u32_e64 s[36:37], s12, v216
	v_mul_f32_e32 v147, v220, v147
	s_and_b64 s[36:37], s[36:37], vcc
	v_cndmask_b32_e64 v7, 0, v147, s[36:37]
	v_cmp_gt_u32_e64 s[36:37], s12, v218
	v_mul_f32_e32 v148, v221, v148
	s_and_b64 s[36:37], s[36:37], vcc
	v_cndmask_b32_e64 v8, 0, v148, s[36:37]
	v_cmp_gt_u32_e64 s[36:37], s12, v219
	v_mul_f32_e32 v149, v223, v149
	s_and_b64 s[36:37], s[36:37], vcc
	v_cndmask_b32_e64 v9, 0, v149, s[36:37]
	v_cmp_gt_u32_e64 s[36:37], s12, v222
	v_mul_f32_e32 v150, v225, v150
	s_and_b64 s[36:37], s[36:37], vcc
	v_cndmask_b32_e64 v10, 0, v150, s[36:37]
	v_cmp_gt_u32_e64 s[36:37], s12, v224
	v_mul_f32_e32 v151, v227, v151
	s_and_b64 s[36:37], s[36:37], vcc
	v_cndmask_b32_e64 v11, 0, v151, s[36:37]
	v_cmp_gt_u32_e64 s[36:37], s12, v226
	v_mul_f32_e32 v152, v229, v152
	s_and_b64 s[36:37], s[36:37], vcc
	v_cndmask_b32_e64 v12, 0, v152, s[36:37]
	v_cmp_gt_u32_e64 s[36:37], s12, v228
	v_mul_f32_e32 v153, v231, v153
	s_and_b64 s[36:37], s[36:37], vcc
	v_cndmask_b32_e64 v13, 0, v153, s[36:37]
	v_cmp_gt_u32_e64 s[36:37], s12, v230
	v_mul_f32_e32 v154, v233, v154
	s_and_b64 s[36:37], s[36:37], vcc
	v_cndmask_b32_e64 v14, 0, v154, s[36:37]
	v_cmp_gt_u32_e64 s[36:37], s12, v232
	v_mul_f32_e32 v155, v234, v155
	s_and_b64 vcc, s[36:37], vcc
	v_cndmask_b32_e32 v15, 0, v155, vcc
	s_mul_hi_i32 s4, s8, 0x2e8ba2e9
	s_lshr_b32 s8, s4, 31
	s_ashr_i32 s4, s4, 4
	s_add_i32 s8, s4, s8
	s_mul_i32 s4, s8, 0x3ffff50
	s_add_i32 s9, s30, s7
	s_add_i32 s9, s9, s4
	s_and_b32 s4, s9, 0x3fffffc
	s_or_b32 s4, s4, s5
	s_lshl_b32 s4, s4, 6
	ds_read2_b32 v[134:135], v52 offset0:65 offset1:73
	ds_read2_b32 v[136:137], v52 offset1:8
	v_add_u32_e32 v138, s4, v51
	s_lshl_b32 s8, s8, 7
	v_ashrrev_i32_e32 v139, 31, v138
	s_ashr_i32 s9, s8, 31
	v_lshlrev_b64 v[138:139], 12, v[138:139]
	v_lshl_add_u64 v[138:139], s[62:63], 0, v[138:139]
	s_lshl_b64 s[8:9], s[8:9], 1
	v_lshl_add_u64 v[138:139], v[138:139], 0, s[8:9]
	s_waitcnt lgkmcnt(0)
	v_cvt_pk_bf16_f32 v134, v136, v134
	v_lshl_add_u64 v[138:139], v[138:139], 0, v[32:33]
	global_store_dword v[138:139], v134, off
	v_add_u32_e32 v134, s4, v53
	v_cvt_pk_bf16_f32 v136, v137, v135
	v_ashrrev_i32_e32 v135, 31, v134
	v_lshlrev_b64 v[134:135], 12, v[134:135]
	v_lshl_add_u64 v[134:135], s[62:63], 0, v[134:135]
	v_lshl_add_u64 v[134:135], v[134:135], 0, s[8:9]
	v_lshl_add_u64 v[134:135], v[134:135], 0, v[32:33]
	global_store_dword v[134:135], v136, off
	ds_read2_b32 v[134:135], v52 offset0:16 offset1:24
	ds_read2_b32 v[136:137], v52 offset0:81 offset1:89
	v_add_u32_e32 v138, s4, v54
	v_ashrrev_i32_e32 v139, 31, v138
	v_lshlrev_b64 v[138:139], 12, v[138:139]
	v_lshl_add_u64 v[138:139], s[62:63], 0, v[138:139]
	v_lshl_add_u64 v[138:139], v[138:139], 0, s[8:9]
	s_waitcnt lgkmcnt(0)
	v_cvt_pk_bf16_f32 v134, v134, v136
	v_lshl_add_u64 v[138:139], v[138:139], 0, v[32:33]
	global_store_dword v[138:139], v134, off
	v_add_u32_e32 v134, s4, v55
	v_cvt_pk_bf16_f32 v136, v135, v137
	v_ashrrev_i32_e32 v135, 31, v134
	v_lshlrev_b64 v[134:135], 12, v[134:135]
	v_lshl_add_u64 v[134:135], s[62:63], 0, v[134:135]
	v_lshl_add_u64 v[134:135], v[134:135], 0, s[8:9]
	v_lshl_add_u64 v[134:135], v[134:135], 0, v[32:33]
	global_store_dword v[134:135], v136, off
	ds_read2_b32 v[134:135], v52 offset0:32 offset1:40
	ds_read2_b32 v[136:137], v52 offset0:97 offset1:105
	v_add_u32_e32 v138, s4, v56
	v_ashrrev_i32_e32 v139, 31, v138
	v_lshlrev_b64 v[138:139], 12, v[138:139]
	v_lshl_add_u64 v[138:139], s[62:63], 0, v[138:139]
	v_lshl_add_u64 v[138:139], v[138:139], 0, s[8:9]
	s_waitcnt lgkmcnt(0)
; DEVI unsigned pk_bf16(float lo, float hi) { unsigned r; asm("v_cvt_pk_bf16_f32 %0, %1, %2" : "=v"(r) : "v"(lo), "v"(hi)); return r; }
; DEVI void cvt_job(LAS float* tile, const float* src, int srcK, int srcN, bf16_t* dst, int dstLd, int dstRows, int dstCol0, int mode, const float* gk = nullptr) {
;     ...
;         for (int i = 0; i < 16; ++i) { const int k = kap0 + ty + 8 * i - dstCol0; regs[i] = (nok && k >= 0 && k < srcK) ? raw[i] * gs[i] : 0.f; }
;     };
;     auto emit = [&](int t, float (&regs)[16]) {
; #pragma unroll
;         for (int i = 0; i < 16; ++i) tile[(ty + 8 * i) * 65 + tx] = regs[i];
;         __syncthreads();
;         int rho0, kap0, n0; coords(t, rho0, kap0, n0);
;         const int tn = t + 2 * gridDim.x;
;         if (tn < ntot) gl(tn, regs);
; #pragma unroll
;         for (int i = 0; i < 8; ++i) { const int row = ty + 8 * i;
;             const float lo = tile[(2 * tx) * 65 + row], hi = tile[(2 * tx + 1) * 65 + row];
;             *(unsigned*)(dst + (size_t)(rho0 + row) * dstLd + kap0 + 2 * tx) = pk_bf16(lo, hi); }
;         __syncthreads();
	v_cvt_pk_bf16_f32 v134, v134, v136
	v_lshl_add_u64 v[138:139], v[138:139], 0, v[32:33]
	global_store_dword v[138:139], v134, off
	v_add_u32_e32 v134, s4, v57
	v_cvt_pk_bf16_f32 v136, v135, v137
	v_ashrrev_i32_e32 v135, 31, v134
	v_lshlrev_b64 v[134:135], 12, v[134:135]
	v_lshl_add_u64 v[134:135], s[62:63], 0, v[134:135]
	v_lshl_add_u64 v[134:135], v[134:135], 0, s[8:9]
	v_lshl_add_u64 v[134:135], v[134:135], 0, v[32:33]
	global_store_dword v[134:135], v136, off
	ds_read2_b32 v[134:135], v52 offset0:48 offset1:56
	ds_read2_b32 v[136:137], v52 offset0:113 offset1:121
	v_add_u32_e32 v138, s4, v58
	v_ashrrev_i32_e32 v139, 31, v138
	v_lshlrev_b64 v[138:139], 12, v[138:139]
	v_lshl_add_u64 v[138:139], s[62:63], 0, v[138:139]
	v_lshl_add_u64 v[138:139], v[138:139], 0, s[8:9]
	s_waitcnt lgkmcnt(0)
	v_cvt_pk_bf16_f32 v134, v134, v136
	v_lshl_add_u64 v[138:139], v[138:139], 0, v[32:33]
	global_store_dword v[138:139], v134, off
	v_add_u32_e32 v134, s4, v59
	v_cvt_pk_bf16_f32 v136, v135, v137
	v_ashrrev_i32_e32 v135, 31, v134
	v_lshlrev_b64 v[134:135], 12, v[134:135]
	v_lshl_add_u64 v[134:135], s[62:63], 0, v[134:135]
	v_lshl_add_u64 v[134:135], v[134:135], 0, s[8:9]
	v_lshl_add_u64 v[134:135], v[134:135], 0, v[32:33]
	global_store_dword v[134:135], v136, off
	v_cmp_gt_i32_e32 vcc, s11, v63
	v_cmp_gt_u32_e64 s[36:37], s12, v62
	s_waitcnt vmcnt(23)
	v_mul_f32_e32 v16, v65, v16
	s_and_b64 s[36:37], s[36:37], vcc
	v_cndmask_b32_e64 v16, 0, v16, s[36:37]
	v_cmp_gt_u32_e64 s[36:37], s12, v64
	s_waitcnt vmcnt(22)
	v_mul_f32_e32 v17, v67, v17
	s_and_b64 s[36:37], s[36:37], vcc
	v_cndmask_b32_e64 v17, 0, v17, s[36:37]
	v_cmp_gt_u32_e64 s[36:37], s12, v66
	s_waitcnt vmcnt(21)
	v_mul_f32_e32 v18, v69, v18
	s_and_b64 s[36:37], s[36:37], vcc
	v_cndmask_b32_e64 v18, 0, v18, s[36:37]
	v_cmp_gt_u32_e64 s[36:37], s12, v68
	s_waitcnt vmcnt(20)
	v_mul_f32_e32 v19, v71, v19
	s_and_b64 s[36:37], s[36:37], vcc
	v_cndmask_b32_e64 v19, 0, v19, s[36:37]
	v_cmp_gt_u32_e64 s[36:37], s12, v70
	s_waitcnt vmcnt(19)
	v_mul_f32_e32 v20, v73, v20
	s_and_b64 s[36:37], s[36:37], vcc
	v_cndmask_b32_e64 v20, 0, v20, s[36:37]
	v_cmp_gt_u32_e64 s[36:37], s12, v72
	s_waitcnt vmcnt(18)
	v_mul_f32_e32 v21, v75, v21
	s_and_b64 s[36:37], s[36:37], vcc
	v_cndmask_b32_e64 v21, 0, v21, s[36:37]
	v_cmp_gt_u32_e64 s[36:37], s12, v74
	s_waitcnt vmcnt(17)
	v_mul_f32_e32 v22, v77, v22
	s_and_b64 s[36:37], s[36:37], vcc
	v_cndmask_b32_e64 v22, 0, v22, s[36:37]
	v_cmp_gt_u32_e64 s[36:37], s12, v76
	s_waitcnt vmcnt(16)
	v_mul_f32_e32 v23, v80, v23
	s_and_b64 s[36:37], s[36:37], vcc
	v_cndmask_b32_e64 v23, 0, v23, s[36:37]
	v_cmp_gt_u32_e64 s[36:37], s12, v78
	s_waitcnt vmcnt(15)
	v_mul_f32_e32 v24, v81, v24
	s_and_b64 s[36:37], s[36:37], vcc
	v_cndmask_b32_e64 v24, 0, v24, s[36:37]
	v_cmp_gt_u32_e64 s[36:37], s12, v79
	s_waitcnt vmcnt(14)
	v_mul_f32_e32 v25, v83, v25
	s_and_b64 s[36:37], s[36:37], vcc
	v_cndmask_b32_e64 v25, 0, v25, s[36:37]
	v_cmp_gt_u32_e64 s[36:37], s12, v82
	s_waitcnt vmcnt(13)
	v_mul_f32_e32 v26, v85, v26
	s_and_b64 s[36:37], s[36:37], vcc
	v_cndmask_b32_e64 v26, 0, v26, s[36:37]
	v_cmp_gt_u32_e64 s[36:37], s12, v84
	s_waitcnt vmcnt(12)
	v_mul_f32_e32 v27, v87, v27
	s_and_b64 s[36:37], s[36:37], vcc
	v_cndmask_b32_e64 v27, 0, v27, s[36:37]
	v_cmp_gt_u32_e64 s[36:37], s12, v86
	s_waitcnt vmcnt(11)
	v_mul_f32_e32 v28, v89, v28
	s_and_b64 s[36:37], s[36:37], vcc
	v_cndmask_b32_e64 v28, 0, v28, s[36:37]
	v_cmp_gt_u32_e64 s[36:37], s12, v88
	s_waitcnt vmcnt(10)
	v_mul_f32_e32 v29, v91, v29
	s_and_b64 s[36:37], s[36:37], vcc
	v_cndmask_b32_e64 v29, 0, v29, s[36:37]
	v_cmp_gt_u32_e64 s[36:37], s12, v90
	s_waitcnt vmcnt(9)
	v_mul_f32_e32 v30, v93, v30
	s_and_b64 s[36:37], s[36:37], vcc
	v_cndmask_b32_e64 v30, 0, v30, s[36:37]
	v_cmp_gt_u32_e64 s[36:37], s12, v92
	s_waitcnt vmcnt(8)
	v_mul_f32_e32 v31, v94, v31
	s_and_b64 vcc, s[36:37], vcc
	v_cndmask_b32_e32 v31, 0, v31, vcc
	s_barrier

; DEVI void cvt_job(LAS float* tile, const float* src, int srcK, int srcN, bf16_t* dst, int dstLd, int dstRows, int dstCol0, int mode, const float* gk = nullptr) {
;     ...
;     auto gl = [&](int t, float (&regs)[16]) {
;         int rho0, kap0, n0; coords(t, rho0, kap0, n0);
;         const int n = n0 + tx, nc = n < srcN ? n : srcN - 1;
;         const bool nok = n < srcN;
;         float raw[16], gs[16];
; #pragma unroll
;         for (int i = 0; i < 16; ++i) { const int k = kap0 + ty + 8 * i - dstCol0; const int kc = k < 0 ? 0 : (k < srcK ? k : srcK - 1);
;             raw[i] = __builtin_nontemporal_load(src + (size_t)kc * srcN + nc); }
;         if (gk) {
; #pragma unroll
;             for (int i = 0; i < 16; ++i) { const int k = kap0 + ty + 8 * i - dstCol0; const int kc = k < 0 ? 0 : (k < srcK ? k : srcK - 1); gs[i] = gk[kc]; }
;         } else {
; #pragma unroll
;             for (int i = 0; i < 16; ++i) gs[i] = 1.0f;
;         }
; #pragma unroll
;         for (int i = 0; i < 16; ++i) { const int k = kap0 + ty + 8 * i - dstCol0; regs[i] = (nok && k >= 0 && k < srcK) ? raw[i] * gs[i] : 0.f; }
;     };
;     auto emit = [&](int t, float (&regs)[16]) {
; #pragma unroll
;         for (int i = 0; i < 16; ++i) tile[(ty + 8 * i) * 65 + tx] = regs[i];
;         __syncthreads();
;         int rho0, kap0, n0; coords(t, rho0, kap0, n0);
;         const int tn = t + 2 * gridDim.x;
;         if (tn < ntot) gl(tn, regs);
.LBB0_1525:
	s_add_i32 s13, s4, s30
	s_cmpk_gt_i32 s13, 0x57f
	s_cselect_b64 s[2:3], -1, 0
	s_and_b64 vcc, exec, s[2:3]
	ds_write_b32 v60, v0
	ds_write_b32 v60, v1 offset:2080
	ds_write_b32 v60, v2 offset:4160
	ds_write_b32 v60, v3 offset:6240
	ds_write_b32 v60, v4 offset:8320
	ds_write_b32 v60, v5 offset:10400
	ds_write_b32 v60, v6 offset:12480
	ds_write_b32 v60, v7 offset:14560
	ds_write_b32 v60, v8 offset:16640
	ds_write_b32 v60, v9 offset:18720
	ds_write_b32 v60, v10 offset:20800
	ds_write_b32 v60, v11 offset:22880
	ds_write_b32 v60, v12 offset:24960
	ds_write_b32 v60, v13 offset:27040
	ds_write_b32 v60, v14 offset:29120
	ds_write_b32 v60, v15 offset:31200
	s_waitcnt lgkmcnt(0)
	s_barrier
	s_cbranch_vccnz .LBB0_1530
	s_mul_hi_i32 s8, s13, 0x2e8ba2e9
	s_lshr_b32 s9, s8, 31
	s_ashr_i32 s8, s8, 4
	s_add_i32 s8, s8, s9
	s_mul_i32 s9, s8, 0x3ffff50
	s_add_i32 s14, s48, s7
	s_add_i32 s14, s14, s9
	s_and_b32 s9, s14, 0x3fffffc
	s_or_b32 s9, s9, s6
	s_lshl_b32 s9, s9, 6
	s_ashr_i32 s14, s9, 1
	s_and_b32 s14, s14, 0xffffff80
	s_and_b32 s9, s9, 64
	s_or_b32 s9, s9, s14
	v_or_b32_e32 v203, s9, v50
	v_min_i32_e32 v140, 0x15ff, v203
	v_lshl_add_u32 v202, s8, 7, v51
	v_ashrrev_i32_e32 v141, 31, v140
	v_lshl_add_u64 v[234:235], v[140:141], 2, s[0:1]
	v_med3_i32 v140, v202, 0, v61
	v_mad_u64_u32 v[142:143], s[8:9], v140, s10, v[234:235]
	v_add_u32_e32 v204, 8, v202
	global_load_dword v205, v[142:143], off nt
	v_med3_i32 v142, v204, 0, v61
	v_mad_u64_u32 v[144:145], s[8:9], v142, s10, v[234:235]
	v_add_u32_e32 v206, 16, v202
	global_load_dword v207, v[144:145], off nt
	v_med3_i32 v144, v206, 0, v61
	v_mad_u64_u32 v[146:147], s[8:9], v144, s10, v[234:235]
	v_add_u32_e32 v208, 24, v202
	global_load_dword v209, v[146:147], off nt
	v_med3_i32 v146, v208, 0, v61
	v_mad_u64_u32 v[148:149], s[8:9], v146, s10, v[234:235]
	v_add_u32_e32 v210, 32, v202
	global_load_dword v211, v[148:149], off nt
	v_med3_i32 v148, v210, 0, v61
	v_mad_u64_u32 v[150:151], s[8:9], v148, s10, v[234:235]
	v_add_u32_e32 v212, 40, v202
	global_load_dword v213, v[150:151], off nt
	v_med3_i32 v150, v212, 0, v61
	v_mad_u64_u32 v[152:153], s[8:9], v150, s10, v[234:235]
	v_add_u32_e32 v214, 48, v202
	global_load_dword v215, v[152:153], off nt
	v_med3_i32 v152, v214, 0, v61
	v_mad_u64_u32 v[154:155], s[8:9], v152, s10, v[234:235]
	v_add_u32_e32 v216, 56, v202
	global_load_dword v217, v[154:155], off nt
	v_med3_i32 v154, v216, 0, v61
	v_mad_u64_u32 v[174:175], s[8:9], v154, s10, v[234:235]
	v_add_u32_e32 v218, 64, v202
	global_load_dword v220, v[174:175], off nt
	v_med3_i32 v174, v218, 0, v61
	v_mad_u64_u32 v[176:177], s[8:9], v174, s10, v[234:235]
	v_add_u32_e32 v219, 0x48, v202
	global_load_dword v221, v[176:177], off nt
	v_med3_i32 v176, v219, 0, v61
	v_mad_u64_u32 v[178:179], s[8:9], v176, s10, v[234:235]
	v_add_u32_e32 v222, 0x50, v202
	global_load_dword v223, v[178:179], off nt
	v_med3_i32 v178, v222, 0, v61
	v_mad_u64_u32 v[180:181], s[8:9], v178, s10, v[234:235]
	v_add_u32_e32 v224, 0x58, v202
	global_load_dword v225, v[180:181], off nt
	v_med3_i32 v180, v224, 0, v61
	v_mad_u64_u32 v[182:183], s[8:9], v180, s10, v[234:235]
	v_add_u32_e32 v226, 0x60, v202
	global_load_dword v227, v[182:183], off nt
	v_med3_i32 v182, v226, 0, v61
	v_mad_u64_u32 v[184:185], s[8:9], v182, s10, v[234:235]
	v_add_u32_e32 v228, 0x68, v202
	global_load_dword v229, v[184:185], off nt
	v_med3_i32 v184, v228, 0, v61
	v_mad_u64_u32 v[186:187], s[8:9], v184, s10, v[234:235]
	v_add_u32_e32 v230, 0x70, v202
	global_load_dword v231, v[186:187], off nt
	v_med3_i32 v186, v230, 0, v61
	v_mad_u64_u32 v[188:189], s[8:9], v186, s10, v[234:235]
	v_add_u32_e32 v232, 0x78, v202
	global_load_dword v233, v[188:189], off nt
	v_med3_i32 v188, v232, 0, v61
	v_mad_u64_u32 v[234:235], s[8:9], v188, s10, v[234:235]
	global_load_dword v234, v[234:235], off nt
	v_readlane_b32 s8, v240, 48
	v_readlane_b32 s9, v240, 49
	s_and_b64 vcc, exec, s[8:9]
	s_cbranch_vccnz .LBB0_1528
	v_mov_b32_e32 v141, v33
	v_mov_b32_e32 v143, v33
	v_mov_b32_e32 v145, v33
	v_mov_b32_e32 v147, v33
	v_mov_b32_e32 v149, v33
	v_mov_b32_e32 v151, v33
	v_mov_b32_e32 v153, v33
	v_mov_b32_e32 v155, v33
	v_mov_b32_e32 v175, v33
	v_mov_b32_e32 v177, v33
	v_mov_b32_e32 v179, v33
	v_mov_b32_e32 v181, v33
	v_lshl_add_u64 v[140:141], v[140:141], 2, s[38:39]
	v_lshl_add_u64 v[142:143], v[142:143], 2, s[38:39]
	v_lshl_add_u64 v[144:145], v[144:145], 2, s[38:39]
	v_lshl_add_u64 v[146:147], v[146:147], 2, s[38:39]
	v_lshl_add_u64 v[148:149], v[148:149], 2, s[38:39]
	v_lshl_add_u64 v[150:151], v[150:151], 2, s[38:39]
	v_lshl_add_u64 v[152:153], v[152:153], 2, s[38:39]
	v_lshl_add_u64 v[154:155], v[154:155], 2, s[38:39]
	v_mov_b32_e32 v183, v33
	v_mov_b32_e32 v185, v33
	v_mov_b32_e32 v187, v33
	v_mov_b32_e32 v189, v33
	global_load_dword v140, v[140:141], off
	s_nop 0
	global_load_dword v141, v[142:143], off
	s_nop 0
	global_load_dword v142, v[144:145], off
	global_load_dword v143, v[146:147], off
	s_nop 0
	global_load_dword v144, v[148:149], off
	global_load_dword v145, v[150:151], off
	global_load_dword v146, v[152:153], off
	global_load_dword v147, v[154:155], off
	v_lshl_add_u64 v[148:149], v[174:175], 2, s[38:39]
	v_lshl_add_u64 v[150:151], v[176:177], 2, s[38:39]
	v_lshl_add_u64 v[152:153], v[178:179], 2, s[38:39]
	v_lshl_add_u64 v[154:155], v[180:181], 2, s[38:39]
	v_lshl_add_u64 v[174:175], v[182:183], 2, s[38:39]
	v_lshl_add_u64 v[176:177], v[184:185], 2, s[38:39]
	v_lshl_add_u64 v[178:179], v[186:187], 2, s[38:39]
	v_lshl_add_u64 v[180:181], v[188:189], 2, s[38:39]
	global_load_dword v148, v[148:149], off
	s_nop 0
	global_load_dword v149, v[150:151], off
	s_nop 0
	global_load_dword v150, v[152:153], off
	global_load_dword v151, v[154:155], off
	s_nop 0
	global_load_dword v152, v[174:175], off
	global_load_dword v153, v[176:177], off
	global_load_dword v154, v[178:179], off
	global_load_dword v155, v[180:181], off
	s_branch .LBB0_1529

; DEVI unsigned pk_bf16(float lo, float hi) { unsigned r; asm("v_cvt_pk_bf16_f32 %0, %1, %2" : "=v"(r) : "v"(lo), "v"(hi)); return r; }
; DEVI void cvt_job(LAS float* tile, const float* src, int srcK, int srcN, bf16_t* dst, int dstLd, int dstRows, int dstCol0, int mode, const float* gk = nullptr) {
;     ...
;     auto emit = [&](int t, float (&regs)[16]) {
; #pragma unroll
;         for (int i = 0; i < 16; ++i) tile[(ty + 8 * i) * 65 + tx] = regs[i];
;         __syncthreads();
;         int rho0, kap0, n0; coords(t, rho0, kap0, n0);
;         const int tn = t + 2 * gridDim.x;
;         if (tn < ntot) gl(tn, regs);
; #pragma unroll
;         for (int i = 0; i < 8; ++i) { const int row = ty + 8 * i;
;             const float lo = tile[(2 * tx) * 65 + row], hi = tile[(2 * tx + 1) * 65 + row];
;             *(unsigned*)(dst + (size_t)(rho0 + row) * dstLd + kap0 + 2 * tx) = pk_bf16(lo, hi); }
;         __syncthreads();
.LBB0_1529:
.LBB0_1530:
	s_mul_hi_i32 s8, s4, 0x2e8ba2e9
	s_lshr_b32 s9, s8, 31
	s_ashr_i32 s8, s8, 4
	s_add_i32 s8, s8, s9
	s_mul_i32 s9, s8, 0x3ffff50
	s_add_i32 s9, s7, s9
	s_and_b32 s9, s9, 0x3fffffc
	s_or_b32 s9, s9, s6
	s_lshl_b32 s14, s9, 6
	ds_read2_b32 v[34:35], v52 offset0:65 offset1:73
	ds_read2_b32 v[36:37], v52 offset1:8
	v_add_u32_e32 v38, s14, v51
	s_lshl_b32 s8, s8, 7
	v_ashrrev_i32_e32 v39, 31, v38
	s_ashr_i32 s9, s8, 31
	v_lshlrev_b64 v[38:39], 12, v[38:39]
	v_lshl_add_u64 v[38:39], s[62:63], 0, v[38:39]
	s_lshl_b64 s[8:9], s[8:9], 1
	v_lshl_add_u64 v[38:39], v[38:39], 0, s[8:9]
	s_waitcnt lgkmcnt(0)
	v_cvt_pk_bf16_f32 v34, v36, v34
	v_lshl_add_u64 v[38:39], v[38:39], 0, v[32:33]
	global_store_dword v[38:39], v34, off
	v_add_u32_e32 v34, s14, v53
	v_cvt_pk_bf16_f32 v36, v37, v35
	v_ashrrev_i32_e32 v35, 31, v34
	v_lshlrev_b64 v[34:35], 12, v[34:35]
	v_lshl_add_u64 v[34:35], s[62:63], 0, v[34:35]
	v_lshl_add_u64 v[34:35], v[34:35], 0, s[8:9]
	v_lshl_add_u64 v[34:35], v[34:35], 0, v[32:33]
	global_store_dword v[34:35], v36, off
	ds_read2_b32 v[34:35], v52 offset0:16 offset1:24
	ds_read2_b32 v[36:37], v52 offset0:81 offset1:89
	v_add_u32_e32 v38, s14, v54
	v_ashrrev_i32_e32 v39, 31, v38
	v_lshlrev_b64 v[38:39], 12, v[38:39]
	v_lshl_add_u64 v[38:39], s[62:63], 0, v[38:39]
	v_lshl_add_u64 v[38:39], v[38:39], 0, s[8:9]
	s_waitcnt lgkmcnt(0)
	v_cvt_pk_bf16_f32 v34, v34, v36
	v_lshl_add_u64 v[38:39], v[38:39], 0, v[32:33]
	global_store_dword v[38:39], v34, off
	v_add_u32_e32 v34, s14, v55
	v_cvt_pk_bf16_f32 v36, v35, v37
	v_ashrrev_i32_e32 v35, 31, v34
	v_lshlrev_b64 v[34:35], 12, v[34:35]
	v_lshl_add_u64 v[34:35], s[62:63], 0, v[34:35]
	v_lshl_add_u64 v[34:35], v[34:35], 0, s[8:9]
	v_lshl_add_u64 v[34:35], v[34:35], 0, v[32:33]
	global_store_dword v[34:35], v36, off
	ds_read2_b32 v[34:35], v52 offset0:32 offset1:40
	ds_read2_b32 v[36:37], v52 offset0:97 offset1:105
	v_add_u32_e32 v38, s14, v56
	v_ashrrev_i32_e32 v39, 31, v38
	v_lshlrev_b64 v[38:39], 12, v[38:39]
	v_lshl_add_u64 v[38:39], s[62:63], 0, v[38:39]
	v_lshl_add_u64 v[38:39], v[38:39], 0, s[8:9]
	s_waitcnt lgkmcnt(0)
	v_cvt_pk_bf16_f32 v34, v34, v36
	v_lshl_add_u64 v[38:39], v[38:39], 0, v[32:33]
	global_store_dword v[38:39], v34, off
	v_add_u32_e32 v34, s14, v57
	v_cvt_pk_bf16_f32 v36, v35, v37
	v_ashrrev_i32_e32 v35, 31, v34
	v_lshlrev_b64 v[34:35], 12, v[34:35]
	v_lshl_add_u64 v[34:35], s[62:63], 0, v[34:35]
	v_lshl_add_u64 v[34:35], v[34:35], 0, s[8:9]
	v_lshl_add_u64 v[34:35], v[34:35], 0, v[32:33]
	global_store_dword v[34:35], v36, off
	ds_read2_b32 v[34:35], v52 offset0:48 offset1:56
	ds_read2_b32 v[36:37], v52 offset0:113 offset1:121
	v_add_u32_e32 v38, s14, v58
	v_ashrrev_i32_e32 v39, 31, v38
	v_lshlrev_b64 v[38:39], 12, v[38:39]
	v_lshl_add_u64 v[38:39], s[62:63], 0, v[38:39]
	v_lshl_add_u64 v[38:39], v[38:39], 0, s[8:9]
	s_waitcnt lgkmcnt(0)
	v_cvt_pk_bf16_f32 v34, v34, v36
	v_lshl_add_u64 v[38:39], v[38:39], 0, v[32:33]
	global_store_dword v[38:39], v34, off
	v_add_u32_e32 v34, s14, v59
	v_cvt_pk_bf16_f32 v36, v35, v37
	v_ashrrev_i32_e32 v35, 31, v34
	v_lshlrev_b64 v[34:35], 12, v[34:35]
	v_lshl_add_u64 v[34:35], s[62:63], 0, v[34:35]
	v_lshl_add_u64 v[34:35], v[34:35], 0, s[8:9]
	s_add_i32 s8, s33, s4
	v_lshl_add_u64 v[34:35], v[34:35], 0, v[32:33]
	s_cmpk_gt_i32 s8, 0x57f
	global_store_dword v[34:35], v36, off
	s_barrier
	s_cbranch_scc1 .LBB0_1524
	s_add_i32 s4, s18, s4
	s_cmpk_gt_i32 s4, 0x57f
	ds_write_b32 v60, v16
	ds_write_b32 v60, v17 offset:2080
	ds_write_b32 v60, v18 offset:4160
	ds_write_b32 v60, v19 offset:6240
	ds_write_b32 v60, v20 offset:8320
	ds_write_b32 v60, v21 offset:10400
	ds_write_b32 v60, v22 offset:12480
	ds_write_b32 v60, v23 offset:14560
	ds_write_b32 v60, v24 offset:16640
	ds_write_b32 v60, v25 offset:18720
	ds_write_b32 v60, v26 offset:20800
	ds_write_b32 v60, v27 offset:22880
	ds_write_b32 v60, v28 offset:24960
	ds_write_b32 v60, v29 offset:27040
	ds_write_b32 v60, v30 offset:29120
	ds_write_b32 v60, v31 offset:31200
	s_waitcnt lgkmcnt(0)
	s_barrier
; DEVI void cvt_job(LAS float* tile, const float* src, int srcK, int srcN, bf16_t* dst, int dstLd, int dstRows, int dstCol0, int mode, const float* gk = nullptr) {
;     ...
;     auto coords = [&](int t, int& rho0, int& kap0, int& n0) {
;         const int tc = t / nvr, v = t - tc * nvr; kap0 = tc << 7;
;         if (mode) { const int tr = ((v >> 1) << 2) + (mode == 2 ? 2 : 0) + (v & 1); rho0 = tr << 6; n0 = ((rho0 >> 8) << 7) + (rho0 & 127); }
;         else { rho0 = v << 6; n0 = rho0; }
;     };
;     auto gl = [&](int t, float (&regs)[16]) {
;         int rho0, kap0, n0; coords(t, rho0, kap0, n0);
;         const int n = n0 + tx, nc = n < srcN ? n : srcN - 1;
;         const bool nok = n < srcN;
;         float raw[16], gs[16];
; #pragma unroll
;         for (int i = 0; i < 16; ++i) { const int k = kap0 + ty + 8 * i - dstCol0; const int kc = k < 0 ? 0 : (k < srcK ? k : srcK - 1);
;             raw[i] = __builtin_nontemporal_load(src + (size_t)kc * srcN + nc); }
;         if (gk) {
; #pragma unroll
;             for (int i = 0; i < 16; ++i) { const int k = kap0 + ty + 8 * i - dstCol0; const int kc = k < 0 ? 0 : (k < srcK ? k : srcK - 1); gs[i] = gk[kc]; }
;         } else {
; #pragma unroll
;             for (int i = 0; i < 16; ++i) gs[i] = 1.0f;
	s_cbranch_scc1 .Lcvt_stub_5
	s_mul_hi_i32 s4, s4, 0x2e8ba2e9
	s_lshr_b32 s9, s4, 31
	s_ashr_i32 s4, s4, 4
	s_add_i32 s4, s4, s9
	s_mul_i32 s9, s4, 0x3ffff50
	s_add_i32 s14, s96, s7
	s_add_i32 s14, s14, s9
	s_and_b32 s9, s14, 0x3fffffc
	s_or_b32 s9, s9, s5
	s_lshl_b32 s9, s9, 6
	s_ashr_i32 s14, s9, 1
	s_and_b32 s14, s14, 0xffffff80
	s_and_b32 s9, s9, 64
	s_or_b32 s9, s9, s14
	v_or_b32_e32 v63, s9, v50
	v_min_i32_e32 v16, 0x15ff, v63
	v_lshl_add_u32 v62, s4, 7, v51
	v_ashrrev_i32_e32 v17, 31, v16
	v_lshl_add_u64 v[94:95], v[16:17], 2, s[0:1]
	v_med3_i32 v16, v62, 0, v61
	v_mad_u64_u32 v[18:19], s[14:15], v16, s10, v[94:95]
	v_add_u32_e32 v64, 8, v62
	global_load_dword v65, v[18:19], off nt
	v_med3_i32 v18, v64, 0, v61
	v_mad_u64_u32 v[20:21], s[14:15], v18, s10, v[94:95]
	v_add_u32_e32 v66, 16, v62
	global_load_dword v67, v[20:21], off nt
	v_med3_i32 v20, v66, 0, v61
	v_mad_u64_u32 v[22:23], s[14:15], v20, s10, v[94:95]
	v_add_u32_e32 v68, 24, v62
	global_load_dword v69, v[22:23], off nt
	v_med3_i32 v22, v68, 0, v61
	v_mad_u64_u32 v[24:25], s[14:15], v22, s10, v[94:95]
	v_add_u32_e32 v70, 32, v62
	global_load_dword v71, v[24:25], off nt
	v_med3_i32 v24, v70, 0, v61
	v_mad_u64_u32 v[26:27], s[14:15], v24, s10, v[94:95]
	v_add_u32_e32 v72, 40, v62
	global_load_dword v73, v[26:27], off nt
	v_med3_i32 v26, v72, 0, v61
	v_mad_u64_u32 v[28:29], s[14:15], v26, s10, v[94:95]
	v_add_u32_e32 v74, 48, v62
	global_load_dword v75, v[28:29], off nt
	v_med3_i32 v28, v74, 0, v61
	v_mad_u64_u32 v[30:31], s[14:15], v28, s10, v[94:95]
	v_add_u32_e32 v76, 56, v62
	global_load_dword v77, v[30:31], off nt
	v_med3_i32 v30, v76, 0, v61
	v_mad_u64_u32 v[34:35], s[14:15], v30, s10, v[94:95]
	v_add_u32_e32 v78, 64, v62
	global_load_dword v80, v[34:35], off nt
	v_med3_i32 v34, v78, 0, v61
	v_mad_u64_u32 v[36:37], s[14:15], v34, s10, v[94:95]
	v_add_u32_e32 v79, 0x48, v62
	global_load_dword v81, v[36:37], off nt
	v_med3_i32 v36, v79, 0, v61
	v_mad_u64_u32 v[38:39], s[14:15], v36, s10, v[94:95]
	v_add_u32_e32 v82, 0x50, v62
	global_load_dword v83, v[38:39], off nt
	v_med3_i32 v38, v82, 0, v61
	v_mad_u64_u32 v[40:41], s[14:15], v38, s10, v[94:95]
	v_add_u32_e32 v84, 0x58, v62
	global_load_dword v85, v[40:41], off nt
	v_med3_i32 v40, v84, 0, v61
	v_mad_u64_u32 v[42:43], s[14:15], v40, s10, v[94:95]
	v_add_u32_e32 v86, 0x60, v62
	global_load_dword v87, v[42:43], off nt
	v_med3_i32 v42, v86, 0, v61
	v_mad_u64_u32 v[44:45], s[14:15], v42, s10, v[94:95]
	v_add_u32_e32 v88, 0x68, v62
	global_load_dword v89, v[44:45], off nt
	v_med3_i32 v44, v88, 0, v61
	v_mad_u64_u32 v[46:47], s[14:15], v44, s10, v[94:95]
	v_add_u32_e32 v90, 0x70, v62
	global_load_dword v91, v[46:47], off nt
	v_med3_i32 v46, v90, 0, v61
	v_mad_u64_u32 v[48:49], s[14:15], v46, s10, v[94:95]
	v_add_u32_e32 v92, 0x78, v62
	global_load_dword v93, v[48:49], off nt
	v_med3_i32 v48, v92, 0, v61
	v_mad_u64_u32 v[94:95], s[14:15], v48, s10, v[94:95]
	global_load_dword v94, v[94:95], off nt
	v_readlane_b32 s14, v240, 48
	v_readlane_b32 s15, v240, 49
	s_and_b64 vcc, exec, s[14:15]
	s_cbranch_vccz .LBB0_1521
	v_mov_b32_e32 v31, 1.0
	v_mov_b32_e32 v30, 1.0
	v_mov_b32_e32 v29, 1.0
	v_mov_b32_e32 v28, 1.0
	v_mov_b32_e32 v27, 1.0
	v_mov_b32_e32 v26, 1.0
	v_mov_b32_e32 v25, 1.0
	v_mov_b32_e32 v24, 1.0
	v_mov_b32_e32 v23, 1.0
	v_mov_b32_e32 v22, 1.0
	v_mov_b32_e32 v21, 1.0
	v_mov_b32_e32 v20, 1.0
	v_mov_b32_e32 v19, 1.0
	v_mov_b32_e32 v18, 1.0
	v_mov_b32_e32 v17, 1.0
	v_mov_b32_e32 v16, 1.0
	s_waitcnt vmcnt(24)
	s_branch .LBB0_1522

; DEVI unsigned pk_bf16(float lo, float hi) { unsigned r; asm("v_cvt_pk_bf16_f32 %0, %1, %2" : "=v"(r) : "v"(lo), "v"(hi)); return r; }
; DEVI void cvt_job(LAS float* tile, const float* src, int srcK, int srcN, bf16_t* dst, int dstLd, int dstRows, int dstCol0, int mode, const float* gk = nullptr) {
;     ...
;         for (int i = 0; i < 16; ++i) { const int k = kap0 + ty + 8 * i - dstCol0; regs[i] = (nok && k >= 0 && k < srcK) ? raw[i] * gs[i] : 0.f; }
;     ...
;         int rho0, kap0, n0; coords(t, rho0, kap0, n0);
;         const int tn = t + 2 * gridDim.x;
;         if (tn < ntot) gl(tn, regs);
; #pragma unroll
;         for (int i = 0; i < 8; ++i) { const int row = ty + 8 * i;
;             const float lo = tile[(2 * tx) * 65 + row], hi = tile[(2 * tx + 1) * 65 + row];
;             *(unsigned*)(dst + (size_t)(rho0 + row) * dstLd + kap0 + 2 * tx) = pk_bf16(lo, hi); }
.LBB0_1547:
.LBB0_1548:
	v_cmp_gt_i32_e32 vcc, s11, v203
	v_cmp_gt_u32_e64 s[36:37], s12, v202
	v_mul_f32_e32 v140, v205, v140
	s_and_b64 s[36:37], s[36:37], vcc
	v_cndmask_b32_e64 v0, 0, v140, s[36:37]
	v_cmp_gt_u32_e64 s[36:37], s12, v204
	v_mul_f32_e32 v141, v207, v141
	s_and_b64 s[36:37], s[36:37], vcc
	v_cndmask_b32_e64 v1, 0, v141, s[36:37]
	v_cmp_gt_u32_e64 s[36:37], s12, v206
	v_mul_f32_e32 v142, v209, v142
	s_and_b64 s[36:37], s[36:37], vcc
	v_cndmask_b32_e64 v2, 0, v142, s[36:37]
	v_cmp_gt_u32_e64 s[36:37], s12, v208
	v_mul_f32_e32 v143, v211, v143
	s_and_b64 s[36:37], s[36:37], vcc
	v_cndmask_b32_e64 v3, 0, v143, s[36:37]
	v_cmp_gt_u32_e64 s[36:37], s12, v210
	v_mul_f32_e32 v144, v213, v144
	s_and_b64 s[36:37], s[36:37], vcc
	v_cndmask_b32_e64 v4, 0, v144, s[36:37]
	v_cmp_gt_u32_e64 s[36:37], s12, v212
	v_mul_f32_e32 v145, v215, v145
	s_and_b64 s[36:37], s[36:37], vcc
	v_cndmask_b32_e64 v5, 0, v145, s[36:37]
	v_cmp_gt_u32_e64 s[36:37], s12, v214
	v_mul_f32_e32 v146, v217, v146
	s_and_b64 s[36:37], s[36:37], vcc
	v_cndmask_b32_e64 v6, 0, v146, s[36:37]
	v_cmp_gt_u32_e64 s[36:37], s12, v216
	v_mul_f32_e32 v147, v220, v147
	s_and_b64 s[36:37], s[36:37], vcc
	v_cndmask_b32_e64 v7, 0, v147, s[36:37]
	v_cmp_gt_u32_e64 s[36:37], s12, v218
	v_mul_f32_e32 v148, v221, v148
	s_and_b64 s[36:37], s[36:37], vcc
	v_cndmask_b32_e64 v8, 0, v148, s[36:37]
	v_cmp_gt_u32_e64 s[36:37], s12, v219
	v_mul_f32_e32 v149, v223, v149
	s_and_b64 s[36:37], s[36:37], vcc
	v_cndmask_b32_e64 v9, 0, v149, s[36:37]
	v_cmp_gt_u32_e64 s[36:37], s12, v222
	v_mul_f32_e32 v150, v225, v150
	s_and_b64 s[36:37], s[36:37], vcc
	v_cndmask_b32_e64 v10, 0, v150, s[36:37]
	v_cmp_gt_u32_e64 s[36:37], s12, v224
	v_mul_f32_e32 v151, v227, v151
	s_and_b64 s[36:37], s[36:37], vcc
	v_cndmask_b32_e64 v11, 0, v151, s[36:37]
	v_cmp_gt_u32_e64 s[36:37], s12, v226
	v_mul_f32_e32 v152, v229, v152
	s_and_b64 s[36:37], s[36:37], vcc
	v_cndmask_b32_e64 v12, 0, v152, s[36:37]
	v_cmp_gt_u32_e64 s[36:37], s12, v228
	v_mul_f32_e32 v153, v231, v153
	s_and_b64 s[36:37], s[36:37], vcc
	v_cndmask_b32_e64 v13, 0, v153, s[36:37]
	v_cmp_gt_u32_e64 s[36:37], s12, v230
	v_mul_f32_e32 v154, v233, v154
	s_and_b64 s[36:37], s[36:37], vcc
	v_cndmask_b32_e64 v14, 0, v154, s[36:37]
	v_cmp_gt_u32_e64 s[36:37], s12, v232
	v_mul_f32_e32 v155, v234, v155
	s_and_b64 vcc, s[36:37], vcc
	v_cndmask_b32_e32 v15, 0, v155, vcc
	s_mul_hi_i32 s4, s8, 0x2e8ba2e9
	s_lshr_b32 s8, s4, 31
	s_ashr_i32 s4, s4, 4
	s_add_i32 s8, s4, s8
	s_mul_i32 s4, s8, 0x3ffff50
	s_add_i32 s9, s30, s7
	s_add_i32 s9, s9, s4
	s_and_b32 s4, s9, 0x3fffffc
	s_or_b32 s4, s4, s5
	s_lshl_b32 s4, s4, 6
	s_bitset1_b32 s4, 7
	ds_read2_b32 v[134:135], v52 offset0:65 offset1:73
	ds_read2_b32 v[136:137], v52 offset1:8
	v_add_u32_e32 v138, s4, v51
	s_lshl_b32 s8, s8, 7
	v_ashrrev_i32_e32 v139, 31, v138
	s_ashr_i32 s9, s8, 31
	v_lshlrev_b64 v[138:139], 12, v[138:139]
	v_lshl_add_u64 v[138:139], s[62:63], 0, v[138:139]
	s_lshl_b64 s[8:9], s[8:9], 1
	v_lshl_add_u64 v[138:139], v[138:139], 0, s[8:9]
	s_waitcnt lgkmcnt(0)
	v_cvt_pk_bf16_f32 v134, v136, v134
	v_lshl_add_u64 v[138:139], v[138:139], 0, v[32:33]
	global_store_dword v[138:139], v134, off
	v_add_u32_e32 v134, s4, v53
	v_cvt_pk_bf16_f32 v136, v137, v135
	v_ashrrev_i32_e32 v135, 31, v134
	v_lshlrev_b64 v[134:135], 12, v[134:135]
	v_lshl_add_u64 v[134:135], s[62:63], 0, v[134:135]
	v_lshl_add_u64 v[134:135], v[134:135], 0, s[8:9]
	v_lshl_add_u64 v[134:135], v[134:135], 0, v[32:33]
	global_store_dword v[134:135], v136, off
	ds_read2_b32 v[134:135], v52 offset0:16 offset1:24
	ds_read2_b32 v[136:137], v52 offset0:81 offset1:89
	v_add_u32_e32 v138, s4, v54
	v_ashrrev_i32_e32 v139, 31, v138
	v_lshlrev_b64 v[138:139], 12, v[138:139]
	v_lshl_add_u64 v[138:139], s[62:63], 0, v[138:139]
	v_lshl_add_u64 v[138:139], v[138:139], 0, s[8:9]
	s_waitcnt lgkmcnt(0)
	v_cvt_pk_bf16_f32 v134, v134, v136
	v_lshl_add_u64 v[138:139], v[138:139], 0, v[32:33]
	global_store_dword v[138:139], v134, off
	v_add_u32_e32 v134, s4, v55
	v_cvt_pk_bf16_f32 v136, v135, v137
	v_ashrrev_i32_e32 v135, 31, v134
	v_lshlrev_b64 v[134:135], 12, v[134:135]
	v_lshl_add_u64 v[134:135], s[62:63], 0, v[134:135]
	v_lshl_add_u64 v[134:135], v[134:135], 0, s[8:9]
	v_lshl_add_u64 v[134:135], v[134:135], 0, v[32:33]
	global_store_dword v[134:135], v136, off
	ds_read2_b32 v[134:135], v52 offset0:32 offset1:40
	ds_read2_b32 v[136:137], v52 offset0:97 offset1:105
	v_add_u32_e32 v138, s4, v56
	v_ashrrev_i32_e32 v139, 31, v138
	v_lshlrev_b64 v[138:139], 12, v[138:139]
	v_lshl_add_u64 v[138:139], s[62:63], 0, v[138:139]
	v_lshl_add_u64 v[138:139], v[138:139], 0, s[8:9]
	s_waitcnt lgkmcnt(0)
; DEVI unsigned pk_bf16(float lo, float hi) { unsigned r; asm("v_cvt_pk_bf16_f32 %0, %1, %2" : "=v"(r) : "v"(lo), "v"(hi)); return r; }
; DEVI void cvt_job(LAS float* tile, const float* src, int srcK, int srcN, bf16_t* dst, int dstLd, int dstRows, int dstCol0, int mode, const float* gk = nullptr) {
;     ...
;         for (int i = 0; i < 16; ++i) { const int k = kap0 + ty + 8 * i - dstCol0; regs[i] = (nok && k >= 0 && k < srcK) ? raw[i] * gs[i] : 0.f; }
;     };
;     auto emit = [&](int t, float (&regs)[16]) {
; #pragma unroll
;         for (int i = 0; i < 16; ++i) tile[(ty + 8 * i) * 65 + tx] = regs[i];
;         __syncthreads();
;         int rho0, kap0, n0; coords(t, rho0, kap0, n0);
;         const int tn = t + 2 * gridDim.x;
;         if (tn < ntot) gl(tn, regs);
; #pragma unroll
;         for (int i = 0; i < 8; ++i) { const int row = ty + 8 * i;
;             const float lo = tile[(2 * tx) * 65 + row], hi = tile[(2 * tx + 1) * 65 + row];
;             *(unsigned*)(dst + (size_t)(rho0 + row) * dstLd + kap0 + 2 * tx) = pk_bf16(lo, hi); }
	v_cvt_pk_bf16_f32 v134, v134, v136
	v_lshl_add_u64 v[138:139], v[138:139], 0, v[32:33]
	global_store_dword v[138:139], v134, off
	v_add_u32_e32 v134, s4, v57
	v_cvt_pk_bf16_f32 v136, v135, v137
	v_ashrrev_i32_e32 v135, 31, v134
	v_lshlrev_b64 v[134:135], 12, v[134:135]
	v_lshl_add_u64 v[134:135], s[62:63], 0, v[134:135]
	v_lshl_add_u64 v[134:135], v[134:135], 0, s[8:9]
	v_lshl_add_u64 v[134:135], v[134:135], 0, v[32:33]
	global_store_dword v[134:135], v136, off
	ds_read2_b32 v[134:135], v52 offset0:48 offset1:56
	ds_read2_b32 v[136:137], v52 offset0:113 offset1:121
	v_add_u32_e32 v138, s4, v58
	v_ashrrev_i32_e32 v139, 31, v138
	v_lshlrev_b64 v[138:139], 12, v[138:139]
	v_lshl_add_u64 v[138:139], s[62:63], 0, v[138:139]
	v_lshl_add_u64 v[138:139], v[138:139], 0, s[8:9]
	s_waitcnt lgkmcnt(0)
	v_cvt_pk_bf16_f32 v134, v134, v136
	v_lshl_add_u64 v[138:139], v[138:139], 0, v[32:33]
	global_store_dword v[138:139], v134, off
	v_add_u32_e32 v134, s4, v59
	v_cvt_pk_bf16_f32 v136, v135, v137
	v_ashrrev_i32_e32 v135, 31, v134
	v_lshlrev_b64 v[134:135], 12, v[134:135]
	v_lshl_add_u64 v[134:135], s[62:63], 0, v[134:135]
	v_lshl_add_u64 v[134:135], v[134:135], 0, s[8:9]
	v_lshl_add_u64 v[134:135], v[134:135], 0, v[32:33]
	global_store_dword v[134:135], v136, off
	v_cmp_gt_i32_e32 vcc, s11, v63
	v_cmp_gt_u32_e64 s[36:37], s12, v62
	s_waitcnt vmcnt(23)
	v_mul_f32_e32 v16, v65, v16
	s_and_b64 s[36:37], s[36:37], vcc
	v_cndmask_b32_e64 v16, 0, v16, s[36:37]
	v_cmp_gt_u32_e64 s[36:37], s12, v64
	s_waitcnt vmcnt(22)
	v_mul_f32_e32 v17, v67, v17
	s_and_b64 s[36:37], s[36:37], vcc
	v_cndmask_b32_e64 v17, 0, v17, s[36:37]
	v_cmp_gt_u32_e64 s[36:37], s12, v66
	s_waitcnt vmcnt(21)
	v_mul_f32_e32 v18, v69, v18
	s_and_b64 s[36:37], s[36:37], vcc
	v_cndmask_b32_e64 v18, 0, v18, s[36:37]
	v_cmp_gt_u32_e64 s[36:37], s12, v68
	s_waitcnt vmcnt(20)
	v_mul_f32_e32 v19, v71, v19
	s_and_b64 s[36:37], s[36:37], vcc
	v_cndmask_b32_e64 v19, 0, v19, s[36:37]
	v_cmp_gt_u32_e64 s[36:37], s12, v70
	s_waitcnt vmcnt(19)
	v_mul_f32_e32 v20, v73, v20
	s_and_b64 s[36:37], s[36:37], vcc
	v_cndmask_b32_e64 v20, 0, v20, s[36:37]
	v_cmp_gt_u32_e64 s[36:37], s12, v72
	s_waitcnt vmcnt(18)
	v_mul_f32_e32 v21, v75, v21
	s_and_b64 s[36:37], s[36:37], vcc
	v_cndmask_b32_e64 v21, 0, v21, s[36:37]
	v_cmp_gt_u32_e64 s[36:37], s12, v74
	s_waitcnt vmcnt(17)
	v_mul_f32_e32 v22, v77, v22
	s_and_b64 s[36:37], s[36:37], vcc
	v_cndmask_b32_e64 v22, 0, v22, s[36:37]
	v_cmp_gt_u32_e64 s[36:37], s12, v76
	s_waitcnt vmcnt(16)
	v_mul_f32_e32 v23, v80, v23
	s_and_b64 s[36:37], s[36:37], vcc
	v_cndmask_b32_e64 v23, 0, v23, s[36:37]
	v_cmp_gt_u32_e64 s[36:37], s12, v78
	s_waitcnt vmcnt(15)
	v_mul_f32_e32 v24, v81, v24
	s_and_b64 s[36:37], s[36:37], vcc
	v_cndmask_b32_e64 v24, 0, v24, s[36:37]
	v_cmp_gt_u32_e64 s[36:37], s12, v79
	s_waitcnt vmcnt(14)
	v_mul_f32_e32 v25, v83, v25
	s_and_b64 s[36:37], s[36:37], vcc
	v_cndmask_b32_e64 v25, 0, v25, s[36:37]
	v_cmp_gt_u32_e64 s[36:37], s12, v82
	s_waitcnt vmcnt(13)
	v_mul_f32_e32 v26, v85, v26
	s_and_b64 s[36:37], s[36:37], vcc
	v_cndmask_b32_e64 v26, 0, v26, s[36:37]
	v_cmp_gt_u32_e64 s[36:37], s12, v84
	s_waitcnt vmcnt(12)
	v_mul_f32_e32 v27, v87, v27
	s_and_b64 s[36:37], s[36:37], vcc
	v_cndmask_b32_e64 v27, 0, v27, s[36:37]
	v_cmp_gt_u32_e64 s[36:37], s12, v86
	s_waitcnt vmcnt(11)
	v_mul_f32_e32 v28, v89, v28
	s_and_b64 s[36:37], s[36:37], vcc
	v_cndmask_b32_e64 v28, 0, v28, s[36:37]
	v_cmp_gt_u32_e64 s[36:37], s12, v88
	s_waitcnt vmcnt(10)
	v_mul_f32_e32 v29, v91, v29
	s_and_b64 s[36:37], s[36:37], vcc
	v_cndmask_b32_e64 v29, 0, v29, s[36:37]
	v_cmp_gt_u32_e64 s[36:37], s12, v90
	s_waitcnt vmcnt(9)
	v_mul_f32_e32 v30, v93, v30
	s_and_b64 s[36:37], s[36:37], vcc
	v_cndmask_b32_e64 v30, 0, v30, s[36:37]
	v_cmp_gt_u32_e64 s[36:37], s12, v92
	s_waitcnt vmcnt(8)
	v_mul_f32_e32 v31, v94, v31
	s_and_b64 vcc, s[36:37], vcc
	v_cndmask_b32_e32 v31, 0, v31, vcc
	s_barrier

; DEVI unsigned pk_bf16(float lo, float hi) { unsigned r; asm("v_cvt_pk_bf16_f32 %0, %1, %2" : "=v"(r) : "v"(lo), "v"(hi)); return r; }
; DEVI void cvt_job(LAS float* tile, const float* src, int srcK, int srcN, bf16_t* dst, int dstLd, int dstRows, int dstCol0, int mode, const float* gk = nullptr) {
;     ...
;     auto emit = [&](int t, float (&regs)[16]) {
; #pragma unroll
;         for (int i = 0; i < 16; ++i) tile[(ty + 8 * i) * 65 + tx] = regs[i];
;         __syncthreads();
;         int rho0, kap0, n0; coords(t, rho0, kap0, n0);
;         const int tn = t + 2 * gridDim.x;
;         if (tn < ntot) gl(tn, regs);
; #pragma unroll
;         for (int i = 0; i < 8; ++i) { const int row = ty + 8 * i;
;             const float lo = tile[(2 * tx) * 65 + row], hi = tile[(2 * tx + 1) * 65 + row];
;             *(unsigned*)(dst + (size_t)(rho0 + row) * dstLd + kap0 + 2 * tx) = pk_bf16(lo, hi); }
;         __syncthreads();
.LBB0_1554:
.LBB0_1555:
	s_mul_hi_i32 s8, s4, 0x2e8ba2e9
	s_lshr_b32 s9, s8, 31
	s_ashr_i32 s8, s8, 4
	s_add_i32 s8, s8, s9
	s_mul_i32 s9, s8, 0x3ffff50
	s_add_i32 s9, s7, s9
	s_and_b32 s9, s9, 0x3fffffc
	s_or_b32 s9, s9, s6
	s_lshl_b32 s14, s9, 6
	s_bitset1_b32 s14, 7
	ds_read2_b32 v[34:35], v52 offset0:65 offset1:73
	ds_read2_b32 v[36:37], v52 offset1:8
	v_add_u32_e32 v38, s14, v51
	s_lshl_b32 s8, s8, 7
	v_ashrrev_i32_e32 v39, 31, v38
	s_ashr_i32 s9, s8, 31
	v_lshlrev_b64 v[38:39], 12, v[38:39]
	v_lshl_add_u64 v[38:39], s[62:63], 0, v[38:39]
	s_lshl_b64 s[8:9], s[8:9], 1
	v_lshl_add_u64 v[38:39], v[38:39], 0, s[8:9]
	s_waitcnt lgkmcnt(0)
	v_cvt_pk_bf16_f32 v34, v36, v34
	v_lshl_add_u64 v[38:39], v[38:39], 0, v[32:33]
	global_store_dword v[38:39], v34, off
	v_add_u32_e32 v34, s14, v53
	v_cvt_pk_bf16_f32 v36, v37, v35
	v_ashrrev_i32_e32 v35, 31, v34
	v_lshlrev_b64 v[34:35], 12, v[34:35]
	v_lshl_add_u64 v[34:35], s[62:63], 0, v[34:35]
	v_lshl_add_u64 v[34:35], v[34:35], 0, s[8:9]
	v_lshl_add_u64 v[34:35], v[34:35], 0, v[32:33]
	global_store_dword v[34:35], v36, off
	ds_read2_b32 v[34:35], v52 offset0:16 offset1:24
	ds_read2_b32 v[36:37], v52 offset0:81 offset1:89
	v_add_u32_e32 v38, s14, v54
	v_ashrrev_i32_e32 v39, 31, v38
	v_lshlrev_b64 v[38:39], 12, v[38:39]
	v_lshl_add_u64 v[38:39], s[62:63], 0, v[38:39]
	v_lshl_add_u64 v[38:39], v[38:39], 0, s[8:9]
	s_waitcnt lgkmcnt(0)
	v_cvt_pk_bf16_f32 v34, v34, v36
	v_lshl_add_u64 v[38:39], v[38:39], 0, v[32:33]
	global_store_dword v[38:39], v34, off
	v_add_u32_e32 v34, s14, v55
	v_cvt_pk_bf16_f32 v36, v35, v37
	v_ashrrev_i32_e32 v35, 31, v34
	v_lshlrev_b64 v[34:35], 12, v[34:35]
	v_lshl_add_u64 v[34:35], s[62:63], 0, v[34:35]
	v_lshl_add_u64 v[34:35], v[34:35], 0, s[8:9]
	v_lshl_add_u64 v[34:35], v[34:35], 0, v[32:33]
	global_store_dword v[34:35], v36, off
	ds_read2_b32 v[34:35], v52 offset0:32 offset1:40
	ds_read2_b32 v[36:37], v52 offset0:97 offset1:105
	v_add_u32_e32 v38, s14, v56
	v_ashrrev_i32_e32 v39, 31, v38
	v_lshlrev_b64 v[38:39], 12, v[38:39]
	v_lshl_add_u64 v[38:39], s[62:63], 0, v[38:39]
	v_lshl_add_u64 v[38:39], v[38:39], 0, s[8:9]
	s_waitcnt lgkmcnt(0)
	v_cvt_pk_bf16_f32 v34, v34, v36
	v_lshl_add_u64 v[38:39], v[38:39], 0, v[32:33]
	global_store_dword v[38:39], v34, off
	v_add_u32_e32 v34, s14, v57
	v_cvt_pk_bf16_f32 v36, v35, v37
	v_ashrrev_i32_e32 v35, 31, v34
	v_lshlrev_b64 v[34:35], 12, v[34:35]
	v_lshl_add_u64 v[34:35], s[62:63], 0, v[34:35]
	v_lshl_add_u64 v[34:35], v[34:35], 0, s[8:9]
	v_lshl_add_u64 v[34:35], v[34:35], 0, v[32:33]
	global_store_dword v[34:35], v36, off
	ds_read2_b32 v[34:35], v52 offset0:48 offset1:56
	ds_read2_b32 v[36:37], v52 offset0:113 offset1:121
	v_add_u32_e32 v38, s14, v58
	v_ashrrev_i32_e32 v39, 31, v38
	v_lshlrev_b64 v[38:39], 12, v[38:39]
	v_lshl_add_u64 v[38:39], s[62:63], 0, v[38:39]
	v_lshl_add_u64 v[38:39], v[38:39], 0, s[8:9]
	s_waitcnt lgkmcnt(0)
	v_cvt_pk_bf16_f32 v34, v34, v36
	v_lshl_add_u64 v[38:39], v[38:39], 0, v[32:33]
	global_store_dword v[38:39], v34, off
	v_add_u32_e32 v34, s14, v59
	v_cvt_pk_bf16_f32 v36, v35, v37
	v_ashrrev_i32_e32 v35, 31, v34
	v_lshlrev_b64 v[34:35], 12, v[34:35]
	v_lshl_add_u64 v[34:35], s[62:63], 0, v[34:35]
	v_lshl_add_u64 v[34:35], v[34:35], 0, s[8:9]
	s_add_i32 s8, s33, s4
	v_lshl_add_u64 v[34:35], v[34:35], 0, v[32:33]
	s_cmpk_gt_i32 s8, 0x57f
	global_store_dword v[34:35], v36, off
	s_barrier
	s_cbranch_scc1 .LBB0_1549
	s_add_i32 s4, s18, s4
	s_cmpk_gt_i32 s4, 0x57f
	ds_write_b32 v60, v16
	ds_write_b32 v60, v17 offset:2080
	ds_write_b32 v60, v18 offset:4160
	ds_write_b32 v60, v19 offset:6240
	ds_write_b32 v60, v20 offset:8320
	ds_write_b32 v60, v21 offset:10400
	ds_write_b32 v60, v22 offset:12480
	ds_write_b32 v60, v23 offset:14560
	ds_write_b32 v60, v24 offset:16640
	ds_write_b32 v60, v25 offset:18720
	ds_write_b32 v60, v26 offset:20800
	ds_write_b32 v60, v27 offset:22880
	ds_write_b32 v60, v28 offset:24960
	ds_write_b32 v60, v29 offset:27040
	ds_write_b32 v60, v30 offset:29120
	ds_write_b32 v60, v31 offset:31200
	s_waitcnt lgkmcnt(0)
	s_barrier
; DEVI void cvt_job(LAS float* tile, const float* src, int srcK, int srcN, bf16_t* dst, int dstLd, int dstRows, int dstCol0, int mode, const float* gk = nullptr) {
;     ...
;     auto coords = [&](int t, int& rho0, int& kap0, int& n0) {
;         const int tc = t / nvr, v = t - tc * nvr; kap0 = tc << 7;
;         if (mode) { const int tr = ((v >> 1) << 2) + (mode == 2 ? 2 : 0) + (v & 1); rho0 = tr << 6; n0 = ((rho0 >> 8) << 7) + (rho0 & 127); }
;         else { rho0 = v << 6; n0 = rho0; }
;     };
;     auto gl = [&](int t, float (&regs)[16]) {
;         int rho0, kap0, n0; coords(t, rho0, kap0, n0);
;         const int n = n0 + tx, nc = n < srcN ? n : srcN - 1;
;         const bool nok = n < srcN;
;         float raw[16], gs[16];
; #pragma unroll
;         for (int i = 0; i < 16; ++i) { const int k = kap0 + ty + 8 * i - dstCol0; const int kc = k < 0 ? 0 : (k < srcK ? k : srcK - 1);
;             raw[i] = __builtin_nontemporal_load(src + (size_t)kc * srcN + nc); }
;         if (gk) {
; #pragma unroll
;             for (int i = 0; i < 16; ++i) { const int k = kap0 + ty + 8 * i - dstCol0; const int kc = k < 0 ? 0 : (k < srcK ? k : srcK - 1); gs[i] = gk[kc]; }
;         } else {
; #pragma unroll
;             for (int i = 0; i < 16; ++i) gs[i] = 1.0f;
	s_cbranch_scc1 .Lcvt_stub_6
	s_mul_hi_i32 s4, s4, 0x2e8ba2e9
	s_lshr_b32 s9, s4, 31
	s_ashr_i32 s4, s4, 4
	s_add_i32 s4, s4, s9
	s_mul_i32 s9, s4, 0x3ffff50
	s_add_i32 s14, s96, s7
	s_add_i32 s14, s14, s9
	s_and_b32 s9, s14, 0x3fffffc
	s_or_b32 s9, s9, s5
	s_lshl_b32 s9, s9, 6
	s_ashr_i32 s14, s9, 1
	s_and_b32 s14, s14, 0xffffff80
	s_and_b32 s9, s9, 64
	s_or_b32 s9, s9, s14
	v_or_b32_e32 v63, s9, v50
	v_min_i32_e32 v16, 0x15ff, v63
	v_lshl_add_u32 v62, s4, 7, v51
	v_ashrrev_i32_e32 v17, 31, v16
	v_lshl_add_u64 v[94:95], v[16:17], 2, s[0:1]
	v_med3_i32 v16, v62, 0, v61
	v_mad_u64_u32 v[18:19], s[14:15], v16, s10, v[94:95]
	v_add_u32_e32 v64, 8, v62
	global_load_dword v65, v[18:19], off nt
	v_med3_i32 v18, v64, 0, v61
	v_mad_u64_u32 v[20:21], s[14:15], v18, s10, v[94:95]
	v_add_u32_e32 v66, 16, v62
	global_load_dword v67, v[20:21], off nt
	v_med3_i32 v20, v66, 0, v61
	v_mad_u64_u32 v[22:23], s[14:15], v20, s10, v[94:95]
	v_add_u32_e32 v68, 24, v62
	global_load_dword v69, v[22:23], off nt
	v_med3_i32 v22, v68, 0, v61
	v_mad_u64_u32 v[24:25], s[14:15], v22, s10, v[94:95]
	v_add_u32_e32 v70, 32, v62
	global_load_dword v71, v[24:25], off nt
	v_med3_i32 v24, v70, 0, v61
	v_mad_u64_u32 v[26:27], s[14:15], v24, s10, v[94:95]
	v_add_u32_e32 v72, 40, v62
	global_load_dword v73, v[26:27], off nt
	v_med3_i32 v26, v72, 0, v61
	v_mad_u64_u32 v[28:29], s[14:15], v26, s10, v[94:95]
	v_add_u32_e32 v74, 48, v62
	global_load_dword v75, v[28:29], off nt
	v_med3_i32 v28, v74, 0, v61
	v_mad_u64_u32 v[30:31], s[14:15], v28, s10, v[94:95]
	v_add_u32_e32 v76, 56, v62
	global_load_dword v77, v[30:31], off nt
	v_med3_i32 v30, v76, 0, v61
	v_mad_u64_u32 v[34:35], s[14:15], v30, s10, v[94:95]
	v_add_u32_e32 v78, 64, v62
	global_load_dword v80, v[34:35], off nt
	v_med3_i32 v34, v78, 0, v61
	v_mad_u64_u32 v[36:37], s[14:15], v34, s10, v[94:95]
	v_add_u32_e32 v79, 0x48, v62
	global_load_dword v81, v[36:37], off nt
	v_med3_i32 v36, v79, 0, v61
	v_mad_u64_u32 v[38:39], s[14:15], v36, s10, v[94:95]
	v_add_u32_e32 v82, 0x50, v62
	global_load_dword v83, v[38:39], off nt
	v_med3_i32 v38, v82, 0, v61
	v_mad_u64_u32 v[40:41], s[14:15], v38, s10, v[94:95]
	v_add_u32_e32 v84, 0x58, v62
	global_load_dword v85, v[40:41], off nt
	v_med3_i32 v40, v84, 0, v61
	v_mad_u64_u32 v[42:43], s[14:15], v40, s10, v[94:95]
	v_add_u32_e32 v86, 0x60, v62
	global_load_dword v87, v[42:43], off nt
	v_med3_i32 v42, v86, 0, v61
	v_mad_u64_u32 v[44:45], s[14:15], v42, s10, v[94:95]
	v_add_u32_e32 v88, 0x68, v62
	global_load_dword v89, v[44:45], off nt
	v_med3_i32 v44, v88, 0, v61
	v_mad_u64_u32 v[46:47], s[14:15], v44, s10, v[94:95]
	v_add_u32_e32 v90, 0x70, v62
	global_load_dword v91, v[46:47], off nt
	v_med3_i32 v46, v90, 0, v61
	v_mad_u64_u32 v[48:49], s[14:15], v46, s10, v[94:95]
	v_add_u32_e32 v92, 0x78, v62
	global_load_dword v93, v[48:49], off nt
	v_med3_i32 v48, v92, 0, v61
	v_mad_u64_u32 v[94:95], s[14:15], v48, s10, v[94:95]
	global_load_dword v94, v[94:95], off nt
	v_readlane_b32 s14, v240, 48
	v_readlane_b32 s15, v240, 49
	s_and_b64 vcc, exec, s[14:15]
	s_cbranch_vccz .LBB0_1546
	v_mov_b32_e32 v31, 1.0
	v_mov_b32_e32 v30, 1.0
	v_mov_b32_e32 v29, 1.0
	v_mov_b32_e32 v28, 1.0
	v_mov_b32_e32 v27, 1.0
	v_mov_b32_e32 v26, 1.0
	v_mov_b32_e32 v25, 1.0
	v_mov_b32_e32 v24, 1.0
	v_mov_b32_e32 v23, 1.0
	v_mov_b32_e32 v22, 1.0
	v_mov_b32_e32 v21, 1.0
	v_mov_b32_e32 v20, 1.0
	v_mov_b32_e32 v19, 1.0
	v_mov_b32_e32 v18, 1.0
	v_mov_b32_e32 v17, 1.0
	v_mov_b32_e32 v16, 1.0
	s_waitcnt vmcnt(24)
	s_branch .LBB0_1547

; DEVI void cvt_job(LAS float* tile, const float* src, int srcK, int srcN, bf16_t* dst, int dstLd, int dstRows, int dstCol0, int mode, const float* gk = nullptr) {
;     ...
;     auto gl = [&](int t, float (&regs)[16]) {
;         int rho0, kap0, n0; coords(t, rho0, kap0, n0);
;         const int n = n0 + tx, nc = n < srcN ? n : srcN - 1;
;         const bool nok = n < srcN;
;         float raw[16], gs[16];
; #pragma unroll
;         for (int i = 0; i < 16; ++i) { const int k = kap0 + ty + 8 * i - dstCol0; const int kc = k < 0 ? 0 : (k < srcK ? k : srcK - 1);
;             raw[i] = __builtin_nontemporal_load(src + (size_t)kc * srcN + nc); }
;         if (gk) {
; #pragma unroll
;             for (int i = 0; i < 16; ++i) { const int k = kap0 + ty + 8 * i - dstCol0; const int kc = k < 0 ? 0 : (k < srcK ? k : srcK - 1); gs[i] = gk[kc]; }
;         } else {
; #pragma unroll
;             for (int i = 0; i < 16; ++i) gs[i] = 1.0f;
;         }
; #pragma unroll
;         for (int i = 0; i < 16; ++i) { const int k = kap0 + ty + 8 * i - dstCol0; regs[i] = (nok && k >= 0 && k < srcK) ? raw[i] * gs[i] : 0.f; }
;     };
;     auto emit = [&](int t, float (&regs)[16]) {
; #pragma unroll
;         for (int i = 0; i < 16; ++i) tile[(ty + 8 * i) * 65 + tx] = regs[i];
;         __syncthreads();
.LBB0_1799:
	s_add_i32 s13, s4, s30
	s_cmpk_gt_i32 s13, 0x57f
	s_cselect_b64 s[2:3], -1, 0
	s_and_b64 vcc, exec, s[2:3]
	ds_write_b32 v60, v0
	ds_write_b32 v60, v1 offset:2080
	ds_write_b32 v60, v2 offset:4160
	ds_write_b32 v60, v3 offset:6240
	ds_write_b32 v60, v4 offset:8320
	ds_write_b32 v60, v5 offset:10400
	ds_write_b32 v60, v6 offset:12480
	ds_write_b32 v60, v7 offset:14560
	ds_write_b32 v60, v8 offset:16640
	ds_write_b32 v60, v9 offset:18720
	ds_write_b32 v60, v10 offset:20800
	ds_write_b32 v60, v11 offset:22880
	ds_write_b32 v60, v12 offset:24960
	ds_write_b32 v60, v13 offset:27040
	ds_write_b32 v60, v14 offset:29120
	ds_write_b32 v60, v15 offset:31200
	s_waitcnt lgkmcnt(0)
	s_barrier
	s_cbranch_vccnz .LBB0_1804
	s_mul_hi_i32 s8, s13, 0x2e8ba2e9
	s_lshr_b32 s9, s8, 31
	s_ashr_i32 s8, s8, 4
	s_add_i32 s8, s8, s9
	s_mul_i32 s9, s8, 0x3ffff50
	s_add_i32 s14, s48, s7
	s_add_i32 s14, s14, s9
	s_and_b32 s9, s14, 0x3fffffc
	s_or_b32 s9, s9, s6
	s_lshl_b32 s9, s9, 6
	s_ashr_i32 s14, s9, 1
	s_and_b32 s14, s14, 0xffffff80
	s_and_b32 s9, s9, 64
	s_or_b32 s9, s9, s14
	v_or_b32_e32 v203, s9, v50
	v_min_i32_e32 v140, 0x15ff, v203
	v_lshl_add_u32 v202, s8, 7, v51
	v_ashrrev_i32_e32 v141, 31, v140
	v_lshl_add_u64 v[234:235], v[140:141], 2, s[0:1]
	v_med3_i32 v140, v202, 0, v61
	v_mad_u64_u32 v[142:143], s[8:9], v140, s10, v[234:235]
	v_add_u32_e32 v204, 8, v202
	global_load_dword v205, v[142:143], off nt
	v_med3_i32 v142, v204, 0, v61
	v_mad_u64_u32 v[144:145], s[8:9], v142, s10, v[234:235]
	v_add_u32_e32 v206, 16, v202
	global_load_dword v207, v[144:145], off nt
	v_med3_i32 v144, v206, 0, v61
	v_mad_u64_u32 v[146:147], s[8:9], v144, s10, v[234:235]
	v_add_u32_e32 v208, 24, v202
	global_load_dword v209, v[146:147], off nt
	v_med3_i32 v146, v208, 0, v61
	v_mad_u64_u32 v[148:149], s[8:9], v146, s10, v[234:235]
	v_add_u32_e32 v210, 32, v202
	global_load_dword v211, v[148:149], off nt
	v_med3_i32 v148, v210, 0, v61
	v_mad_u64_u32 v[150:151], s[8:9], v148, s10, v[234:235]
	v_add_u32_e32 v212, 40, v202
	global_load_dword v213, v[150:151], off nt
	v_med3_i32 v150, v212, 0, v61
	v_mad_u64_u32 v[152:153], s[8:9], v150, s10, v[234:235]
	v_add_u32_e32 v214, 48, v202
	global_load_dword v215, v[152:153], off nt
	v_med3_i32 v152, v214, 0, v61
	v_mad_u64_u32 v[154:155], s[8:9], v152, s10, v[234:235]
	v_add_u32_e32 v216, 56, v202
	global_load_dword v217, v[154:155], off nt
	v_med3_i32 v154, v216, 0, v61
	v_mad_u64_u32 v[174:175], s[8:9], v154, s10, v[234:235]
	v_add_u32_e32 v218, 64, v202
	global_load_dword v220, v[174:175], off nt
	v_med3_i32 v174, v218, 0, v61
	v_mad_u64_u32 v[176:177], s[8:9], v174, s10, v[234:235]
	v_add_u32_e32 v219, 0x48, v202
	global_load_dword v221, v[176:177], off nt
	v_med3_i32 v176, v219, 0, v61
	v_mad_u64_u32 v[178:179], s[8:9], v176, s10, v[234:235]
	v_add_u32_e32 v222, 0x50, v202
	global_load_dword v223, v[178:179], off nt
	v_med3_i32 v178, v222, 0, v61
	v_mad_u64_u32 v[180:181], s[8:9], v178, s10, v[234:235]
	v_add_u32_e32 v224, 0x58, v202
	global_load_dword v225, v[180:181], off nt
	v_med3_i32 v180, v224, 0, v61
	v_mad_u64_u32 v[182:183], s[8:9], v180, s10, v[234:235]
	v_add_u32_e32 v226, 0x60, v202
	global_load_dword v227, v[182:183], off nt
	v_med3_i32 v182, v226, 0, v61
	v_mad_u64_u32 v[184:185], s[8:9], v182, s10, v[234:235]
	v_add_u32_e32 v228, 0x68, v202
	global_load_dword v229, v[184:185], off nt
	v_med3_i32 v184, v228, 0, v61
	v_mad_u64_u32 v[186:187], s[8:9], v184, s10, v[234:235]
	v_add_u32_e32 v230, 0x70, v202
	global_load_dword v231, v[186:187], off nt
	v_med3_i32 v186, v230, 0, v61
	v_mad_u64_u32 v[188:189], s[8:9], v186, s10, v[234:235]
	v_add_u32_e32 v232, 0x78, v202
	global_load_dword v233, v[188:189], off nt
	v_med3_i32 v188, v232, 0, v61
	v_mad_u64_u32 v[234:235], s[8:9], v188, s10, v[234:235]
	global_load_dword v234, v[234:235], off nt
	s_and_b64 vcc, exec, s[16:17]
	s_cbranch_vccnz .LBB0_1802
	v_mov_b32_e32 v141, v33
	v_mov_b32_e32 v143, v33
	v_mov_b32_e32 v145, v33
	v_mov_b32_e32 v147, v33
	v_mov_b32_e32 v149, v33
	v_mov_b32_e32 v151, v33
	v_mov_b32_e32 v153, v33
	v_mov_b32_e32 v155, v33
	v_mov_b32_e32 v175, v33
	v_mov_b32_e32 v177, v33
	v_mov_b32_e32 v179, v33
	v_mov_b32_e32 v181, v33
	v_lshl_add_u64 v[140:141], v[140:141], 2, s[38:39]
	v_lshl_add_u64 v[142:143], v[142:143], 2, s[38:39]
	v_lshl_add_u64 v[144:145], v[144:145], 2, s[38:39]
	v_lshl_add_u64 v[146:147], v[146:147], 2, s[38:39]
	v_lshl_add_u64 v[148:149], v[148:149], 2, s[38:39]
	v_lshl_add_u64 v[150:151], v[150:151], 2, s[38:39]
	v_lshl_add_u64 v[152:153], v[152:153], 2, s[38:39]
	v_lshl_add_u64 v[154:155], v[154:155], 2, s[38:39]
	v_mov_b32_e32 v183, v33
	v_mov_b32_e32 v185, v33
	v_mov_b32_e32 v187, v33
	v_mov_b32_e32 v189, v33
	global_load_dword v140, v[140:141], off
	s_nop 0
	global_load_dword v141, v[142:143], off
	s_nop 0
	global_load_dword v142, v[144:145], off
	global_load_dword v143, v[146:147], off
	s_nop 0
	global_load_dword v144, v[148:149], off
	global_load_dword v145, v[150:151], off
	global_load_dword v146, v[152:153], off
	global_load_dword v147, v[154:155], off
	v_lshl_add_u64 v[148:149], v[174:175], 2, s[38:39]
	v_lshl_add_u64 v[150:151], v[176:177], 2, s[38:39]
	v_lshl_add_u64 v[152:153], v[178:179], 2, s[38:39]
	v_lshl_add_u64 v[154:155], v[180:181], 2, s[38:39]
	v_lshl_add_u64 v[174:175], v[182:183], 2, s[38:39]
	v_lshl_add_u64 v[176:177], v[184:185], 2, s[38:39]
	v_lshl_add_u64 v[178:179], v[186:187], 2, s[38:39]
	v_lshl_add_u64 v[180:181], v[188:189], 2, s[38:39]
	global_load_dword v148, v[148:149], off
	s_nop 0
	global_load_dword v149, v[150:151], off
	s_nop 0
	global_load_dword v150, v[152:153], off
	global_load_dword v151, v[154:155], off
	s_nop 0
	global_load_dword v152, v[174:175], off
	global_load_dword v153, v[176:177], off
	global_load_dword v154, v[178:179], off
	global_load_dword v155, v[180:181], off
	s_branch .LBB0_1803

; DEVI unsigned pk_bf16(float lo, float hi) { unsigned r; asm("v_cvt_pk_bf16_f32 %0, %1, %2" : "=v"(r) : "v"(lo), "v"(hi)); return r; }
; DEVI void cvt_job(LAS float* tile, const float* src, int srcK, int srcN, bf16_t* dst, int dstLd, int dstRows, int dstCol0, int mode, const float* gk = nullptr) {
;     ...
;     auto emit = [&](int t, float (&regs)[16]) {
; #pragma unroll
;         for (int i = 0; i < 16; ++i) tile[(ty + 8 * i) * 65 + tx] = regs[i];
;         __syncthreads();
;         int rho0, kap0, n0; coords(t, rho0, kap0, n0);
;         const int tn = t + 2 * gridDim.x;
;         if (tn < ntot) gl(tn, regs);
; #pragma unroll
;         for (int i = 0; i < 8; ++i) { const int row = ty + 8 * i;
;             const float lo = tile[(2 * tx) * 65 + row], hi = tile[(2 * tx + 1) * 65 + row];
;             *(unsigned*)(dst + (size_t)(rho0 + row) * dstLd + kap0 + 2 * tx) = pk_bf16(lo, hi); }
;         __syncthreads();
.LBB0_1803:
.LBB0_1804:
	s_mul_hi_i32 s8, s4, 0x2e8ba2e9
	s_lshr_b32 s9, s8, 31
	s_ashr_i32 s8, s8, 4
	s_add_i32 s8, s8, s9
	s_mul_i32 s9, s8, 0x3ffff50
	s_add_i32 s9, s7, s9
	s_and_b32 s9, s9, 0x3fffffc
	s_or_b32 s9, s9, s6
	s_lshl_b32 s14, s9, 6
	ds_read2_b32 v[34:35], v52 offset0:65 offset1:73
	ds_read2_b32 v[36:37], v52 offset1:8
	v_add_u32_e32 v38, s14, v51
	s_lshl_b32 s8, s8, 7
	v_ashrrev_i32_e32 v39, 31, v38
	s_ashr_i32 s9, s8, 31
	v_lshlrev_b64 v[38:39], 12, v[38:39]
	v_lshl_add_u64 v[38:39], s[62:63], 0, v[38:39]
	s_lshl_b64 s[8:9], s[8:9], 1
	v_lshl_add_u64 v[38:39], v[38:39], 0, s[8:9]
	s_waitcnt lgkmcnt(0)
	v_cvt_pk_bf16_f32 v34, v36, v34
	v_lshl_add_u64 v[38:39], v[38:39], 0, v[32:33]
	global_store_dword v[38:39], v34, off
	v_add_u32_e32 v34, s14, v53
	v_cvt_pk_bf16_f32 v36, v37, v35
	v_ashrrev_i32_e32 v35, 31, v34
	v_lshlrev_b64 v[34:35], 12, v[34:35]
	v_lshl_add_u64 v[34:35], s[62:63], 0, v[34:35]
	v_lshl_add_u64 v[34:35], v[34:35], 0, s[8:9]
	v_lshl_add_u64 v[34:35], v[34:35], 0, v[32:33]
	global_store_dword v[34:35], v36, off
	ds_read2_b32 v[34:35], v52 offset0:16 offset1:24
	ds_read2_b32 v[36:37], v52 offset0:81 offset1:89
	v_add_u32_e32 v38, s14, v54
	v_ashrrev_i32_e32 v39, 31, v38
	v_lshlrev_b64 v[38:39], 12, v[38:39]
	v_lshl_add_u64 v[38:39], s[62:63], 0, v[38:39]
	v_lshl_add_u64 v[38:39], v[38:39], 0, s[8:9]
	s_waitcnt lgkmcnt(0)
	v_cvt_pk_bf16_f32 v34, v34, v36
	v_lshl_add_u64 v[38:39], v[38:39], 0, v[32:33]
	global_store_dword v[38:39], v34, off
	v_add_u32_e32 v34, s14, v55
	v_cvt_pk_bf16_f32 v36, v35, v37
	v_ashrrev_i32_e32 v35, 31, v34
	v_lshlrev_b64 v[34:35], 12, v[34:35]
	v_lshl_add_u64 v[34:35], s[62:63], 0, v[34:35]
	v_lshl_add_u64 v[34:35], v[34:35], 0, s[8:9]
	v_lshl_add_u64 v[34:35], v[34:35], 0, v[32:33]
	global_store_dword v[34:35], v36, off
	ds_read2_b32 v[34:35], v52 offset0:32 offset1:40
	ds_read2_b32 v[36:37], v52 offset0:97 offset1:105
	v_add_u32_e32 v38, s14, v56
	v_ashrrev_i32_e32 v39, 31, v38
	v_lshlrev_b64 v[38:39], 12, v[38:39]
	v_lshl_add_u64 v[38:39], s[62:63], 0, v[38:39]
	v_lshl_add_u64 v[38:39], v[38:39], 0, s[8:9]
	s_waitcnt lgkmcnt(0)
	v_cvt_pk_bf16_f32 v34, v34, v36
	v_lshl_add_u64 v[38:39], v[38:39], 0, v[32:33]
	global_store_dword v[38:39], v34, off
	v_add_u32_e32 v34, s14, v57
	v_cvt_pk_bf16_f32 v36, v35, v37
	v_ashrrev_i32_e32 v35, 31, v34
	v_lshlrev_b64 v[34:35], 12, v[34:35]
	v_lshl_add_u64 v[34:35], s[62:63], 0, v[34:35]
	v_lshl_add_u64 v[34:35], v[34:35], 0, s[8:9]
	v_lshl_add_u64 v[34:35], v[34:35], 0, v[32:33]
	global_store_dword v[34:35], v36, off
	ds_read2_b32 v[34:35], v52 offset0:48 offset1:56
	ds_read2_b32 v[36:37], v52 offset0:113 offset1:121
	v_add_u32_e32 v38, s14, v58
	v_ashrrev_i32_e32 v39, 31, v38
	v_lshlrev_b64 v[38:39], 12, v[38:39]
	v_lshl_add_u64 v[38:39], s[62:63], 0, v[38:39]
	v_lshl_add_u64 v[38:39], v[38:39], 0, s[8:9]
	s_waitcnt lgkmcnt(0)
	v_cvt_pk_bf16_f32 v34, v34, v36
	v_lshl_add_u64 v[38:39], v[38:39], 0, v[32:33]
	global_store_dword v[38:39], v34, off
	v_add_u32_e32 v34, s14, v59
	v_cvt_pk_bf16_f32 v36, v35, v37
	v_ashrrev_i32_e32 v35, 31, v34
	v_lshlrev_b64 v[34:35], 12, v[34:35]
	v_lshl_add_u64 v[34:35], s[62:63], 0, v[34:35]
	v_lshl_add_u64 v[34:35], v[34:35], 0, s[8:9]
	s_add_i32 s8, s33, s4
	v_lshl_add_u64 v[34:35], v[34:35], 0, v[32:33]
	s_cmpk_gt_i32 s8, 0x57f
	global_store_dword v[34:35], v36, off
	s_barrier
	s_cbranch_scc1 .LBB0_1798
	s_add_i32 s4, s18, s4
	s_cmpk_gt_i32 s4, 0x57f
	ds_write_b32 v60, v16
	ds_write_b32 v60, v17 offset:2080
	ds_write_b32 v60, v18 offset:4160
	ds_write_b32 v60, v19 offset:6240
	ds_write_b32 v60, v20 offset:8320
	ds_write_b32 v60, v21 offset:10400
	ds_write_b32 v60, v22 offset:12480
	ds_write_b32 v60, v23 offset:14560
	ds_write_b32 v60, v24 offset:16640
	ds_write_b32 v60, v25 offset:18720
	ds_write_b32 v60, v26 offset:20800
	ds_write_b32 v60, v27 offset:22880
	ds_write_b32 v60, v28 offset:24960
	ds_write_b32 v60, v29 offset:27040
	ds_write_b32 v60, v30 offset:29120
	ds_write_b32 v60, v31 offset:31200
	s_waitcnt lgkmcnt(0)
	s_barrier
; DEVI void cvt_job(LAS float* tile, const float* src, int srcK, int srcN, bf16_t* dst, int dstLd, int dstRows, int dstCol0, int mode, const float* gk = nullptr) {
;     ...
;     auto coords = [&](int t, int& rho0, int& kap0, int& n0) {
;         const int tc = t / nvr, v = t - tc * nvr; kap0 = tc << 7;
;         if (mode) { const int tr = ((v >> 1) << 2) + (mode == 2 ? 2 : 0) + (v & 1); rho0 = tr << 6; n0 = ((rho0 >> 8) << 7) + (rho0 & 127); }
;         else { rho0 = v << 6; n0 = rho0; }
;     };
;     auto gl = [&](int t, float (&regs)[16]) {
;         int rho0, kap0, n0; coords(t, rho0, kap0, n0);
;         const int n = n0 + tx, nc = n < srcN ? n : srcN - 1;
;         const bool nok = n < srcN;
;         float raw[16], gs[16];
; #pragma unroll
;         for (int i = 0; i < 16; ++i) { const int k = kap0 + ty + 8 * i - dstCol0; const int kc = k < 0 ? 0 : (k < srcK ? k : srcK - 1);
;             raw[i] = __builtin_nontemporal_load(src + (size_t)kc * srcN + nc); }
;         if (gk) {
; #pragma unroll
;             for (int i = 0; i < 16; ++i) { const int k = kap0 + ty + 8 * i - dstCol0; const int kc = k < 0 ? 0 : (k < srcK ? k : srcK - 1); gs[i] = gk[kc]; }
;         } else {
; #pragma unroll
;             for (int i = 0; i < 16; ++i) gs[i] = 1.0f;
	s_cbranch_scc1 .Lcvt_stub_8
	s_mul_hi_i32 s4, s4, 0x2e8ba2e9
	s_lshr_b32 s9, s4, 31
	s_ashr_i32 s4, s4, 4
	s_add_i32 s4, s4, s9
	s_mul_i32 s9, s4, 0x3ffff50
	s_add_i32 s14, s96, s7
	s_add_i32 s14, s14, s9
	s_and_b32 s9, s14, 0x3fffffc
	s_or_b32 s9, s9, s5
	s_lshl_b32 s9, s9, 6
	s_ashr_i32 s14, s9, 1
	s_and_b32 s14, s14, 0xffffff80
	s_and_b32 s9, s9, 64
	s_or_b32 s9, s9, s14
	v_or_b32_e32 v63, s9, v50
	v_min_i32_e32 v16, 0x15ff, v63
	v_lshl_add_u32 v62, s4, 7, v51
	v_ashrrev_i32_e32 v17, 31, v16
	v_lshl_add_u64 v[94:95], v[16:17], 2, s[0:1]
	v_med3_i32 v16, v62, 0, v61
	v_mad_u64_u32 v[18:19], s[14:15], v16, s10, v[94:95]
	v_add_u32_e32 v64, 8, v62
	global_load_dword v65, v[18:19], off nt
	v_med3_i32 v18, v64, 0, v61
	v_mad_u64_u32 v[20:21], s[14:15], v18, s10, v[94:95]
	v_add_u32_e32 v66, 16, v62
	global_load_dword v67, v[20:21], off nt
	v_med3_i32 v20, v66, 0, v61
	v_mad_u64_u32 v[22:23], s[14:15], v20, s10, v[94:95]
	v_add_u32_e32 v68, 24, v62
	global_load_dword v69, v[22:23], off nt
	v_med3_i32 v22, v68, 0, v61
	v_mad_u64_u32 v[24:25], s[14:15], v22, s10, v[94:95]
	v_add_u32_e32 v70, 32, v62
	global_load_dword v71, v[24:25], off nt
	v_med3_i32 v24, v70, 0, v61
	v_mad_u64_u32 v[26:27], s[14:15], v24, s10, v[94:95]
	v_add_u32_e32 v72, 40, v62
	global_load_dword v73, v[26:27], off nt
	v_med3_i32 v26, v72, 0, v61
	v_mad_u64_u32 v[28:29], s[14:15], v26, s10, v[94:95]
	v_add_u32_e32 v74, 48, v62
	global_load_dword v75, v[28:29], off nt
	v_med3_i32 v28, v74, 0, v61
	v_mad_u64_u32 v[30:31], s[14:15], v28, s10, v[94:95]
	v_add_u32_e32 v76, 56, v62
	global_load_dword v77, v[30:31], off nt
	v_med3_i32 v30, v76, 0, v61
	v_mad_u64_u32 v[34:35], s[14:15], v30, s10, v[94:95]
	v_add_u32_e32 v78, 64, v62
	global_load_dword v80, v[34:35], off nt
	v_med3_i32 v34, v78, 0, v61
	v_mad_u64_u32 v[36:37], s[14:15], v34, s10, v[94:95]
	v_add_u32_e32 v79, 0x48, v62
	global_load_dword v81, v[36:37], off nt
	v_med3_i32 v36, v79, 0, v61
	v_mad_u64_u32 v[38:39], s[14:15], v36, s10, v[94:95]
	v_add_u32_e32 v82, 0x50, v62
	global_load_dword v83, v[38:39], off nt
	v_med3_i32 v38, v82, 0, v61
	v_mad_u64_u32 v[40:41], s[14:15], v38, s10, v[94:95]
	v_add_u32_e32 v84, 0x58, v62
	global_load_dword v85, v[40:41], off nt
	v_med3_i32 v40, v84, 0, v61
	v_mad_u64_u32 v[42:43], s[14:15], v40, s10, v[94:95]
	v_add_u32_e32 v86, 0x60, v62
	global_load_dword v87, v[42:43], off nt
	v_med3_i32 v42, v86, 0, v61
	v_mad_u64_u32 v[44:45], s[14:15], v42, s10, v[94:95]
	v_add_u32_e32 v88, 0x68, v62
	global_load_dword v89, v[44:45], off nt
	v_med3_i32 v44, v88, 0, v61
	v_mad_u64_u32 v[46:47], s[14:15], v44, s10, v[94:95]
	v_add_u32_e32 v90, 0x70, v62
	global_load_dword v91, v[46:47], off nt
	v_med3_i32 v46, v90, 0, v61
	v_mad_u64_u32 v[48:49], s[14:15], v46, s10, v[94:95]
	v_add_u32_e32 v92, 0x78, v62
	global_load_dword v93, v[48:49], off nt
	v_med3_i32 v48, v92, 0, v61
	v_mad_u64_u32 v[94:95], s[14:15], v48, s10, v[94:95]
	global_load_dword v94, v[94:95], off nt
	s_and_b64 vcc, exec, s[16:17]
	s_cbranch_vccz .LBB0_1795
	v_mov_b32_e32 v31, 1.0
	v_mov_b32_e32 v30, 1.0
	v_mov_b32_e32 v29, 1.0
	v_mov_b32_e32 v28, 1.0
	v_mov_b32_e32 v27, 1.0
	v_mov_b32_e32 v26, 1.0
	v_mov_b32_e32 v25, 1.0
	v_mov_b32_e32 v24, 1.0
	v_mov_b32_e32 v23, 1.0
	v_mov_b32_e32 v22, 1.0
	v_mov_b32_e32 v21, 1.0
	v_mov_b32_e32 v20, 1.0
	v_mov_b32_e32 v19, 1.0
	v_mov_b32_e32 v18, 1.0
	v_mov_b32_e32 v17, 1.0
	v_mov_b32_e32 v16, 1.0
	s_waitcnt vmcnt(24)
	s_branch .LBB0_1796

; DEVI unsigned pk_bf16(float lo, float hi) { unsigned r; asm("v_cvt_pk_bf16_f32 %0, %1, %2" : "=v"(r) : "v"(lo), "v"(hi)); return r; }
; DEVI void cvt_job(LAS float* tile, const float* src, int srcK, int srcN, bf16_t* dst, int dstLd, int dstRows, int dstCol0, int mode, const float* gk = nullptr) {
;     ...
;     auto emit = [&](int t, float (&regs)[16]) {
; #pragma unroll
;         for (int i = 0; i < 16; ++i) tile[(ty + 8 * i) * 65 + tx] = regs[i];
;         __syncthreads();
;         int rho0, kap0, n0; coords(t, rho0, kap0, n0);
;         const int tn = t + 2 * gridDim.x;
;         if (tn < ntot) gl(tn, regs);
; #pragma unroll
;         for (int i = 0; i < 8; ++i) { const int row = ty + 8 * i;
;             const float lo = tile[(2 * tx) * 65 + row], hi = tile[(2 * tx + 1) * 65 + row];
;             *(unsigned*)(dst + (size_t)(rho0 + row) * dstLd + kap0 + 2 * tx) = pk_bf16(lo, hi); }
;         __syncthreads();
.LBB0_1828:
.LBB0_1829:
	s_mul_hi_i32 s8, s4, 0x2e8ba2e9
	s_lshr_b32 s9, s8, 31
	s_ashr_i32 s8, s8, 4
	s_add_i32 s8, s8, s9
	s_mul_i32 s9, s8, 0x3ffff50
	s_add_i32 s9, s7, s9
	s_and_b32 s9, s9, 0x3fffffc
	s_or_b32 s9, s9, s6
	s_lshl_b32 s14, s9, 6
	s_bitset1_b32 s14, 7
	ds_read2_b32 v[34:35], v52 offset0:65 offset1:73
	ds_read2_b32 v[36:37], v52 offset1:8
	v_add_u32_e32 v38, s14, v51
	s_lshl_b32 s8, s8, 7
	v_ashrrev_i32_e32 v39, 31, v38
	s_ashr_i32 s9, s8, 31
	v_lshlrev_b64 v[38:39], 12, v[38:39]
	v_lshl_add_u64 v[38:39], s[62:63], 0, v[38:39]
	s_lshl_b64 s[8:9], s[8:9], 1
	v_lshl_add_u64 v[38:39], v[38:39], 0, s[8:9]
	s_waitcnt lgkmcnt(0)
	v_cvt_pk_bf16_f32 v34, v36, v34
	v_lshl_add_u64 v[38:39], v[38:39], 0, v[32:33]
	global_store_dword v[38:39], v34, off
	v_add_u32_e32 v34, s14, v53
	v_cvt_pk_bf16_f32 v36, v37, v35
	v_ashrrev_i32_e32 v35, 31, v34
	v_lshlrev_b64 v[34:35], 12, v[34:35]
	v_lshl_add_u64 v[34:35], s[62:63], 0, v[34:35]
	v_lshl_add_u64 v[34:35], v[34:35], 0, s[8:9]
	v_lshl_add_u64 v[34:35], v[34:35], 0, v[32:33]
	global_store_dword v[34:35], v36, off
	ds_read2_b32 v[34:35], v52 offset0:16 offset1:24
	ds_read2_b32 v[36:37], v52 offset0:81 offset1:89
	v_add_u32_e32 v38, s14, v54
	v_ashrrev_i32_e32 v39, 31, v38
	v_lshlrev_b64 v[38:39], 12, v[38:39]
	v_lshl_add_u64 v[38:39], s[62:63], 0, v[38:39]
	v_lshl_add_u64 v[38:39], v[38:39], 0, s[8:9]
	s_waitcnt lgkmcnt(0)
	v_cvt_pk_bf16_f32 v34, v34, v36
	v_lshl_add_u64 v[38:39], v[38:39], 0, v[32:33]
	global_store_dword v[38:39], v34, off
	v_add_u32_e32 v34, s14, v55
	v_cvt_pk_bf16_f32 v36, v35, v37
	v_ashrrev_i32_e32 v35, 31, v34
	v_lshlrev_b64 v[34:35], 12, v[34:35]
	v_lshl_add_u64 v[34:35], s[62:63], 0, v[34:35]
	v_lshl_add_u64 v[34:35], v[34:35], 0, s[8:9]
	v_lshl_add_u64 v[34:35], v[34:35], 0, v[32:33]
	global_store_dword v[34:35], v36, off
	ds_read2_b32 v[34:35], v52 offset0:32 offset1:40
	ds_read2_b32 v[36:37], v52 offset0:97 offset1:105
	v_add_u32_e32 v38, s14, v56
	v_ashrrev_i32_e32 v39, 31, v38
	v_lshlrev_b64 v[38:39], 12, v[38:39]
	v_lshl_add_u64 v[38:39], s[62:63], 0, v[38:39]
	v_lshl_add_u64 v[38:39], v[38:39], 0, s[8:9]
	s_waitcnt lgkmcnt(0)
	v_cvt_pk_bf16_f32 v34, v34, v36
	v_lshl_add_u64 v[38:39], v[38:39], 0, v[32:33]
	global_store_dword v[38:39], v34, off
	v_add_u32_e32 v34, s14, v57
	v_cvt_pk_bf16_f32 v36, v35, v37
	v_ashrrev_i32_e32 v35, 31, v34
	v_lshlrev_b64 v[34:35], 12, v[34:35]
	v_lshl_add_u64 v[34:35], s[62:63], 0, v[34:35]
	v_lshl_add_u64 v[34:35], v[34:35], 0, s[8:9]
	v_lshl_add_u64 v[34:35], v[34:35], 0, v[32:33]
	global_store_dword v[34:35], v36, off
	ds_read2_b32 v[34:35], v52 offset0:48 offset1:56
	ds_read2_b32 v[36:37], v52 offset0:113 offset1:121
	v_add_u32_e32 v38, s14, v58
	v_ashrrev_i32_e32 v39, 31, v38
	v_lshlrev_b64 v[38:39], 12, v[38:39]
	v_lshl_add_u64 v[38:39], s[62:63], 0, v[38:39]
	v_lshl_add_u64 v[38:39], v[38:39], 0, s[8:9]
	s_waitcnt lgkmcnt(0)
	v_cvt_pk_bf16_f32 v34, v34, v36
	v_lshl_add_u64 v[38:39], v[38:39], 0, v[32:33]
	global_store_dword v[38:39], v34, off
	v_add_u32_e32 v34, s14, v59
	v_cvt_pk_bf16_f32 v36, v35, v37
	v_ashrrev_i32_e32 v35, 31, v34
	v_lshlrev_b64 v[34:35], 12, v[34:35]
	v_lshl_add_u64 v[34:35], s[62:63], 0, v[34:35]
	v_lshl_add_u64 v[34:35], v[34:35], 0, s[8:9]
	s_add_i32 s8, s33, s4
	v_lshl_add_u64 v[34:35], v[34:35], 0, v[32:33]
	s_cmpk_gt_i32 s8, 0x57f
	global_store_dword v[34:35], v36, off
	s_barrier
	s_cbranch_scc1 .LBB0_1823
	s_add_i32 s4, s18, s4
	s_cmpk_gt_i32 s4, 0x57f
	ds_write_b32 v60, v16
	ds_write_b32 v60, v17 offset:2080
	ds_write_b32 v60, v18 offset:4160
	ds_write_b32 v60, v19 offset:6240
	ds_write_b32 v60, v20 offset:8320
	ds_write_b32 v60, v21 offset:10400
	ds_write_b32 v60, v22 offset:12480
	ds_write_b32 v60, v23 offset:14560
	ds_write_b32 v60, v24 offset:16640
	ds_write_b32 v60, v25 offset:18720
	ds_write_b32 v60, v26 offset:20800
	ds_write_b32 v60, v27 offset:22880
	ds_write_b32 v60, v28 offset:24960
	ds_write_b32 v60, v29 offset:27040
	ds_write_b32 v60, v30 offset:29120
	ds_write_b32 v60, v31 offset:31200
	s_waitcnt lgkmcnt(0)
	s_barrier
; DEVI void cvt_job(LAS float* tile, const float* src, int srcK, int srcN, bf16_t* dst, int dstLd, int dstRows, int dstCol0, int mode, const float* gk = nullptr) {
;     ...
;     auto coords = [&](int t, int& rho0, int& kap0, int& n0) {
;         const int tc = t / nvr, v = t - tc * nvr; kap0 = tc << 7;
;         if (mode) { const int tr = ((v >> 1) << 2) + (mode == 2 ? 2 : 0) + (v & 1); rho0 = tr << 6; n0 = ((rho0 >> 8) << 7) + (rho0 & 127); }
;         else { rho0 = v << 6; n0 = rho0; }
;     };
;     auto gl = [&](int t, float (&regs)[16]) {
;         int rho0, kap0, n0; coords(t, rho0, kap0, n0);
;         const int n = n0 + tx, nc = n < srcN ? n : srcN - 1;
;         const bool nok = n < srcN;
;         float raw[16], gs[16];
; #pragma unroll
;         for (int i = 0; i < 16; ++i) { const int k = kap0 + ty + 8 * i - dstCol0; const int kc = k < 0 ? 0 : (k < srcK ? k : srcK - 1);
;             raw[i] = __builtin_nontemporal_load(src + (size_t)kc * srcN + nc); }
;         if (gk) {
; #pragma unroll
;             for (int i = 0; i < 16; ++i) { const int k = kap0 + ty + 8 * i - dstCol0; const int kc = k < 0 ? 0 : (k < srcK ? k : srcK - 1); gs[i] = gk[kc]; }
;         } else {
; #pragma unroll
;             for (int i = 0; i < 16; ++i) gs[i] = 1.0f;
	s_cbranch_scc1 .Lcvt_stub_9
	s_mul_hi_i32 s4, s4, 0x2e8ba2e9
	s_lshr_b32 s9, s4, 31
	s_ashr_i32 s4, s4, 4
	s_add_i32 s4, s4, s9
	s_mul_i32 s9, s4, 0x3ffff50
	s_add_i32 s14, s96, s7
	s_add_i32 s14, s14, s9
	s_and_b32 s9, s14, 0x3fffffc
	s_or_b32 s9, s9, s5
	s_lshl_b32 s9, s9, 6
	s_ashr_i32 s14, s9, 1
	s_and_b32 s14, s14, 0xffffff80
	s_and_b32 s9, s9, 64
	s_or_b32 s9, s9, s14
	v_or_b32_e32 v63, s9, v50
	v_min_i32_e32 v16, 0x15ff, v63
	v_lshl_add_u32 v62, s4, 7, v51
	v_ashrrev_i32_e32 v17, 31, v16
	v_lshl_add_u64 v[94:95], v[16:17], 2, s[0:1]
	v_med3_i32 v16, v62, 0, v61
	v_mad_u64_u32 v[18:19], s[14:15], v16, s10, v[94:95]
	v_add_u32_e32 v64, 8, v62
	global_load_dword v65, v[18:19], off nt
	v_med3_i32 v18, v64, 0, v61
	v_mad_u64_u32 v[20:21], s[14:15], v18, s10, v[94:95]
	v_add_u32_e32 v66, 16, v62
	global_load_dword v67, v[20:21], off nt
	v_med3_i32 v20, v66, 0, v61
	v_mad_u64_u32 v[22:23], s[14:15], v20, s10, v[94:95]
	v_add_u32_e32 v68, 24, v62
	global_load_dword v69, v[22:23], off nt
	v_med3_i32 v22, v68, 0, v61
	v_mad_u64_u32 v[24:25], s[14:15], v22, s10, v[94:95]
	v_add_u32_e32 v70, 32, v62
	global_load_dword v71, v[24:25], off nt
	v_med3_i32 v24, v70, 0, v61
	v_mad_u64_u32 v[26:27], s[14:15], v24, s10, v[94:95]
	v_add_u32_e32 v72, 40, v62
	global_load_dword v73, v[26:27], off nt
	v_med3_i32 v26, v72, 0, v61
	v_mad_u64_u32 v[28:29], s[14:15], v26, s10, v[94:95]
	v_add_u32_e32 v74, 48, v62
	global_load_dword v75, v[28:29], off nt
	v_med3_i32 v28, v74, 0, v61
	v_mad_u64_u32 v[30:31], s[14:15], v28, s10, v[94:95]
	v_add_u32_e32 v76, 56, v62
	global_load_dword v77, v[30:31], off nt
	v_med3_i32 v30, v76, 0, v61
	v_mad_u64_u32 v[34:35], s[14:15], v30, s10, v[94:95]
	v_add_u32_e32 v78, 64, v62
	global_load_dword v80, v[34:35], off nt
	v_med3_i32 v34, v78, 0, v61
	v_mad_u64_u32 v[36:37], s[14:15], v34, s10, v[94:95]
	v_add_u32_e32 v79, 0x48, v62
	global_load_dword v81, v[36:37], off nt
	v_med3_i32 v36, v79, 0, v61
	v_mad_u64_u32 v[38:39], s[14:15], v36, s10, v[94:95]
	v_add_u32_e32 v82, 0x50, v62
	global_load_dword v83, v[38:39], off nt
	v_med3_i32 v38, v82, 0, v61
	v_mad_u64_u32 v[40:41], s[14:15], v38, s10, v[94:95]
	v_add_u32_e32 v84, 0x58, v62
	global_load_dword v85, v[40:41], off nt
	v_med3_i32 v40, v84, 0, v61
	v_mad_u64_u32 v[42:43], s[14:15], v40, s10, v[94:95]
	v_add_u32_e32 v86, 0x60, v62
	global_load_dword v87, v[42:43], off nt
	v_med3_i32 v42, v86, 0, v61
	v_mad_u64_u32 v[44:45], s[14:15], v42, s10, v[94:95]
	v_add_u32_e32 v88, 0x68, v62
	global_load_dword v89, v[44:45], off nt
	v_med3_i32 v44, v88, 0, v61
	v_mad_u64_u32 v[46:47], s[14:15], v44, s10, v[94:95]
	v_add_u32_e32 v90, 0x70, v62
	global_load_dword v91, v[46:47], off nt
	v_med3_i32 v46, v90, 0, v61
	v_mad_u64_u32 v[48:49], s[14:15], v46, s10, v[94:95]
	v_add_u32_e32 v92, 0x78, v62
	global_load_dword v93, v[48:49], off nt
	v_med3_i32 v48, v92, 0, v61
	v_mad_u64_u32 v[94:95], s[14:15], v48, s10, v[94:95]
	global_load_dword v94, v[94:95], off nt
	s_and_b64 vcc, exec, s[16:17]
	s_cbranch_vccz .LBB0_1820
	v_mov_b32_e32 v31, 1.0
	v_mov_b32_e32 v30, 1.0
	v_mov_b32_e32 v29, 1.0
	v_mov_b32_e32 v28, 1.0
	v_mov_b32_e32 v27, 1.0
	v_mov_b32_e32 v26, 1.0
	v_mov_b32_e32 v25, 1.0
	v_mov_b32_e32 v24, 1.0
	v_mov_b32_e32 v23, 1.0
	v_mov_b32_e32 v22, 1.0
	v_mov_b32_e32 v21, 1.0
	v_mov_b32_e32 v20, 1.0
	v_mov_b32_e32 v19, 1.0
	v_mov_b32_e32 v18, 1.0
	v_mov_b32_e32 v17, 1.0
	v_mov_b32_e32 v16, 1.0
	s_waitcnt vmcnt(24)
	s_branch .LBB0_1821

; DEVI unsigned pk_bf16(float lo, float hi) { unsigned r; asm("v_cvt_pk_bf16_f32 %0, %1, %2" : "=v"(r) : "v"(lo), "v"(hi)); return r; }
; DEVI void cvt_job(LAS float* tile, const float* src, int srcK, int srcN, bf16_t* dst, int dstLd, int dstRows, int dstCol0, int mode, const float* gk = nullptr) {
;     ...
;         for (int i = 0; i < 16; ++i) { const int k = kap0 + ty + 8 * i - dstCol0; regs[i] = (nok && k >= 0 && k < srcK) ? raw[i] * gs[i] : 0.f; }
;     };
;     auto emit = [&](int t, float (&regs)[16]) {
; #pragma unroll
;         for (int i = 0; i < 16; ++i) tile[(ty + 8 * i) * 65 + tx] = regs[i];
;         __syncthreads();
;         int rho0, kap0, n0; coords(t, rho0, kap0, n0);
;         const int tn = t + 2 * gridDim.x;
;         if (tn < ntot) gl(tn, regs);
; #pragma unroll
;         for (int i = 0; i < 8; ++i) { const int row = ty + 8 * i;
;             const float lo = tile[(2 * tx) * 65 + row], hi = tile[(2 * tx + 1) * 65 + row];
;             *(unsigned*)(dst + (size_t)(rho0 + row) * dstLd + kap0 + 2 * tx) = pk_bf16(lo, hi); }
.LBB0_2476:
	v_cmp_gt_i32_e32 vcc, s7, v154
	v_cmp_gt_u32_e64 s[34:35], s10, v155
	s_and_b64 s[34:35], s[34:35], vcc
	v_cndmask_b32_e64 v0, 0, v163, s[34:35]
	v_cmp_gt_u32_e64 s[34:35], s10, v156
	s_and_b64 s[34:35], s[34:35], vcc
	v_cndmask_b32_e64 v1, 0, v164, s[34:35]
	v_cmp_gt_u32_e64 s[34:35], s10, v157
	s_and_b64 s[34:35], s[34:35], vcc
	v_cndmask_b32_e64 v2, 0, v165, s[34:35]
	v_cmp_gt_u32_e64 s[34:35], s10, v158
	s_and_b64 s[34:35], s[34:35], vcc
	v_cndmask_b32_e64 v3, 0, v166, s[34:35]
	v_cmp_gt_u32_e64 s[34:35], s10, v159
	s_and_b64 s[34:35], s[34:35], vcc
	v_cndmask_b32_e64 v4, 0, v167, s[34:35]
	v_cmp_gt_u32_e64 s[34:35], s10, v160
	s_and_b64 s[34:35], s[34:35], vcc
	v_cndmask_b32_e64 v5, 0, v122, s[34:35]
	v_cmp_gt_u32_e64 s[34:35], s10, v161
	s_and_b64 s[34:35], s[34:35], vcc
	v_cndmask_b32_e64 v6, 0, v123, s[34:35]
	v_cmp_gt_u32_e64 s[34:35], s10, v162
	s_and_b64 s[34:35], s[34:35], vcc
	v_cndmask_b32_e64 v7, 0, v124, s[34:35]
	v_cmp_gt_u32_e64 s[34:35], s10, v125
	s_and_b64 s[34:35], s[34:35], vcc
	v_cndmask_b32_e64 v8, 0, v170, s[34:35]
	v_cmp_gt_u32_e64 s[34:35], s10, v152
	s_and_b64 s[34:35], s[34:35], vcc
	v_cndmask_b32_e64 v9, 0, v171, s[34:35]
	v_cmp_gt_u32_e64 s[34:35], s10, v153
	s_and_b64 s[34:35], s[34:35], vcc
	v_cndmask_b32_e64 v10, 0, v172, s[34:35]
	v_cmp_gt_u32_e64 s[34:35], s10, v168
	s_and_b64 s[34:35], s[34:35], vcc
	v_cndmask_b32_e64 v11, 0, v173, s[34:35]
	v_cmp_gt_u32_e64 s[34:35], s10, v169
	s_and_b64 s[34:35], s[34:35], vcc
	v_cndmask_b32_e64 v12, 0, v174, s[34:35]
	v_cmp_gt_u32_e64 s[34:35], s10, v175
	s_and_b64 s[34:35], s[34:35], vcc
	v_cndmask_b32_e64 v13, 0, v177, s[34:35]
	v_cmp_gt_u32_e64 s[34:35], s10, v176
	s_and_b64 s[34:35], s[34:35], vcc
	v_cndmask_b32_e64 v14, 0, v178, s[34:35]
	v_cmp_gt_u32_e64 s[34:35], s10, v179
	s_and_b64 vcc, s[34:35], vcc
	v_cndmask_b32_e32 v15, 0, v180, vcc
	ds_read2_b32 v[142:143], v35 offset0:65 offset1:73
	ds_read2_b32 v[144:145], v35 offset1:8
	s_ashr_i32 s4, s8, 31
	s_lshr_b32 s4, s4, 27
	s_add_i32 s8, s8, s4
	s_ashr_i32 s4, s8, 5
	v_readlane_b32 s14, v238, 59
	s_lshl_b32 s8, s4, 7
	s_waitcnt lgkmcnt(0)
	v_cvt_pk_bf16_f32 v142, v144, v142
	v_add_u32_e32 v144, s5, v37
	s_lshl_b32 s4, s4, 11
	v_readlane_b32 s15, v238, 60
	s_ashr_i32 s9, s8, 31
	v_subrev_u32_e32 v150, s4, v144
	v_mov_b64_e32 v[146:147], s[14:15]
	v_mad_i64_i32 v[148:149], s[14:15], v150, s11, v[146:147]
	s_lshl_b64 s[8:9], s[8:9], 1
	v_lshl_add_u64 v[148:149], v[148:149], 0, s[8:9]
	v_lshl_add_u64 v[148:149], v[148:149], 0, v[32:33]
	global_store_dword v[148:149], v142, off
	v_add_u32_e32 v142, 8, v150
	v_cvt_pk_bf16_f32 v144, v145, v143
	v_mad_i64_i32 v[142:143], s[14:15], v142, s11, v[146:147]
	v_lshl_add_u64 v[142:143], v[142:143], 0, s[8:9]
	v_lshl_add_u64 v[142:143], v[142:143], 0, v[32:33]
	global_store_dword v[142:143], v144, off
	ds_read2_b32 v[142:143], v35 offset0:16 offset1:24
	ds_read2_b32 v[144:145], v35 offset0:81 offset1:89
	s_waitcnt lgkmcnt(0)
	v_cvt_pk_bf16_f32 v142, v142, v144
	v_add_u32_e32 v144, 16, v150
	v_mad_i64_i32 v[148:149], s[14:15], v144, s11, v[146:147]
	v_lshl_add_u64 v[148:149], v[148:149], 0, s[8:9]
	v_lshl_add_u64 v[148:149], v[148:149], 0, v[32:33]
	global_store_dword v[148:149], v142, off
	v_add_u32_e32 v142, 24, v150
	v_cvt_pk_bf16_f32 v144, v143, v145
	v_mad_i64_i32 v[142:143], s[14:15], v142, s11, v[146:147]
	v_lshl_add_u64 v[142:143], v[142:143], 0, s[8:9]
	v_lshl_add_u64 v[142:143], v[142:143], 0, v[32:33]
	global_store_dword v[142:143], v144, off
	ds_read2_b32 v[142:143], v35 offset0:32 offset1:40
	ds_read2_b32 v[144:145], v35 offset0:97 offset1:105
	s_waitcnt lgkmcnt(0)
	v_cvt_pk_bf16_f32 v142, v142, v144
	v_add_u32_e32 v144, 32, v150
	v_mad_i64_i32 v[148:149], s[14:15], v144, s11, v[146:147]
	v_lshl_add_u64 v[148:149], v[148:149], 0, s[8:9]
	v_lshl_add_u64 v[148:149], v[148:149], 0, v[32:33]
	global_store_dword v[148:149], v142, off
	v_add_u32_e32 v142, 40, v150
	v_cvt_pk_bf16_f32 v144, v143, v145
	v_mad_i64_i32 v[142:143], s[14:15], v142, s11, v[146:147]
	v_lshl_add_u64 v[142:143], v[142:143], 0, s[8:9]
	v_lshl_add_u64 v[142:143], v[142:143], 0, v[32:33]
	global_store_dword v[142:143], v144, off
	ds_read2_b32 v[142:143], v35 offset0:48 offset1:56
	ds_read2_b32 v[144:145], v35 offset0:113 offset1:121
	s_waitcnt lgkmcnt(0)
	v_cvt_pk_bf16_f32 v142, v142, v144
	v_add_u32_e32 v144, 48, v150
	v_mad_i64_i32 v[148:149], s[14:15], v144, s11, v[146:147]
	v_lshl_add_u64 v[148:149], v[148:149], 0, s[8:9]
	v_lshl_add_u64 v[148:149], v[148:149], 0, v[32:33]
	global_store_dword v[148:149], v142, off
	v_add_u32_e32 v142, 56, v150
	v_cvt_pk_bf16_f32 v144, v143, v145
	v_mad_i64_i32 v[142:143], s[14:15], v142, s11, v[146:147]
	v_lshl_add_u64 v[142:143], v[142:143], 0, s[8:9]
	v_lshl_add_u64 v[142:143], v[142:143], 0, v[32:33]
	global_store_dword v[142:143], v144, off
	v_cmp_gt_i32_e32 vcc, s7, v44
	v_cmp_gt_u32_e64 s[34:35], s10, v45
	s_and_b64 s[34:35], s[34:35], vcc
	s_waitcnt vmcnt(23)
	v_cndmask_b32_e64 v16, 0, v53, s[34:35]
	v_cmp_gt_u32_e64 s[34:35], s10, v46
	s_and_b64 s[34:35], s[34:35], vcc
	s_waitcnt vmcnt(22)
	v_cndmask_b32_e64 v17, 0, v54, s[34:35]
	v_cmp_gt_u32_e64 s[34:35], s10, v47
	s_and_b64 s[34:35], s[34:35], vcc
	s_waitcnt vmcnt(21)
	v_cndmask_b32_e64 v18, 0, v55, s[34:35]
	v_cmp_gt_u32_e64 s[34:35], s10, v48
	s_and_b64 s[34:35], s[34:35], vcc
	s_waitcnt vmcnt(20)
	v_cndmask_b32_e64 v19, 0, v56, s[34:35]
	v_cmp_gt_u32_e64 s[34:35], s10, v49
	s_and_b64 s[34:35], s[34:35], vcc
	s_waitcnt vmcnt(19)
	v_cndmask_b32_e64 v20, 0, v57, s[34:35]
	v_cmp_gt_u32_e64 s[34:35], s10, v50
	s_and_b64 s[34:35], s[34:35], vcc
	s_waitcnt vmcnt(18)
	v_cndmask_b32_e64 v21, 0, v28, s[34:35]
	v_cmp_gt_u32_e64 s[34:35], s10, v51
	s_and_b64 s[34:35], s[34:35], vcc
	s_waitcnt vmcnt(17)
	v_cndmask_b32_e64 v22, 0, v29, s[34:35]
	v_cmp_gt_u32_e64 s[34:35], s10, v52
	s_and_b64 s[34:35], s[34:35], vcc
	s_waitcnt vmcnt(16)
	v_cndmask_b32_e64 v23, 0, v30, s[34:35]
	v_cmp_gt_u32_e64 s[34:35], s10, v31
	s_and_b64 s[34:35], s[34:35], vcc
	s_waitcnt vmcnt(15)
	v_cndmask_b32_e64 v24, 0, v60, s[34:35]
	v_cmp_gt_u32_e64 s[34:35], s10, v42
	s_and_b64 s[34:35], s[34:35], vcc
	s_waitcnt vmcnt(14)
	v_cndmask_b32_e64 v25, 0, v61, s[34:35]
	v_cmp_gt_u32_e64 s[34:35], s10, v43
	s_and_b64 s[34:35], s[34:35], vcc
	s_waitcnt vmcnt(13)
	v_cndmask_b32_e64 v26, 0, v62, s[34:35]
	v_cmp_gt_u32_e64 s[34:35], s10, v58
	s_and_b64 s[34:35], s[34:35], vcc
	s_waitcnt vmcnt(12)
	v_cndmask_b32_e64 v27, 0, v63, s[34:35]
	v_cmp_gt_u32_e64 s[34:35], s10, v59
	s_and_b64 s[34:35], s[34:35], vcc
	s_waitcnt vmcnt(11)
	v_cndmask_b32_e64 v28, 0, v64, s[34:35]
	v_cmp_gt_u32_e64 s[34:35], s10, v65
	s_and_b64 s[34:35], s[34:35], vcc
	s_waitcnt vmcnt(10)
	v_cndmask_b32_e64 v29, 0, v67, s[34:35]
	v_cmp_gt_u32_e64 s[34:35], s10, v66
	s_and_b64 s[34:35], s[34:35], vcc
	s_waitcnt vmcnt(9)
	v_cndmask_b32_e64 v30, 0, v68, s[34:35]
	v_cmp_gt_u32_e64 s[34:35], s10, v69
	s_and_b64 vcc, s[34:35], vcc
	s_waitcnt vmcnt(8)
	v_cndmask_b32_e32 v31, 0, v70, vcc
	s_waitcnt vmcnt(63) expcnt(7) lgkmcnt(15)
	s_barrier

; DEVI unsigned pk_bf16(float lo, float hi) { unsigned r; asm("v_cvt_pk_bf16_f32 %0, %1, %2" : "=v"(r) : "v"(lo), "v"(hi)); return r; }
; DEVI void cvt_job(LAS float* tile, const float* src, int srcK, int srcN, bf16_t* dst, int dstLd, int dstRows, int dstCol0, int mode, const float* gk = nullptr) {
;     ...
;         int rho0, kap0, n0; coords(t, rho0, kap0, n0);
;         const int tn = t + 2 * gridDim.x;
;         if (tn < ntot) gl(tn, regs);
; #pragma unroll
;         for (int i = 0; i < 8; ++i) { const int row = ty + 8 * i;
;             const float lo = tile[(2 * tx) * 65 + row], hi = tile[(2 * tx + 1) * 65 + row];
;             *(unsigned*)(dst + (size_t)(rho0 + row) * dstLd + kap0 + 2 * tx) = pk_bf16(lo, hi); }
;         __syncthreads();
.LBB0_2480:
	ds_read2_b32 v[42:43], v35 offset0:65 offset1:73
	ds_read2_b32 v[44:45], v35 offset1:8
	s_ashr_i32 s8, s4, 31
	s_lshr_b32 s8, s8, 27
	s_add_i32 s8, s4, s8
	s_ashr_i32 s13, s8, 5
	v_readlane_b32 s14, v238, 59
	s_lshl_b32 s8, s13, 7
	s_waitcnt lgkmcnt(0)
	v_cvt_pk_bf16_f32 v42, v44, v42
	v_add_u32_e32 v44, s5, v38
	s_lshl_b32 s13, s13, 11
	v_readlane_b32 s15, v238, 60
	s_ashr_i32 s9, s8, 31
	v_subrev_u32_e32 v50, s13, v44
	v_mov_b64_e32 v[46:47], s[14:15]
	v_mad_i64_i32 v[48:49], s[14:15], v50, s11, v[46:47]
	s_lshl_b64 s[8:9], s[8:9], 1
	v_lshl_add_u64 v[48:49], v[48:49], 0, s[8:9]
	v_lshl_add_u64 v[48:49], v[48:49], 0, v[32:33]
	global_store_dword v[48:49], v42, off
	v_add_u32_e32 v42, 8, v50
	v_cvt_pk_bf16_f32 v44, v45, v43
	v_mad_i64_i32 v[42:43], s[14:15], v42, s11, v[46:47]
	v_lshl_add_u64 v[42:43], v[42:43], 0, s[8:9]
	v_lshl_add_u64 v[42:43], v[42:43], 0, v[32:33]
	global_store_dword v[42:43], v44, off
	ds_read2_b32 v[42:43], v35 offset0:16 offset1:24
	ds_read2_b32 v[44:45], v35 offset0:81 offset1:89
	s_waitcnt lgkmcnt(0)
	v_cvt_pk_bf16_f32 v42, v42, v44
	v_add_u32_e32 v44, 16, v50
	v_mad_i64_i32 v[48:49], s[14:15], v44, s11, v[46:47]
	v_lshl_add_u64 v[48:49], v[48:49], 0, s[8:9]
	v_lshl_add_u64 v[48:49], v[48:49], 0, v[32:33]
	global_store_dword v[48:49], v42, off
	v_add_u32_e32 v42, 24, v50
	v_cvt_pk_bf16_f32 v44, v43, v45
	v_mad_i64_i32 v[42:43], s[14:15], v42, s11, v[46:47]
	v_lshl_add_u64 v[42:43], v[42:43], 0, s[8:9]
	v_lshl_add_u64 v[42:43], v[42:43], 0, v[32:33]
	global_store_dword v[42:43], v44, off
	ds_read2_b32 v[42:43], v35 offset0:32 offset1:40
	ds_read2_b32 v[44:45], v35 offset0:97 offset1:105
	s_waitcnt lgkmcnt(0)
	v_cvt_pk_bf16_f32 v42, v42, v44
	v_add_u32_e32 v44, 32, v50
	v_mad_i64_i32 v[48:49], s[14:15], v44, s11, v[46:47]
	v_lshl_add_u64 v[48:49], v[48:49], 0, s[8:9]
	v_lshl_add_u64 v[48:49], v[48:49], 0, v[32:33]
	global_store_dword v[48:49], v42, off
	v_add_u32_e32 v42, 40, v50
	v_cvt_pk_bf16_f32 v44, v43, v45
	v_mad_i64_i32 v[42:43], s[14:15], v42, s11, v[46:47]
	v_lshl_add_u64 v[42:43], v[42:43], 0, s[8:9]
	v_lshl_add_u64 v[42:43], v[42:43], 0, v[32:33]
	global_store_dword v[42:43], v44, off
	ds_read2_b32 v[42:43], v35 offset0:48 offset1:56
	ds_read2_b32 v[44:45], v35 offset0:113 offset1:121
	s_waitcnt lgkmcnt(0)
	v_cvt_pk_bf16_f32 v42, v42, v44
	v_add_u32_e32 v44, 48, v50
	v_mad_i64_i32 v[48:49], s[14:15], v44, s11, v[46:47]
	v_lshl_add_u64 v[48:49], v[48:49], 0, s[8:9]
	v_lshl_add_u64 v[48:49], v[48:49], 0, v[32:33]
	global_store_dword v[48:49], v42, off
	v_add_u32_e32 v42, 56, v50
	v_cvt_pk_bf16_f32 v44, v43, v45
	v_mad_i64_i32 v[42:43], s[14:15], v42, s11, v[46:47]
	v_lshl_add_u64 v[42:43], v[42:43], 0, s[8:9]
	s_add_i32 s8, s33, s4
	v_lshl_add_u64 v[42:43], v[42:43], 0, v[32:33]
	s_cmpk_gt_i32 s8, 0x57f
	global_store_dword v[42:43], v44, off
	s_waitcnt vmcnt(63) expcnt(7) lgkmcnt(15)
	s_barrier
	s_cbranch_scc1 .LBB0_2477
	s_add_i32 s4, s18, s4
	s_cmpk_gt_i32 s4, 0x57f
	ds_write_b32 v40, v16
	ds_write_b32 v40, v17 offset:2080
	ds_write_b32 v40, v18 offset:4160
	ds_write_b32 v40, v19 offset:6240
	ds_write_b32 v40, v20 offset:8320
	ds_write_b32 v40, v21 offset:10400
	ds_write_b32 v40, v22 offset:12480
	ds_write_b32 v40, v23 offset:14560
	ds_write_b32 v40, v24 offset:16640
	ds_write_b32 v40, v25 offset:18720
	ds_write_b32 v40, v26 offset:20800
	ds_write_b32 v40, v27 offset:22880
	ds_write_b32 v40, v28 offset:24960
	ds_write_b32 v40, v29 offset:27040
	ds_write_b32 v40, v30 offset:29120
	ds_write_b32 v40, v31 offset:31200
	s_waitcnt lgkmcnt(0)
	s_barrier
	s_cbranch_scc1 .Lcvt_stub_10
; DEVI void cvt_job(LAS float* tile, const float* src, int srcK, int srcN, bf16_t* dst, int dstLd, int dstRows, int dstCol0, int mode, const float* gk = nullptr) {
;     ...
;     auto gl = [&](int t, float (&regs)[16]) {
;         int rho0, kap0, n0; coords(t, rho0, kap0, n0);
;         const int n = n0 + tx, nc = n < srcN ? n : srcN - 1;
;         const bool nok = n < srcN;
;         float raw[16], gs[16];
; #pragma unroll
;         for (int i = 0; i < 16; ++i) { const int k = kap0 + ty + 8 * i - dstCol0; const int kc = k < 0 ? 0 : (k < srcK ? k : srcK - 1);
;             raw[i] = __builtin_nontemporal_load(src + (size_t)kc * srcN + nc); }
;         if (gk) {
; #pragma unroll
;             for (int i = 0; i < 16; ++i) { const int k = kap0 + ty + 8 * i - dstCol0; const int kc = k < 0 ? 0 : (k < srcK ? k : srcK - 1); gs[i] = gk[kc]; }
;         } else {
; #pragma unroll
;             for (int i = 0; i < 16; ++i) gs[i] = 1.0f;
;         }
; #pragma unroll
;         for (int i = 0; i < 16; ++i) { const int k = kap0 + ty + 8 * i - dstCol0; regs[i] = (nok && k >= 0 && k < srcK) ? raw[i] * gs[i] : 0.f; }
;     };
	s_ashr_i32 s9, s4, 31
	s_lshr_b32 s9, s9, 27
	s_add_i32 s4, s4, s9
	s_ashr_i32 s4, s4, 5
	v_add_u32_e32 v16, s5, v36
	s_lshl_b32 s9, s4, 11
	v_subrev_u32_e32 v44, s9, v16
	v_lshl_add_u32 v45, s4, 7, v34
	v_min_i32_e32 v16, 0x7ff, v44
	v_add_u32_e32 v50, 40, v45
	v_add_u32_e32 v51, 48, v45
	v_ashrrev_i32_e32 v17, 31, v16
	v_med3_i32 v18, v45, 0, v41
	v_add_u32_e32 v46, 8, v45
	v_add_u32_e32 v47, 16, v45
	v_add_u32_e32 v48, 24, v45
	v_add_u32_e32 v49, 32, v45
	v_med3_i32 v28, v50, 0, v41
	v_med3_i32 v30, v51, 0, v41
	v_add_u32_e32 v52, 56, v45
	v_lshl_add_u64 v[16:17], v[16:17], 2, s[0:1]
	v_lshlrev_b32_e32 v18, 13, v18
	v_mov_b32_e32 v19, v33
	v_med3_i32 v20, v46, 0, v41
	v_med3_i32 v22, v47, 0, v41
	v_med3_i32 v24, v48, 0, v41
	v_med3_i32 v26, v49, 0, v41
	v_lshlrev_b32_e32 v28, 13, v28
	v_mov_b32_e32 v29, v33
	v_lshlrev_b32_e32 v30, 13, v30
	v_mov_b32_e32 v31, v33
	v_med3_i32 v42, v52, 0, v41
	v_lshl_add_u64 v[18:19], v[16:17], 0, v[18:19]
	v_lshlrev_b32_e32 v20, 13, v20
	v_mov_b32_e32 v21, v33
	v_lshlrev_b32_e32 v22, 13, v22
	v_mov_b32_e32 v23, v33
	v_lshlrev_b32_e32 v24, 13, v24
	v_mov_b32_e32 v25, v33
	v_lshlrev_b32_e32 v26, 13, v26
	v_mov_b32_e32 v27, v33
	v_lshl_add_u64 v[28:29], v[16:17], 0, v[28:29]
	v_lshl_add_u64 v[30:31], v[16:17], 0, v[30:31]
	v_lshlrev_b32_e32 v42, 13, v42
	v_mov_b32_e32 v43, v33
	v_lshl_add_u64 v[20:21], v[16:17], 0, v[20:21]
	v_lshl_add_u64 v[22:23], v[16:17], 0, v[22:23]
	v_lshl_add_u64 v[24:25], v[16:17], 0, v[24:25]
	v_lshl_add_u64 v[26:27], v[16:17], 0, v[26:27]
	v_lshl_add_u64 v[42:43], v[16:17], 0, v[42:43]
	global_load_dword v53, v[18:19], off nt
	global_load_dword v54, v[20:21], off nt
	global_load_dword v55, v[22:23], off nt
	global_load_dword v56, v[24:25], off nt
	global_load_dword v57, v[26:27], off nt
	s_nop 0
	global_load_dword v28, v[28:29], off nt
	s_nop 0
	global_load_dword v29, v[30:31], off nt
	s_nop 0
	global_load_dword v30, v[42:43], off nt
	v_add_u32_e32 v31, 64, v45
	v_med3_i32 v18, v31, 0, v41
	v_add_u32_e32 v42, 0x48, v45
	v_add_u32_e32 v43, 0x50, v45
	v_add_u32_e32 v58, 0x58, v45
	v_add_u32_e32 v59, 0x60, v45
	v_lshlrev_b32_e32 v18, 13, v18
	v_mov_b32_e32 v19, v33
	v_med3_i32 v20, v42, 0, v41
	v_med3_i32 v22, v43, 0, v41
	v_med3_i32 v24, v58, 0, v41
	v_med3_i32 v26, v59, 0, v41
	v_lshl_add_u64 v[18:19], v[16:17], 0, v[18:19]
	v_lshlrev_b32_e32 v20, 13, v20
	v_mov_b32_e32 v21, v33
	v_lshlrev_b32_e32 v22, 13, v22
	v_mov_b32_e32 v23, v33
	v_lshlrev_b32_e32 v24, 13, v24
	v_mov_b32_e32 v25, v33
	v_lshlrev_b32_e32 v26, 13, v26
	v_mov_b32_e32 v27, v33
	v_lshl_add_u64 v[20:21], v[16:17], 0, v[20:21]
	v_lshl_add_u64 v[22:23], v[16:17], 0, v[22:23]
	v_lshl_add_u64 v[24:25], v[16:17], 0, v[24:25]
	v_lshl_add_u64 v[26:27], v[16:17], 0, v[26:27]
	global_load_dword v60, v[18:19], off nt
	global_load_dword v61, v[20:21], off nt
	global_load_dword v62, v[22:23], off nt
	global_load_dword v63, v[24:25], off nt
	global_load_dword v64, v[26:27], off nt
	v_add_u32_e32 v65, 0x68, v45
	v_med3_i32 v18, v65, 0, v41
	v_add_u32_e32 v66, 0x70, v45
	v_lshlrev_b32_e32 v18, 13, v18
	v_mov_b32_e32 v19, v33
	v_med3_i32 v20, v66, 0, v41
	v_lshl_add_u64 v[18:19], v[16:17], 0, v[18:19]
	v_lshlrev_b32_e32 v20, 13, v20
	v_mov_b32_e32 v21, v33
	v_add_u32_e32 v69, 0x78, v45
	v_lshl_add_u64 v[20:21], v[16:17], 0, v[20:21]
	global_load_dword v67, v[18:19], off nt
	global_load_dword v68, v[20:21], off nt
	v_med3_i32 v18, v69, 0, v41
	v_lshlrev_b32_e32 v18, 13, v18
	v_mov_b32_e32 v19, v33
	v_lshl_add_u64 v[16:17], v[16:17], 0, v[18:19]
	global_load_dword v70, v[16:17], off nt
	s_waitcnt vmcnt(24)
	s_branch .LBB0_2476
